# phase1-selects-in-mfma-shadow
# speedup vs baseline: 1.0199x; 1.0071x over previous
; #define PG8_STAGE(bufoff, gbase, voff) do { _Pragma("unroll") for (int _i = 0; _i < 2; ++_i) \
;         __builtin_amdgcn_global_load_lds((const unsigned*)((const char*)(gbase) + (voff)[_i]), (LAS unsigned*)(lds + (bufoff) + ldsw + _i * 8192), 16, 0, 0); } while (0)
; #define PG8_LDA(dst, b, h) do { _Pragma("unroll") for (int m = 0; m < 4; ++m) _Pragma("unroll") for (int k = 0; k < 2; ++k) dst[m][k] = *(const LAS bf16x8*)(lds + PG8_SA(b, h) + aoff + m * 2048 + k * 1024); } while (0)
; #define PG8_LDB(dst, b, h) do { _Pragma("unroll") for (int n = 0; n < 2; ++n) _Pragma("unroll") for (int k = 0; k < 2; ++k) dst[n][k] = *(const LAS bf16x8*)(lds + PG8_SB(b, h) + boff + n * 2048 + k * 1024); } while (0)
; #define PG8_MMA(ai, bj, At, Bt) do { __builtin_amdgcn_s_setprio(1); _Pragma("unroll") for (int m = 0; m < 4; ++m) _Pragma("unroll") for (int n = 0; n < 2; ++n) _Pragma("unroll") for (int k = 0; k < 2; ++k) \
;         acc[ai][bj][m][n] = __builtin_amdgcn_mfma_f32_16x16x32_bf16(Bt[n][k], At[m][k], acc[ai][bj][m][n], 0, 0, 0); __builtin_amdgcn_s_setprio(0); } while (0)
; #define PG8_WAIT_V(n) asm volatile("s_waitcnt vmcnt(" #n ")" ::: "memory")
; #define PG8_WAIT_L(n) asm volatile("s_waitcnt lgkmcnt(" #n ")" ::: "memory")
; template <class Epi, class Sched, bool ATILE = false>
; __device__ __forceinline__ void gemm_phase(LAS unsigned char* lds, const Gemm g, const Sched& S, const Epi& E) {
;     ...
;         for (int t = 0; t < nt; t += 2) {
;             const bool last = (t == nt - 2);
;             const char* a1 = cA + (size_t)(t + 1) * kstepA;
;             const char* a2 = last ? nA : cA + (size_t)(t + 2) * kstepA; const char* b2 = last ? nB : cB + (size_t)(t + 2) * kstep;
;             const char* a3 = a2 + kstepA; const char* b3 = b2 + kstep;
;             PG8_LDB(B0, 0, 0); PG8_SCHED; PG8_LDA(At, 0, 0); PG8_STAGE(PG8_SA(1, 1), a1 + hstepA, voffA);
;             PG8_WAIT_L(8); PG8_BAR; PG8_WAIT_L(0); PG8_MMA(0, 0, At, B0); PG8_BAR; PG8_SCHED;
;             PG8_LDB(B1, 0, 1); PG8_STAGE(PG8_SB(0, 0), b2, voffB);
;             PG8_BAR; PG8_WAIT_L(0); PG8_MMA(0, 1, At, B1); PG8_BAR;
;             PG8_LDA(At, 0, 1); PG8_STAGE(PG8_SA(0, 0), a2, voffA);
;             PG8_BAR; PG8_WAIT_L(0); PG8_MMA(1, 0, At, B0); PG8_BAR; PG8_SCHED;
;             PG8_STAGE(PG8_SB(0, 1), b2 + hstepB, voffB);
;             PG8_WAIT_V(6); PG8_BAR; PG8_MMA(1, 1, At, B1); PG8_BAR;
.LBB0_625:
	ds_read_b128 v[182:185], v139
	ds_read_b128 v[186:189], v139 offset:1024
	ds_read_b128 v[190:193], v139 offset:2048
	ds_read_b128 v[194:197], v139 offset:3072
	s_add_i32 m0, s35, 0xc000
	ds_read_b128 v[198:201], v163
	ds_read_b128 v[202:205], v163 offset:1024
	ds_read_b128 v[206:209], v163 offset:2048
	ds_read_b128 v[210:213], v163 offset:3072
	ds_read_b128 v[214:217], v163 offset:4096
	ds_read_b128 v[218:221], v163 offset:5120
	ds_read_b128 v[222:225], v163 offset:6144
	ds_read_b128 v[226:229], v163 offset:7168
	global_load_lds_dwordx4 v172, s[26:27]
	s_add_i32 m0, s35, 0xe000
	s_nop 0
	global_load_lds_dwordx4 v174, s[26:27]
	s_waitcnt lgkmcnt(8)
	s_setprio 1
	s_barrier
	s_waitcnt lgkmcnt(0)
	v_mfma_f32_16x16x32_bf16 v[120:123], v[182:185], v[198:201], v[120:123]
	s_add_i32 s62, s28, 2
	v_mfma_f32_16x16x32_bf16 v[112:115], v[190:193], v[198:201], v[112:115]
	s_add_u32 s29, s26, 0xfff80080
	v_mfma_f32_16x16x32_bf16 v[104:107], v[182:185], v[206:209], v[104:107]
	s_addc_u32 s30, s27, -1
	v_mfma_f32_16x16x32_bf16 v[96:99], v[190:193], v[206:209], v[96:99]
	s_cmp_eq_u32 s59, s28
	v_mfma_f32_16x16x32_bf16 v[88:91], v[182:185], v[214:217], v[88:91]
	s_cselect_b32 s28, s58, s60
	v_mfma_f32_16x16x32_bf16 v[80:83], v[190:193], v[214:217], v[80:83]
	s_cselect_b32 s31, s13, s30
	v_mfma_f32_16x16x32_bf16 v[72:75], v[182:185], v[222:225], v[72:75]
	s_cselect_b32 s30, s56, s29
	v_mfma_f32_16x16x32_bf16 v[64:67], v[190:193], v[222:225], v[64:67]
	s_cselect_b32 s29, s57, s61
	v_mfma_f32_16x16x32_bf16 v[120:123], v[186:189], v[202:205], v[120:123]
	s_add_i32 s63, s53, s34
	v_mfma_f32_16x16x32_bf16 v[112:115], v[194:197], v[202:205], v[112:115]
	s_add_u32 s98, s28, s0
	v_mfma_f32_16x16x32_bf16 v[104:107], v[186:189], v[210:213], v[104:107]
	s_addc_u32 s99, s29, s1
	v_mfma_f32_16x16x32_bf16 v[96:99], v[194:197], v[210:213], v[96:99]
	s_mov_b32 m0, s63
	v_mfma_f32_16x16x32_bf16 v[88:91], v[186:189], v[218:221], v[88:91]
	v_mfma_f32_16x16x32_bf16 v[80:83], v[194:197], v[218:221], v[80:83]
	v_mfma_f32_16x16x32_bf16 v[72:75], v[186:189], v[226:229], v[72:75]
	v_mfma_f32_16x16x32_bf16 v[64:67], v[194:197], v[226:229], v[64:67]
	s_barrier
	s_setprio 0
	ds_read_b128 v[230:233], v167
	ds_read_b128 v[234:237], v167 offset:1024
	ds_read_b128 v[238:241], v167 offset:2048
	ds_read_b128 v[242:245], v167 offset:3072
	global_load_lds_dwordx4 v130, s[28:29]
	s_add_i32 m0, s63, 0x2000
	s_nop 0
	global_load_lds_dwordx4 v134, s[28:29]
	s_setprio 1
	s_barrier
	s_waitcnt lgkmcnt(0)
	v_mfma_f32_16x16x32_bf16 v[124:127], v[230:233], v[198:201], v[124:127]
	v_mfma_f32_16x16x32_bf16 v[116:119], v[238:241], v[198:201], v[116:119]
	v_mfma_f32_16x16x32_bf16 v[108:111], v[230:233], v[206:209], v[108:111]
	v_mfma_f32_16x16x32_bf16 v[100:103], v[238:241], v[206:209], v[100:103]
	v_mfma_f32_16x16x32_bf16 v[92:95], v[230:233], v[214:217], v[92:95]
	v_mfma_f32_16x16x32_bf16 v[84:87], v[238:241], v[214:217], v[84:87]
	v_mfma_f32_16x16x32_bf16 v[76:79], v[230:233], v[222:225], v[76:79]
	v_mfma_f32_16x16x32_bf16 v[68:71], v[238:241], v[222:225], v[68:71]
	s_mov_b32 m0, s35
	v_mfma_f32_16x16x32_bf16 v[124:127], v[234:237], v[202:205], v[124:127]
	s_add_u32 s100, s30, s0
	v_mfma_f32_16x16x32_bf16 v[116:119], v[242:245], v[202:205], v[116:119]
	s_addc_u32 s101, s31, s1
	v_mfma_f32_16x16x32_bf16 v[108:111], v[234:237], v[210:213], v[108:111]
	v_mfma_f32_16x16x32_bf16 v[100:103], v[242:245], v[210:213], v[100:103]
	v_mfma_f32_16x16x32_bf16 v[92:95], v[234:237], v[218:221], v[92:95]
	v_mfma_f32_16x16x32_bf16 v[84:87], v[242:245], v[218:221], v[84:87]
	v_mfma_f32_16x16x32_bf16 v[76:79], v[234:237], v[226:229], v[76:79]
	v_mfma_f32_16x16x32_bf16 v[68:71], v[242:245], v[226:229], v[68:71]
	s_barrier
	s_setprio 0
	ds_read_b128 v[198:201], v163 offset:16384
	ds_read_b128 v[202:205], v163 offset:17408
	ds_read_b128 v[206:209], v163 offset:18432
	ds_read_b128 v[210:213], v163 offset:19456
	ds_read_b128 v[214:217], v163 offset:20480
	ds_read_b128 v[218:221], v163 offset:21504
	ds_read_b128 v[222:225], v163 offset:22528
	ds_read_b128 v[226:229], v163 offset:23552
	global_load_lds_dwordx4 v128, s[30:31]
	s_mov_b32 m0, s36
	s_nop 0
	global_load_lds_dwordx4 v132, s[30:31]
	s_setprio 1
	s_barrier
	s_waitcnt lgkmcnt(0)
	v_mfma_f32_16x16x32_bf16 v[56:59], v[182:185], v[198:201], v[56:59]
	v_mfma_f32_16x16x32_bf16 v[48:51], v[190:193], v[198:201], v[48:51]
	v_mfma_f32_16x16x32_bf16 v[40:43], v[182:185], v[206:209], v[40:43]
	v_mfma_f32_16x16x32_bf16 v[32:35], v[190:193], v[206:209], v[32:35]
	v_mfma_f32_16x16x32_bf16 v[24:27], v[182:185], v[214:217], v[24:27]
	v_mfma_f32_16x16x32_bf16 v[16:19], v[190:193], v[214:217], v[16:19]
	v_mfma_f32_16x16x32_bf16 v[8:11], v[182:185], v[222:225], v[8:11]
	v_mfma_f32_16x16x32_bf16 v[4:7], v[190:193], v[222:225], v[4:7]
	s_add_u32 s64, s28, 0x80000
	v_mfma_f32_16x16x32_bf16 v[56:59], v[186:189], v[202:205], v[56:59]
	s_addc_u32 s65, s29, 0
	v_mfma_f32_16x16x32_bf16 v[48:51], v[194:197], v[202:205], v[48:51]
	s_add_i32 s63, s54, s34
	v_mfma_f32_16x16x32_bf16 v[40:43], v[186:189], v[210:213], v[40:43]
	s_mov_b32 m0, s63
	v_mfma_f32_16x16x32_bf16 v[32:35], v[194:197], v[210:213], v[32:35]
	v_mfma_f32_16x16x32_bf16 v[24:27], v[186:189], v[218:221], v[24:27]
	v_mfma_f32_16x16x32_bf16 v[16:19], v[194:197], v[218:221], v[16:19]
	v_mfma_f32_16x16x32_bf16 v[8:11], v[186:189], v[226:229], v[8:11]
	v_mfma_f32_16x16x32_bf16 v[4:7], v[194:197], v[226:229], v[4:7]
	s_barrier
	s_setprio 0
	s_nop 0
	global_load_lds_dwordx4 v130, s[64:65]
	s_add_i32 m0, s63, 0x2000
	s_nop 0
	global_load_lds_dwordx4 v134, s[64:65]
	s_waitcnt vmcnt(6)
	s_setprio 1
	s_barrier
; #define PG8_STAGE(bufoff, gbase, voff) do { _Pragma("unroll") for (int _i = 0; _i < 2; ++_i) \
;         __builtin_amdgcn_global_load_lds((const unsigned*)((const char*)(gbase) + (voff)[_i]), (LAS unsigned*)(lds + (bufoff) + ldsw + _i * 8192), 16, 0, 0); } while (0)
; #define PG8_LDA(dst, b, h) do { _Pragma("unroll") for (int m = 0; m < 4; ++m) _Pragma("unroll") for (int k = 0; k < 2; ++k) dst[m][k] = *(const LAS bf16x8*)(lds + PG8_SA(b, h) + aoff + m * 2048 + k * 1024); } while (0)
; #define PG8_LDB(dst, b, h) do { _Pragma("unroll") for (int n = 0; n < 2; ++n) _Pragma("unroll") for (int k = 0; k < 2; ++k) dst[n][k] = *(const LAS bf16x8*)(lds + PG8_SB(b, h) + boff + n * 2048 + k * 1024); } while (0)
; #define PG8_MMA(ai, bj, At, Bt) do { __builtin_amdgcn_s_setprio(1); _Pragma("unroll") for (int m = 0; m < 4; ++m) _Pragma("unroll") for (int n = 0; n < 2; ++n) _Pragma("unroll") for (int k = 0; k < 2; ++k) \
;         acc[ai][bj][m][n] = __builtin_amdgcn_mfma_f32_16x16x32_bf16(Bt[n][k], At[m][k], acc[ai][bj][m][n], 0, 0, 0); __builtin_amdgcn_s_setprio(0); } while (0)
; #define PG8_WAIT_V(n) asm volatile("s_waitcnt vmcnt(" #n ")" ::: "memory")
; #define PG8_WAIT_L(n) asm volatile("s_waitcnt lgkmcnt(" #n ")" ::: "memory")
; #define PG8_BAR __builtin_amdgcn_s_barrier()
; #define PG8_SCHED __builtin_amdgcn_sched_barrier(0)
; template <class Epi, class Sched, bool ATILE = false>
; __device__ __forceinline__ void gemm_phase(LAS unsigned char* lds, const Gemm g, const Sched& S, const Epi& E) {
;     ...
;             PG8_WAIT_V(6); PG8_BAR; PG8_MMA(1, 1, At, B1); PG8_BAR;
;             PG8_LDB(B0, 1, 0); PG8_SCHED; PG8_LDA(At, 1, 0); PG8_STAGE(PG8_SA(0, 1), a2 + hstepA, voffA);
;             PG8_WAIT_L(8); PG8_BAR; PG8_WAIT_L(0); PG8_MMA(0, 0, At, B0); PG8_BAR; PG8_SCHED;
;             PG8_LDB(B1, 1, 1); PG8_STAGE(PG8_SB(1, 0), b3, voffB);
;             PG8_BAR; PG8_WAIT_L(0); PG8_MMA(0, 1, At, B1); PG8_BAR;
;             PG8_LDA(At, 1, 1); PG8_STAGE(PG8_SA(1, 0), a3, voffA);
;             PG8_BAR; PG8_WAIT_L(0); PG8_MMA(1, 0, At, B0); PG8_BAR; PG8_SCHED;
	v_mfma_f32_16x16x32_bf16 v[60:63], v[230:233], v[198:201], v[60:63]
	v_mfma_f32_16x16x32_bf16 v[52:55], v[238:241], v[198:201], v[52:55]
	v_mfma_f32_16x16x32_bf16 v[44:47], v[230:233], v[206:209], v[44:47]
	v_mfma_f32_16x16x32_bf16 v[36:39], v[238:241], v[206:209], v[36:39]
	v_mfma_f32_16x16x32_bf16 v[28:31], v[230:233], v[214:217], v[28:31]
	v_mfma_f32_16x16x32_bf16 v[20:23], v[238:241], v[214:217], v[20:23]
	v_mfma_f32_16x16x32_bf16 v[12:15], v[230:233], v[222:225], v[12:15]
	v_mfma_f32_16x16x32_bf16 v[0:3], v[238:241], v[222:225], v[0:3]
	s_add_i32 s63, 0, 0x18000
	v_mfma_f32_16x16x32_bf16 v[60:63], v[234:237], v[202:205], v[60:63]
	v_add_u32_e32 v176, s63, v161
	v_mfma_f32_16x16x32_bf16 v[52:55], v[242:245], v[202:205], v[52:55]
	v_mfma_f32_16x16x32_bf16 v[44:47], v[234:237], v[210:213], v[44:47]
	v_mfma_f32_16x16x32_bf16 v[36:39], v[242:245], v[210:213], v[36:39]
	v_mfma_f32_16x16x32_bf16 v[28:31], v[234:237], v[218:221], v[28:31]
	v_mfma_f32_16x16x32_bf16 v[20:23], v[242:245], v[218:221], v[20:23]
	v_mfma_f32_16x16x32_bf16 v[12:15], v[234:237], v[226:229], v[12:15]
	v_mfma_f32_16x16x32_bf16 v[0:3], v[242:245], v[226:229], v[0:3]
	s_barrier
	s_setprio 0
	ds_read_b128 v[182:185], v176
	ds_read_b128 v[186:189], v176 offset:1024
	ds_read_b128 v[190:193], v176 offset:2048
	ds_read_b128 v[194:197], v176 offset:3072
	s_add_u32 s30, s30, 0x80000
	s_addc_u32 s31, s31, 0
	s_mov_b32 m0, s37
	ds_read_b128 v[198:201], v163 offset:32768
	ds_read_b128 v[202:205], v163 offset:33792
	ds_read_b128 v[206:209], v163 offset:34816
	ds_read_b128 v[210:213], v163 offset:35840
	ds_read_b128 v[214:217], v163 offset:36864
	ds_read_b128 v[218:221], v163 offset:37888
	ds_read_b128 v[222:225], v163 offset:38912
	ds_read_b128 v[226:229], v163 offset:39936
	global_load_lds_dwordx4 v128, s[30:31]
	s_mov_b32 m0, s38
	s_nop 0
	global_load_lds_dwordx4 v132, s[30:31]
	s_waitcnt lgkmcnt(8)
	s_setprio 1
	s_barrier
	s_waitcnt lgkmcnt(0)
	v_mfma_f32_16x16x32_bf16 v[120:123], v[182:185], v[198:201], v[120:123]
	v_mfma_f32_16x16x32_bf16 v[112:115], v[190:193], v[198:201], v[112:115]
	v_mfma_f32_16x16x32_bf16 v[104:107], v[182:185], v[206:209], v[104:107]
	v_mfma_f32_16x16x32_bf16 v[96:99], v[190:193], v[206:209], v[96:99]
	v_mfma_f32_16x16x32_bf16 v[88:91], v[182:185], v[214:217], v[88:91]
	v_mfma_f32_16x16x32_bf16 v[80:83], v[190:193], v[214:217], v[80:83]
	v_mfma_f32_16x16x32_bf16 v[72:75], v[182:185], v[222:225], v[72:75]
	v_mfma_f32_16x16x32_bf16 v[64:67], v[190:193], v[222:225], v[64:67]
	s_add_i32 s30, 0, 0x1c000
	v_mfma_f32_16x16x32_bf16 v[120:123], v[186:189], v[202:205], v[120:123]
	s_add_i32 s31, s63, s34
	v_mfma_f32_16x16x32_bf16 v[112:115], v[194:197], v[202:205], v[112:115]
	v_add_u32_e32 v176, s30, v161
	v_mfma_f32_16x16x32_bf16 v[104:107], v[186:189], v[210:213], v[104:107]
	s_mov_b32 m0, s31
	v_mfma_f32_16x16x32_bf16 v[96:99], v[194:197], v[210:213], v[96:99]
	v_mfma_f32_16x16x32_bf16 v[88:91], v[186:189], v[218:221], v[88:91]
	v_mfma_f32_16x16x32_bf16 v[80:83], v[194:197], v[218:221], v[80:83]
	v_mfma_f32_16x16x32_bf16 v[72:75], v[186:189], v[226:229], v[72:75]
	v_mfma_f32_16x16x32_bf16 v[64:67], v[194:197], v[226:229], v[64:67]
	s_barrier
	s_setprio 0
	ds_read_b128 v[230:233], v176
	ds_read_b128 v[234:237], v176 offset:1024
	ds_read_b128 v[238:241], v176 offset:2048
	ds_read_b128 v[242:245], v176 offset:3072
	global_load_lds_dwordx4 v130, s[98:99]
	s_add_i32 m0, s31, 0x2000
	s_nop 0
	global_load_lds_dwordx4 v134, s[98:99]
	s_setprio 1
	s_barrier
; #define PG8_STAGE(bufoff, gbase, voff) do { _Pragma("unroll") for (int _i = 0; _i < 2; ++_i) \
;         __builtin_amdgcn_global_load_lds((const unsigned*)((const char*)(gbase) + (voff)[_i]), (LAS unsigned*)(lds + (bufoff) + ldsw + _i * 8192), 16, 0, 0); } while (0)
; #define PG8_LDA(dst, b, h) do { _Pragma("unroll") for (int m = 0; m < 4; ++m) _Pragma("unroll") for (int k = 0; k < 2; ++k) dst[m][k] = *(const LAS bf16x8*)(lds + PG8_SA(b, h) + aoff + m * 2048 + k * 1024); } while (0)
; #define PG8_MMA(ai, bj, At, Bt) do { __builtin_amdgcn_s_setprio(1); _Pragma("unroll") for (int m = 0; m < 4; ++m) _Pragma("unroll") for (int n = 0; n < 2; ++n) _Pragma("unroll") for (int k = 0; k < 2; ++k) \
;         acc[ai][bj][m][n] = __builtin_amdgcn_mfma_f32_16x16x32_bf16(Bt[n][k], At[m][k], acc[ai][bj][m][n], 0, 0, 0); __builtin_amdgcn_s_setprio(0); } while (0)
; #define PG8_WAIT_V(n) asm volatile("s_waitcnt vmcnt(" #n ")" ::: "memory")
; #define PG8_WAIT_L(n) asm volatile("s_waitcnt lgkmcnt(" #n ")" ::: "memory")
; #define PG8_BAR __builtin_amdgcn_s_barrier()
; #define PG8_SCHED __builtin_amdgcn_sched_barrier(0)
; template <class Epi, class Sched, bool ATILE = false>
; __device__ __forceinline__ void gemm_phase(LAS unsigned char* lds, const Gemm g, const Sched& S, const Epi& E) {
;     ...
;             PG8_BAR; PG8_WAIT_L(0); PG8_MMA(0, 1, At, B1); PG8_BAR;
;             PG8_LDA(At, 1, 1); PG8_STAGE(PG8_SA(1, 0), a3, voffA);
;             PG8_BAR; PG8_WAIT_L(0); PG8_MMA(1, 0, At, B0); PG8_BAR; PG8_SCHED;
;             PG8_STAGE(PG8_SB(1, 1), b3 + hstepB, voffB);
;             PG8_WAIT_V(6); PG8_BAR; PG8_MMA(1, 1, At, B1); PG8_BAR;
	s_waitcnt lgkmcnt(0)
	v_mfma_f32_16x16x32_bf16 v[124:127], v[230:233], v[198:201], v[124:127]
	v_mfma_f32_16x16x32_bf16 v[116:119], v[238:241], v[198:201], v[116:119]
	v_mfma_f32_16x16x32_bf16 v[108:111], v[230:233], v[206:209], v[108:111]
	v_mfma_f32_16x16x32_bf16 v[100:103], v[238:241], v[206:209], v[100:103]
	v_mfma_f32_16x16x32_bf16 v[92:95], v[230:233], v[214:217], v[92:95]
	v_mfma_f32_16x16x32_bf16 v[84:87], v[238:241], v[214:217], v[84:87]
	v_mfma_f32_16x16x32_bf16 v[76:79], v[230:233], v[222:225], v[76:79]
	v_mfma_f32_16x16x32_bf16 v[68:71], v[238:241], v[222:225], v[68:71]
	s_mov_b32 m0, s41
	v_mfma_f32_16x16x32_bf16 v[124:127], v[234:237], v[202:205], v[124:127]
	v_mfma_f32_16x16x32_bf16 v[116:119], v[242:245], v[202:205], v[116:119]
	v_mfma_f32_16x16x32_bf16 v[108:111], v[234:237], v[210:213], v[108:111]
	v_mfma_f32_16x16x32_bf16 v[100:103], v[242:245], v[210:213], v[100:103]
	v_mfma_f32_16x16x32_bf16 v[92:95], v[234:237], v[218:221], v[92:95]
	v_mfma_f32_16x16x32_bf16 v[84:87], v[242:245], v[218:221], v[84:87]
	v_mfma_f32_16x16x32_bf16 v[76:79], v[234:237], v[226:229], v[76:79]
	v_mfma_f32_16x16x32_bf16 v[68:71], v[242:245], v[226:229], v[68:71]
	s_barrier
	s_setprio 0
	ds_read_b128 v[198:201], v163 offset:49152
	ds_read_b128 v[202:205], v163 offset:50176
	ds_read_b128 v[206:209], v163 offset:51200
	ds_read_b128 v[210:213], v163 offset:52224
	ds_read_b128 v[214:217], v163 offset:53248
	ds_read_b128 v[218:221], v163 offset:54272
	ds_read_b128 v[222:225], v163 offset:55296
	ds_read_b128 v[226:229], v163 offset:56320
	global_load_lds_dwordx4 v128, s[100:101]
	s_mov_b32 m0, s42
	s_nop 0
	global_load_lds_dwordx4 v132, s[100:101]
	s_setprio 1
	s_barrier
	s_waitcnt lgkmcnt(0)
	v_mfma_f32_16x16x32_bf16 v[56:59], v[182:185], v[198:201], v[56:59]
	v_mfma_f32_16x16x32_bf16 v[48:51], v[190:193], v[198:201], v[48:51]
	v_mfma_f32_16x16x32_bf16 v[40:43], v[182:185], v[206:209], v[40:43]
	v_mfma_f32_16x16x32_bf16 v[32:35], v[190:193], v[206:209], v[32:35]
	v_mfma_f32_16x16x32_bf16 v[24:27], v[182:185], v[214:217], v[24:27]
	v_mfma_f32_16x16x32_bf16 v[16:19], v[190:193], v[214:217], v[16:19]
	v_mfma_f32_16x16x32_bf16 v[8:11], v[182:185], v[222:225], v[8:11]
	v_mfma_f32_16x16x32_bf16 v[4:7], v[190:193], v[222:225], v[4:7]
	s_add_u32 s28, s28, 0x80080
	v_mfma_f32_16x16x32_bf16 v[56:59], v[186:189], v[202:205], v[56:59]
	s_addc_u32 s29, s29, 0
	v_mfma_f32_16x16x32_bf16 v[48:51], v[194:197], v[202:205], v[48:51]
	s_add_i32 s30, s30, s34
	v_mfma_f32_16x16x32_bf16 v[40:43], v[186:189], v[210:213], v[40:43]
	s_mov_b32 m0, s30
	v_mfma_f32_16x16x32_bf16 v[32:35], v[194:197], v[210:213], v[32:35]
	v_mfma_f32_16x16x32_bf16 v[24:27], v[186:189], v[218:221], v[24:27]
	v_mfma_f32_16x16x32_bf16 v[16:19], v[194:197], v[218:221], v[16:19]
	v_mfma_f32_16x16x32_bf16 v[8:11], v[186:189], v[226:229], v[8:11]
	v_mfma_f32_16x16x32_bf16 v[4:7], v[194:197], v[226:229], v[4:7]
	s_barrier
	s_setprio 0
	s_nop 0
	global_load_lds_dwordx4 v130, s[28:29]
	s_add_i32 m0, s30, 0x2000
	s_nop 0
	global_load_lds_dwordx4 v134, s[28:29]
	s_waitcnt vmcnt(6)
	s_setprio 1
	s_barrier
	v_mfma_f32_16x16x32_bf16 v[60:63], v[230:233], v[198:201], v[60:63]
	v_mfma_f32_16x16x32_bf16 v[52:55], v[238:241], v[198:201], v[52:55]
	v_mfma_f32_16x16x32_bf16 v[44:47], v[230:233], v[206:209], v[44:47]
	v_mfma_f32_16x16x32_bf16 v[36:39], v[238:241], v[206:209], v[36:39]
	v_mfma_f32_16x16x32_bf16 v[28:31], v[230:233], v[214:217], v[28:31]
	v_mfma_f32_16x16x32_bf16 v[20:23], v[238:241], v[214:217], v[20:23]
	v_mfma_f32_16x16x32_bf16 v[12:15], v[230:233], v[222:225], v[12:15]
	s_add_u32 s26, s26, 0x100
	v_mfma_f32_16x16x32_bf16 v[0:3], v[238:241], v[222:225], v[0:3]
	s_addc_u32 s27, s27, 0
	v_mfma_f32_16x16x32_bf16 v[60:63], v[234:237], v[202:205], v[60:63]
	s_add_u32 s60, s60, 0x100
	v_mfma_f32_16x16x32_bf16 v[52:55], v[242:245], v[202:205], v[52:55]
	s_addc_u32 s61, s61, 0
	v_mfma_f32_16x16x32_bf16 v[44:47], v[234:237], v[210:213], v[44:47]
	s_cmp_ge_i32 s62, s11
	v_mfma_f32_16x16x32_bf16 v[36:39], v[242:245], v[210:213], v[36:39]
	s_mov_b32 s28, s62
	v_mfma_f32_16x16x32_bf16 v[28:31], v[234:237], v[218:221], v[28:31]
	v_mfma_f32_16x16x32_bf16 v[20:23], v[242:245], v[218:221], v[20:23]
	v_mfma_f32_16x16x32_bf16 v[12:15], v[234:237], v[226:229], v[12:15]
	v_mfma_f32_16x16x32_bf16 v[0:3], v[242:245], v[226:229], v[0:3]
	s_barrier
	s_setprio 0
	s_cbranch_scc0 .LBB0_625
	s_nop 5
	s_branch .LBB0_616

; #define PG8_STAGE(bufoff, gbase, voff) do { _Pragma("unroll") for (int _i = 0; _i < 2; ++_i) \
;         __builtin_amdgcn_global_load_lds((const unsigned*)((const char*)(gbase) + (voff)[_i]), (LAS unsigned*)(lds + (bufoff) + ldsw + _i * 8192), 16, 0, 0); } while (0)
; #define PG8_LDA(dst, b, h) do { _Pragma("unroll") for (int m = 0; m < 4; ++m) _Pragma("unroll") for (int k = 0; k < 2; ++k) dst[m][k] = *(const LAS bf16x8*)(lds + PG8_SA(b, h) + aoff + m * 2048 + k * 1024); } while (0)
; #define PG8_LDB(dst, b, h) do { _Pragma("unroll") for (int n = 0; n < 2; ++n) _Pragma("unroll") for (int k = 0; k < 2; ++k) dst[n][k] = *(const LAS bf16x8*)(lds + PG8_SB(b, h) + boff + n * 2048 + k * 1024); } while (0)
; #define PG8_MMA(ai, bj, At, Bt) do { __builtin_amdgcn_s_setprio(1); _Pragma("unroll") for (int m = 0; m < 4; ++m) _Pragma("unroll") for (int n = 0; n < 2; ++n) _Pragma("unroll") for (int k = 0; k < 2; ++k) \
;         acc[ai][bj][m][n] = __builtin_amdgcn_mfma_f32_16x16x32_bf16(Bt[n][k], At[m][k], acc[ai][bj][m][n], 0, 0, 0); __builtin_amdgcn_s_setprio(0); } while (0)
; #define PG8_WAIT_V(n) asm volatile("s_waitcnt vmcnt(" #n ")" ::: "memory")
; #define PG8_WAIT_L(n) asm volatile("s_waitcnt lgkmcnt(" #n ")" ::: "memory")
; template <class Epi, class Sched, bool ATILE = false>
; __device__ __forceinline__ void gemm_phase(LAS unsigned char* lds, const Gemm g, const Sched& S, const Epi& E) {
;     ...
;         for (int t = 0; t < nt; t += 2) {
;             const bool last = (t == nt - 2);
;             const char* a1 = cA + (size_t)(t + 1) * kstepA;
;             const char* a2 = last ? nA : cA + (size_t)(t + 2) * kstepA; const char* b2 = last ? nB : cB + (size_t)(t + 2) * kstep;
;             const char* a3 = a2 + kstepA; const char* b3 = b2 + kstep;
;             PG8_LDB(B0, 0, 0); PG8_SCHED; PG8_LDA(At, 0, 0); PG8_STAGE(PG8_SA(1, 1), a1 + hstepA, voffA);
;             PG8_WAIT_L(8); PG8_BAR; PG8_WAIT_L(0); PG8_MMA(0, 0, At, B0); PG8_BAR; PG8_SCHED;
;             PG8_LDB(B1, 0, 1); PG8_STAGE(PG8_SB(0, 0), b2, voffB);
;             PG8_BAR; PG8_WAIT_L(0); PG8_MMA(0, 1, At, B1); PG8_BAR;
;             PG8_LDA(At, 0, 1); PG8_STAGE(PG8_SA(0, 0), a2, voffA);
;             PG8_BAR; PG8_WAIT_L(0); PG8_MMA(1, 0, At, B0); PG8_BAR; PG8_SCHED;
;             PG8_STAGE(PG8_SB(0, 1), b2 + hstepB, voffB);
;             PG8_WAIT_V(6); PG8_BAR; PG8_MMA(1, 1, At, B1); PG8_BAR;
.LBB0_739:
	ds_read_b128 v[20:23], v165
	ds_read_b128 v[28:31], v165 offset:1024
	ds_read_b128 v[136:139], v165 offset:2048
	ds_read_b128 v[140:143], v165 offset:3072
	s_add_i32 m0, s34, 0xc000
	ds_read_b128 v[144:147], v167
	ds_read_b128 v[148:151], v167 offset:1024
	ds_read_b128 v[200:203], v167 offset:2048
	ds_read_b128 v[204:207], v167 offset:3072
	ds_read_b128 v[208:211], v167 offset:4096
	ds_read_b128 v[212:215], v167 offset:5120
	ds_read_b128 v[220:223], v167 offset:6144
	ds_read_b128 v[224:227], v167 offset:7168
	global_load_lds_dwordx4 v194, s[24:25]
	s_add_i32 m0, s34, 0xe000
	s_nop 0
	global_load_lds_dwordx4 v196, s[24:25]
	s_waitcnt lgkmcnt(8)
	s_setprio 1
	s_barrier
	s_waitcnt lgkmcnt(0)
	v_mfma_f32_16x16x32_bf16 v[0:3], v[20:23], v[144:147], v[0:3]
	s_add_i32 s62, s26, 2
	v_mfma_f32_16x16x32_bf16 v[4:7], v[136:139], v[144:147], v[4:7]
	s_add_u32 s27, s24, 0x4000
	v_mfma_f32_16x16x32_bf16 v[44:47], v[20:23], v[200:203], v[44:47]
	s_addc_u32 s28, s25, 0
	v_mfma_f32_16x16x32_bf16 v[36:39], v[136:139], v[200:203], v[36:39]
	s_cmp_eq_u32 s11, s26
	v_mfma_f32_16x16x32_bf16 v[52:55], v[20:23], v[208:211], v[52:55]
	s_cselect_b32 s30, s20, s27
	v_mfma_f32_16x16x32_bf16 v[48:51], v[136:139], v[208:211], v[48:51]
	s_cselect_b32 s31, s21, s28
	v_mfma_f32_16x16x32_bf16 v[92:95], v[20:23], v[220:223], v[92:95]
	s_cselect_b32 s26, s22, s60
	v_mfma_f32_16x16x32_bf16 v[84:87], v[136:139], v[220:223], v[84:87]
	s_cselect_b32 s27, s23, s61
	v_mfma_f32_16x16x32_bf16 v[0:3], v[28:31], v[148:151], v[0:3]
	s_add_u32 s28, s30, 0x8000
	v_mfma_f32_16x16x32_bf16 v[4:7], v[140:143], v[148:151], v[4:7]
	s_addc_u32 s29, s31, 0
	v_mfma_f32_16x16x32_bf16 v[44:47], v[28:31], v[204:207], v[44:47]
	s_add_i32 s63, s52, s33
	v_mfma_f32_16x16x32_bf16 v[36:39], v[140:143], v[204:207], v[36:39]
	s_add_u32 s98, s26, s6
	v_mfma_f32_16x16x32_bf16 v[52:55], v[28:31], v[212:215], v[52:55]
	s_addc_u32 s99, s27, s7
	v_mfma_f32_16x16x32_bf16 v[48:51], v[140:143], v[212:215], v[48:51]
	s_mov_b32 m0, s63
	v_mfma_f32_16x16x32_bf16 v[92:95], v[28:31], v[224:227], v[92:95]
	v_mfma_f32_16x16x32_bf16 v[84:87], v[140:143], v[224:227], v[84:87]
	s_barrier
	s_setprio 0
	ds_read_b128 v[228:231], v177
	ds_read_b128 v[232:235], v177 offset:1024
	ds_read_b128 v[236:239], v177 offset:2048
	ds_read_b128 v[240:243], v177 offset:3072
	global_load_lds_dwordx4 v170, s[26:27]
	s_add_i32 m0, s63, 0x2000
	s_nop 0
	global_load_lds_dwordx4 v174, s[26:27]
	s_setprio 1
	s_barrier
	s_waitcnt lgkmcnt(0)
	v_mfma_f32_16x16x32_bf16 v[12:15], v[228:231], v[144:147], v[12:15]
	v_mfma_f32_16x16x32_bf16 v[8:11], v[236:239], v[144:147], v[8:11]
	v_mfma_f32_16x16x32_bf16 v[24:27], v[228:231], v[200:203], v[24:27]
	v_mfma_f32_16x16x32_bf16 v[16:19], v[236:239], v[200:203], v[16:19]
	v_mfma_f32_16x16x32_bf16 v[40:43], v[228:231], v[208:211], v[40:43]
	v_mfma_f32_16x16x32_bf16 v[32:35], v[236:239], v[208:211], v[32:35]
	v_mfma_f32_16x16x32_bf16 v[56:59], v[228:231], v[220:223], v[56:59]
	v_mfma_f32_16x16x32_bf16 v[60:63], v[236:239], v[220:223], v[60:63]
	s_mov_b32 m0, s34
	v_mfma_f32_16x16x32_bf16 v[12:15], v[232:235], v[148:151], v[12:15]
	v_mfma_f32_16x16x32_bf16 v[8:11], v[240:243], v[148:151], v[8:11]
	v_mfma_f32_16x16x32_bf16 v[24:27], v[232:235], v[204:207], v[24:27]
	v_mfma_f32_16x16x32_bf16 v[16:19], v[240:243], v[204:207], v[16:19]
	v_mfma_f32_16x16x32_bf16 v[40:43], v[232:235], v[212:215], v[40:43]
	v_mfma_f32_16x16x32_bf16 v[32:35], v[240:243], v[212:215], v[32:35]
	v_mfma_f32_16x16x32_bf16 v[56:59], v[232:235], v[224:227], v[56:59]
	v_mfma_f32_16x16x32_bf16 v[60:63], v[240:243], v[224:227], v[60:63]
	s_barrier
	s_setprio 0
	ds_read_b128 v[144:147], v167 offset:16384
	ds_read_b128 v[148:151], v167 offset:17408
	ds_read_b128 v[200:203], v167 offset:18432
	ds_read_b128 v[204:207], v167 offset:19456
	ds_read_b128 v[208:211], v167 offset:20480
	ds_read_b128 v[212:215], v167 offset:21504
	ds_read_b128 v[220:223], v167 offset:22528
	ds_read_b128 v[224:227], v167 offset:23552
	global_load_lds_dwordx4 v168, s[30:31]
	s_mov_b32 m0, s35
	s_nop 0
	global_load_lds_dwordx4 v172, s[30:31]
	s_setprio 1
	s_barrier
	s_waitcnt lgkmcnt(0)
	v_mfma_f32_16x16x32_bf16 v[64:67], v[20:23], v[144:147], v[64:67]
	v_mfma_f32_16x16x32_bf16 v[68:71], v[136:139], v[144:147], v[68:71]
	v_mfma_f32_16x16x32_bf16 v[108:111], v[20:23], v[200:203], v[108:111]
	v_mfma_f32_16x16x32_bf16 v[100:103], v[136:139], v[200:203], v[100:103]
	v_mfma_f32_16x16x32_bf16 v[116:119], v[20:23], v[208:211], v[116:119]
	v_mfma_f32_16x16x32_bf16 v[112:115], v[136:139], v[208:211], v[112:115]
	v_mfma_f32_16x16x32_bf16 v[20:23], v[20:23], v[220:223], v[132:135]
	v_mfma_f32_16x16x32_bf16 v[64:67], v[28:31], v[148:151], v[64:67]
	s_add_u32 s64, s26, 0x158000
	v_mfma_f32_16x16x32_bf16 v[68:71], v[140:143], v[148:151], v[68:71]
	s_addc_u32 s65, s27, 0
	v_mfma_f32_16x16x32_bf16 v[108:111], v[28:31], v[204:207], v[108:111]
	s_add_i32 s63, s53, s33
	v_mfma_f32_16x16x32_bf16 v[100:103], v[140:143], v[204:207], v[100:103]
	s_mov_b32 m0, s63
	v_mfma_f32_16x16x32_bf16 v[116:119], v[28:31], v[212:215], v[116:119]
	v_mfma_f32_16x16x32_bf16 v[112:115], v[140:143], v[212:215], v[112:115]
	v_mfma_f32_16x16x32_bf16 v[20:23], v[28:31], v[224:227], v[20:23]
	v_mfma_f32_16x16x32_bf16 v[28:31], v[136:139], v[220:223], v[128:131]
	v_mfma_f32_16x16x32_bf16 v[28:31], v[140:143], v[224:227], v[28:31]
	s_barrier
	s_setprio 0
	s_nop 0
	global_load_lds_dwordx4 v170, s[64:65]
	s_add_i32 m0, s63, 0x2000
	s_nop 0
	global_load_lds_dwordx4 v174, s[64:65]
	s_waitcnt vmcnt(6)
	s_setprio 1
	s_barrier
; #define PG8_STAGE(bufoff, gbase, voff) do { _Pragma("unroll") for (int _i = 0; _i < 2; ++_i) \
;         __builtin_amdgcn_global_load_lds((const unsigned*)((const char*)(gbase) + (voff)[_i]), (LAS unsigned*)(lds + (bufoff) + ldsw + _i * 8192), 16, 0, 0); } while (0)
; #define PG8_LDA(dst, b, h) do { _Pragma("unroll") for (int m = 0; m < 4; ++m) _Pragma("unroll") for (int k = 0; k < 2; ++k) dst[m][k] = *(const LAS bf16x8*)(lds + PG8_SA(b, h) + aoff + m * 2048 + k * 1024); } while (0)
; #define PG8_LDB(dst, b, h) do { _Pragma("unroll") for (int n = 0; n < 2; ++n) _Pragma("unroll") for (int k = 0; k < 2; ++k) dst[n][k] = *(const LAS bf16x8*)(lds + PG8_SB(b, h) + boff + n * 2048 + k * 1024); } while (0)
; #define PG8_MMA(ai, bj, At, Bt) do { __builtin_amdgcn_s_setprio(1); _Pragma("unroll") for (int m = 0; m < 4; ++m) _Pragma("unroll") for (int n = 0; n < 2; ++n) _Pragma("unroll") for (int k = 0; k < 2; ++k) \
;         acc[ai][bj][m][n] = __builtin_amdgcn_mfma_f32_16x16x32_bf16(Bt[n][k], At[m][k], acc[ai][bj][m][n], 0, 0, 0); __builtin_amdgcn_s_setprio(0); } while (0)
; #define PG8_WAIT_V(n) asm volatile("s_waitcnt vmcnt(" #n ")" ::: "memory")
; #define PG8_WAIT_L(n) asm volatile("s_waitcnt lgkmcnt(" #n ")" ::: "memory")
; #define PG8_BAR __builtin_amdgcn_s_barrier()
; #define PG8_SCHED __builtin_amdgcn_sched_barrier(0)
; template <class Epi, class Sched, bool ATILE = false>
; __device__ __forceinline__ void gemm_phase(LAS unsigned char* lds, const Gemm g, const Sched& S, const Epi& E) {
;     ...
;             PG8_WAIT_V(6); PG8_BAR; PG8_MMA(1, 1, At, B1); PG8_BAR;
;             PG8_LDB(B0, 1, 0); PG8_SCHED; PG8_LDA(At, 1, 0); PG8_STAGE(PG8_SA(0, 1), a2 + hstepA, voffA);
;             PG8_WAIT_L(8); PG8_BAR; PG8_WAIT_L(0); PG8_MMA(0, 0, At, B0); PG8_BAR; PG8_SCHED;
;             PG8_LDB(B1, 1, 1); PG8_STAGE(PG8_SB(1, 0), b3, voffB);
;             PG8_BAR; PG8_WAIT_L(0); PG8_MMA(0, 1, At, B1); PG8_BAR;
;             PG8_LDA(At, 1, 1); PG8_STAGE(PG8_SA(1, 0), a3, voffA);
;             PG8_BAR; PG8_WAIT_L(0); PG8_MMA(1, 0, At, B0); PG8_BAR; PG8_SCHED;
	v_mfma_f32_16x16x32_bf16 v[76:79], v[228:231], v[144:147], v[76:79]
	v_mfma_f32_16x16x32_bf16 v[72:75], v[236:239], v[144:147], v[72:75]
	v_mfma_f32_16x16x32_bf16 v[88:91], v[228:231], v[200:203], v[88:91]
	v_mfma_f32_16x16x32_bf16 v[80:83], v[236:239], v[200:203], v[80:83]
	v_mfma_f32_16x16x32_bf16 v[104:107], v[228:231], v[208:211], v[104:107]
	v_mfma_f32_16x16x32_bf16 v[96:99], v[236:239], v[208:211], v[96:99]
	v_mfma_f32_16x16x32_bf16 v[120:123], v[228:231], v[220:223], v[120:123]
	v_mfma_f32_16x16x32_bf16 v[124:127], v[236:239], v[220:223], v[124:127]
	s_add_i32 s63, 0, 0x18000
	v_mfma_f32_16x16x32_bf16 v[76:79], v[232:235], v[148:151], v[76:79]
	v_add_u32_e32 v140, s63, v161
	v_mfma_f32_16x16x32_bf16 v[72:75], v[240:243], v[148:151], v[72:75]
	v_mfma_f32_16x16x32_bf16 v[88:91], v[232:235], v[204:207], v[88:91]
	v_mfma_f32_16x16x32_bf16 v[80:83], v[240:243], v[204:207], v[80:83]
	v_mfma_f32_16x16x32_bf16 v[104:107], v[232:235], v[212:215], v[104:107]
	v_mfma_f32_16x16x32_bf16 v[96:99], v[240:243], v[212:215], v[96:99]
	v_mfma_f32_16x16x32_bf16 v[120:123], v[232:235], v[224:227], v[120:123]
	v_mfma_f32_16x16x32_bf16 v[124:127], v[240:243], v[224:227], v[124:127]
	s_barrier
	s_setprio 0
	ds_read_b128 v[128:131], v140
	ds_read_b128 v[132:135], v140 offset:1024
	ds_read_b128 v[136:139], v140 offset:2048
	ds_read_b128 v[140:143], v140 offset:3072
	s_add_u32 s30, s30, 0x4000
	s_addc_u32 s31, s31, 0
	s_mov_b32 m0, s36
	ds_read_b128 v[144:147], v167 offset:32768
	ds_read_b128 v[148:151], v167 offset:33792
	ds_read_b128 v[200:203], v167 offset:34816
	ds_read_b128 v[204:207], v167 offset:35840
	ds_read_b128 v[208:211], v167 offset:36864
	ds_read_b128 v[212:215], v167 offset:37888
	ds_read_b128 v[220:223], v167 offset:38912
	ds_read_b128 v[224:227], v167 offset:39936
	global_load_lds_dwordx4 v168, s[30:31]
	s_mov_b32 m0, s37
	s_nop 0
	global_load_lds_dwordx4 v172, s[30:31]
	s_waitcnt lgkmcnt(8)
	s_setprio 1
	s_barrier
	s_waitcnt lgkmcnt(0)
	v_mfma_f32_16x16x32_bf16 v[0:3], v[128:131], v[144:147], v[0:3]
	v_mfma_f32_16x16x32_bf16 v[4:7], v[136:139], v[144:147], v[4:7]
	v_mfma_f32_16x16x32_bf16 v[44:47], v[128:131], v[200:203], v[44:47]
	v_mfma_f32_16x16x32_bf16 v[36:39], v[136:139], v[200:203], v[36:39]
	v_mfma_f32_16x16x32_bf16 v[52:55], v[128:131], v[208:211], v[52:55]
	v_mfma_f32_16x16x32_bf16 v[48:51], v[136:139], v[208:211], v[48:51]
	v_mfma_f32_16x16x32_bf16 v[92:95], v[128:131], v[220:223], v[92:95]
	v_mfma_f32_16x16x32_bf16 v[84:87], v[136:139], v[220:223], v[84:87]
	s_add_i32 s30, 0, 0x1c000
	v_mfma_f32_16x16x32_bf16 v[0:3], v[132:135], v[148:151], v[0:3]
	s_add_i32 s31, s63, s33
	v_mfma_f32_16x16x32_bf16 v[4:7], v[140:143], v[148:151], v[4:7]
	v_add_u32_e32 v219, s30, v161
	v_mfma_f32_16x16x32_bf16 v[44:47], v[132:135], v[204:207], v[44:47]
	s_mov_b32 m0, s31
	v_mfma_f32_16x16x32_bf16 v[36:39], v[140:143], v[204:207], v[36:39]
	v_mfma_f32_16x16x32_bf16 v[52:55], v[132:135], v[212:215], v[52:55]
	v_mfma_f32_16x16x32_bf16 v[48:51], v[140:143], v[212:215], v[48:51]
	v_mfma_f32_16x16x32_bf16 v[92:95], v[132:135], v[224:227], v[92:95]
	v_mfma_f32_16x16x32_bf16 v[84:87], v[140:143], v[224:227], v[84:87]
	s_barrier
	s_setprio 0
	ds_read_b128 v[228:231], v219
	ds_read_b128 v[232:235], v219 offset:1024
	ds_read_b128 v[236:239], v219 offset:2048
	ds_read_b128 v[240:243], v219 offset:3072
	global_load_lds_dwordx4 v170, s[98:99]
	s_add_i32 m0, s31, 0x2000
	s_nop 0
	global_load_lds_dwordx4 v174, s[98:99]
	s_setprio 1
	s_barrier
	s_waitcnt lgkmcnt(0)
	v_mfma_f32_16x16x32_bf16 v[12:15], v[228:231], v[144:147], v[12:15]
	v_mfma_f32_16x16x32_bf16 v[8:11], v[236:239], v[144:147], v[8:11]
	v_mfma_f32_16x16x32_bf16 v[24:27], v[228:231], v[200:203], v[24:27]
	v_mfma_f32_16x16x32_bf16 v[16:19], v[236:239], v[200:203], v[16:19]
	v_mfma_f32_16x16x32_bf16 v[40:43], v[228:231], v[208:211], v[40:43]
	v_mfma_f32_16x16x32_bf16 v[32:35], v[236:239], v[208:211], v[32:35]
	v_mfma_f32_16x16x32_bf16 v[56:59], v[228:231], v[220:223], v[56:59]
	v_mfma_f32_16x16x32_bf16 v[60:63], v[236:239], v[220:223], v[60:63]
	s_mov_b32 m0, s39
	v_mfma_f32_16x16x32_bf16 v[12:15], v[232:235], v[148:151], v[12:15]
	v_mfma_f32_16x16x32_bf16 v[8:11], v[240:243], v[148:151], v[8:11]
	v_mfma_f32_16x16x32_bf16 v[24:27], v[232:235], v[204:207], v[24:27]
	v_mfma_f32_16x16x32_bf16 v[16:19], v[240:243], v[204:207], v[16:19]
	v_mfma_f32_16x16x32_bf16 v[40:43], v[232:235], v[212:215], v[40:43]
	v_mfma_f32_16x16x32_bf16 v[32:35], v[240:243], v[212:215], v[32:35]
	v_mfma_f32_16x16x32_bf16 v[56:59], v[232:235], v[224:227], v[56:59]
	v_mfma_f32_16x16x32_bf16 v[60:63], v[240:243], v[224:227], v[60:63]
	s_barrier
	s_setprio 0
	ds_read_b128 v[144:147], v167 offset:49152
	ds_read_b128 v[148:151], v167 offset:50176
	ds_read_b128 v[200:203], v167 offset:51200
	ds_read_b128 v[204:207], v167 offset:52224
	ds_read_b128 v[208:211], v167 offset:53248
	ds_read_b128 v[212:215], v167 offset:54272
	ds_read_b128 v[220:223], v167 offset:55296
	ds_read_b128 v[224:227], v167 offset:56320
	global_load_lds_dwordx4 v168, s[28:29]
	s_mov_b32 m0, s40
	s_nop 0
	global_load_lds_dwordx4 v172, s[28:29]
	s_setprio 1
	s_barrier
; __device__ __forceinline__ float bflo(unsigned w) { return __uint_as_float(w << 16); }
; __device__ __forceinline__ float bfhi(unsigned w) { return __uint_as_float(w & 0xffff0000u); }
; #define PG8_STAGE(bufoff, gbase, voff) do { _Pragma("unroll") for (int _i = 0; _i < 2; ++_i) \
;         __builtin_amdgcn_global_load_lds((const unsigned*)((const char*)(gbase) + (voff)[_i]), (LAS unsigned*)(lds + (bufoff) + ldsw + _i * 8192), 16, 0, 0); } while (0)
; #define PG8_LDA(dst, b, h) do { _Pragma("unroll") for (int m = 0; m < 4; ++m) _Pragma("unroll") for (int k = 0; k < 2; ++k) dst[m][k] = *(const LAS bf16x8*)(lds + PG8_SA(b, h) + aoff + m * 2048 + k * 1024); } while (0)
; #define PG8_MMA(ai, bj, At, Bt) do { __builtin_amdgcn_s_setprio(1); _Pragma("unroll") for (int m = 0; m < 4; ++m) _Pragma("unroll") for (int n = 0; n < 2; ++n) _Pragma("unroll") for (int k = 0; k < 2; ++k) \
;         acc[ai][bj][m][n] = __builtin_amdgcn_mfma_f32_16x16x32_bf16(Bt[n][k], At[m][k], acc[ai][bj][m][n], 0, 0, 0); __builtin_amdgcn_s_setprio(0); } while (0)
; #define PG8_WAIT_V(n) asm volatile("s_waitcnt vmcnt(" #n ")" ::: "memory")
; #define PG8_WAIT_L(n) asm volatile("s_waitcnt lgkmcnt(" #n ")" ::: "memory")
; #define PG8_BAR __builtin_amdgcn_s_barrier()
; #define PG8_SCHED __builtin_amdgcn_sched_barrier(0)
; template <class Epi, class Sched, bool ATILE = false>
; __device__ __forceinline__ void gemm_phase(LAS unsigned char* lds, const Gemm g, const Sched& S, const Epi& E) {
;     ...
;             PG8_BAR; PG8_WAIT_L(0); PG8_MMA(0, 1, At, B1); PG8_BAR;
;             PG8_LDA(At, 1, 1); PG8_STAGE(PG8_SA(1, 0), a3, voffA);
;             PG8_BAR; PG8_WAIT_L(0); PG8_MMA(1, 0, At, B0); PG8_BAR; PG8_SCHED;
;             PG8_STAGE(PG8_SB(1, 1), b3 + hstepB, voffB);
;             PG8_WAIT_V(6); PG8_BAR; PG8_MMA(1, 1, At, B1); PG8_BAR;
;     __device__ __forceinline__ void operator()(const f32x4 (&acc)[2][2][4][2], const Unit& u, int wr, int wc, int fr, int fq) const {
;     ...
;                     const f32x4 v0 = (f32x4){bflo(x.x), bfhi(x.x), bflo(x.y), bfhi(x.y)} + alpha * acc[ai][bj][m][0];
;                     const f32x4 v1 = (f32x4){bflo(x.z), bfhi(x.z), bflo(x.w), bfhi(x.w)} + alpha * acc[ai][bj][m][1];
	s_waitcnt lgkmcnt(0)
	v_mfma_f32_16x16x32_bf16 v[64:67], v[128:131], v[144:147], v[64:67]
	v_mfma_f32_16x16x32_bf16 v[108:111], v[128:131], v[200:203], v[108:111]
	v_mfma_f32_16x16x32_bf16 v[116:119], v[128:131], v[208:211], v[116:119]
	v_mfma_f32_16x16x32_bf16 v[20:23], v[128:131], v[220:223], v[20:23]
	v_mfma_f32_16x16x32_bf16 v[64:67], v[132:135], v[148:151], v[64:67]
	v_mfma_f32_16x16x32_bf16 v[68:71], v[136:139], v[144:147], v[68:71]
	v_mfma_f32_16x16x32_bf16 v[108:111], v[132:135], v[204:207], v[108:111]
	v_mfma_f32_16x16x32_bf16 v[100:103], v[136:139], v[200:203], v[100:103]
	s_add_u32 s26, s26, 0x158080
	v_mfma_f32_16x16x32_bf16 v[116:119], v[132:135], v[212:215], v[116:119]
	s_addc_u32 s27, s27, 0
	v_mfma_f32_16x16x32_bf16 v[112:115], v[136:139], v[208:211], v[112:115]
	s_add_i32 s28, s30, s33
	v_mfma_f32_16x16x32_bf16 v[132:135], v[132:135], v[224:227], v[20:23]
	s_mov_b32 m0, s28
	v_mfma_f32_16x16x32_bf16 v[20:23], v[136:139], v[220:223], v[28:31]
	v_mfma_f32_16x16x32_bf16 v[68:71], v[140:143], v[148:151], v[68:71]
	v_mfma_f32_16x16x32_bf16 v[100:103], v[140:143], v[204:207], v[100:103]
	v_mfma_f32_16x16x32_bf16 v[112:115], v[140:143], v[212:215], v[112:115]
	v_mfma_f32_16x16x32_bf16 v[128:131], v[140:143], v[224:227], v[20:23]
	s_barrier
	s_setprio 0
	s_nop 0
	global_load_lds_dwordx4 v170, s[26:27]
	s_add_i32 m0, s28, 0x2000
	s_nop 0
	global_load_lds_dwordx4 v174, s[26:27]
	s_waitcnt vmcnt(6)
	s_setprio 1
	s_barrier
	v_mfma_f32_16x16x32_bf16 v[20:23], v[228:231], v[144:147], v[76:79]
	v_mfma_f32_16x16x32_bf16 v[76:79], v[232:235], v[148:151], v[20:23]
	v_mfma_f32_16x16x32_bf16 v[20:23], v[236:239], v[144:147], v[72:75]
	v_mfma_f32_16x16x32_bf16 v[72:75], v[240:243], v[148:151], v[20:23]
	v_mfma_f32_16x16x32_bf16 v[20:23], v[228:231], v[200:203], v[88:91]
	v_mfma_f32_16x16x32_bf16 v[88:91], v[232:235], v[204:207], v[20:23]
	v_mfma_f32_16x16x32_bf16 v[20:23], v[236:239], v[200:203], v[80:83]
	s_add_u32 s60, s60, 0x100
	v_mfma_f32_16x16x32_bf16 v[80:83], v[240:243], v[204:207], v[20:23]
	s_addc_u32 s61, s61, 0
	v_mfma_f32_16x16x32_bf16 v[20:23], v[228:231], v[208:211], v[104:107]
	s_add_u32 s24, s24, 0x10000
	v_mfma_f32_16x16x32_bf16 v[104:107], v[232:235], v[212:215], v[20:23]
	s_addc_u32 s25, s25, 0
	v_mfma_f32_16x16x32_bf16 v[20:23], v[236:239], v[208:211], v[96:99]
	s_cmp_ge_i32 s62, s59
	v_mfma_f32_16x16x32_bf16 v[96:99], v[240:243], v[212:215], v[20:23]
	s_mov_b32 s26, s62
	v_mfma_f32_16x16x32_bf16 v[20:23], v[228:231], v[220:223], v[120:123]
	v_mfma_f32_16x16x32_bf16 v[120:123], v[232:235], v[224:227], v[20:23]
	v_mfma_f32_16x16x32_bf16 v[20:23], v[236:239], v[220:223], v[124:127]
	v_mfma_f32_16x16x32_bf16 v[124:127], v[240:243], v[224:227], v[20:23]
	s_barrier
	s_setprio 0
	s_cbranch_scc0 .LBB0_739
	s_nop 5
	v_pk_mul_f32 v[2:3], v[2:3], 0.5 op_sel_hi:[1,0]
	v_pk_mul_f32 v[0:1], v[0:1], 0.5 op_sel_hi:[1,0]
	v_pk_mul_f32 v[6:7], v[6:7], 0.5 op_sel_hi:[1,0]
	v_pk_mul_f32 v[4:5], v[4:5], 0.5 op_sel_hi:[1,0]
	v_pk_mul_f32 v[22:23], v[14:15], 0.5 op_sel_hi:[1,0]
	v_pk_mul_f32 v[20:21], v[12:13], 0.5 op_sel_hi:[1,0]
	v_pk_mul_f32 v[30:31], v[10:11], 0.5 op_sel_hi:[1,0]
	v_pk_mul_f32 v[28:29], v[8:9], 0.5 op_sel_hi:[1,0]
	v_pk_mul_f32 v[10:11], v[46:47], 0.5 op_sel_hi:[1,0]
	v_pk_mul_f32 v[8:9], v[44:45], 0.5 op_sel_hi:[1,0]
	v_pk_mul_f32 v[14:15], v[38:39], 0.5 op_sel_hi:[1,0]
	v_pk_mul_f32 v[12:13], v[36:37], 0.5 op_sel_hi:[1,0]
	v_pk_mul_f32 v[38:39], v[26:27], 0.5 op_sel_hi:[1,0]
	v_pk_mul_f32 v[36:37], v[24:25], 0.5 op_sel_hi:[1,0]
	v_pk_mul_f32 v[46:47], v[18:19], 0.5 op_sel_hi:[1,0]
	v_pk_mul_f32 v[44:45], v[16:17], 0.5 op_sel_hi:[1,0]
	v_pk_mul_f32 v[18:19], v[54:55], 0.5 op_sel_hi:[1,0]
	v_pk_mul_f32 v[16:17], v[52:53], 0.5 op_sel_hi:[1,0]
	v_pk_mul_f32 v[26:27], v[50:51], 0.5 op_sel_hi:[1,0]
	v_pk_mul_f32 v[24:25], v[48:49], 0.5 op_sel_hi:[1,0]
	v_pk_mul_f32 v[50:51], v[42:43], 0.5 op_sel_hi:[1,0]
	v_pk_mul_f32 v[48:49], v[40:41], 0.5 op_sel_hi:[1,0]
	v_pk_mul_f32 v[54:55], v[34:35], 0.5 op_sel_hi:[1,0]
	v_pk_mul_f32 v[52:53], v[32:33], 0.5 op_sel_hi:[1,0]
	v_pk_mul_f32 v[34:35], v[94:95], 0.5 op_sel_hi:[1,0]
	v_pk_mul_f32 v[32:33], v[92:93], 0.5 op_sel_hi:[1,0]
	v_pk_mul_f32 v[42:43], v[86:87], 0.5 op_sel_hi:[1,0]
	v_pk_mul_f32 v[40:41], v[84:85], 0.5 op_sel_hi:[1,0]
	v_pk_mul_f32 v[58:59], v[58:59], 0.5 op_sel_hi:[1,0]
	v_pk_mul_f32 v[56:57], v[56:57], 0.5 op_sel_hi:[1,0]
	v_pk_mul_f32 v[62:63], v[62:63], 0.5 op_sel_hi:[1,0]
	v_pk_mul_f32 v[60:61], v[60:61], 0.5 op_sel_hi:[1,0]
	v_pk_mul_f32 v[66:67], v[66:67], 0.5 op_sel_hi:[1,0]
	v_pk_mul_f32 v[64:65], v[64:65], 0.5 op_sel_hi:[1,0]
	v_pk_mul_f32 v[70:71], v[70:71], 0.5 op_sel_hi:[1,0]
	v_pk_mul_f32 v[68:69], v[68:69], 0.5 op_sel_hi:[1,0]
	v_pk_mul_f32 v[86:87], v[78:79], 0.5 op_sel_hi:[1,0]
	v_pk_mul_f32 v[84:85], v[76:77], 0.5 op_sel_hi:[1,0]
	v_pk_mul_f32 v[94:95], v[74:75], 0.5 op_sel_hi:[1,0]
	v_pk_mul_f32 v[92:93], v[72:73], 0.5 op_sel_hi:[1,0]
	v_pk_mul_f32 v[74:75], v[110:111], 0.5 op_sel_hi:[1,0]
	v_pk_mul_f32 v[72:73], v[108:109], 0.5 op_sel_hi:[1,0]
	v_pk_mul_f32 v[78:79], v[102:103], 0.5 op_sel_hi:[1,0]
	v_pk_mul_f32 v[76:77], v[100:101], 0.5 op_sel_hi:[1,0]
	v_pk_mul_f32 v[102:103], v[90:91], 0.5 op_sel_hi:[1,0]
	v_pk_mul_f32 v[100:101], v[88:89], 0.5 op_sel_hi:[1,0]
	v_pk_mul_f32 v[110:111], v[82:83], 0.5 op_sel_hi:[1,0]
	v_pk_mul_f32 v[108:109], v[80:81], 0.5 op_sel_hi:[1,0]
	v_pk_mul_f32 v[82:83], v[118:119], 0.5 op_sel_hi:[1,0]
	v_pk_mul_f32 v[80:81], v[116:117], 0.5 op_sel_hi:[1,0]
	v_pk_mul_f32 v[90:91], v[114:115], 0.5 op_sel_hi:[1,0]
	v_pk_mul_f32 v[88:89], v[112:113], 0.5 op_sel_hi:[1,0]
	v_pk_mul_f32 v[114:115], v[106:107], 0.5 op_sel_hi:[1,0]
	v_pk_mul_f32 v[112:113], v[104:105], 0.5 op_sel_hi:[1,0]
	v_pk_mul_f32 v[118:119], v[98:99], 0.5 op_sel_hi:[1,0]
	v_pk_mul_f32 v[116:117], v[96:97], 0.5 op_sel_hi:[1,0]
	v_pk_mul_f32 v[98:99], v[134:135], 0.5 op_sel_hi:[1,0]
	v_pk_mul_f32 v[96:97], v[132:133], 0.5 op_sel_hi:[1,0]
	v_pk_mul_f32 v[106:107], v[130:131], 0.5 op_sel_hi:[1,0]
	v_pk_mul_f32 v[104:105], v[128:129], 0.5 op_sel_hi:[1,0]
	v_pk_mul_f32 v[122:123], v[122:123], 0.5 op_sel_hi:[1,0]
	v_pk_mul_f32 v[120:121], v[120:121], 0.5 op_sel_hi:[1,0]
	v_pk_mul_f32 v[126:127], v[126:127], 0.5 op_sel_hi:[1,0]
	v_pk_mul_f32 v[124:125], v[124:125], 0.5 op_sel_hi:[1,0]
	s_branch .LBB0_744

; #define PG8_STAGE(bufoff, gbase, voff) do { _Pragma("unroll") for (int _i = 0; _i < 2; ++_i) \
;         __builtin_amdgcn_global_load_lds((const unsigned*)((const char*)(gbase) + (voff)[_i]), (LAS unsigned*)(lds + (bufoff) + ldsw + _i * 8192), 16, 0, 0); } while (0)
; #define PG8_LDA(dst, b, h) do { _Pragma("unroll") for (int m = 0; m < 4; ++m) _Pragma("unroll") for (int k = 0; k < 2; ++k) dst[m][k] = *(const LAS bf16x8*)(lds + PG8_SA(b, h) + aoff + m * 2048 + k * 1024); } while (0)
; #define PG8_LDB(dst, b, h) do { _Pragma("unroll") for (int n = 0; n < 2; ++n) _Pragma("unroll") for (int k = 0; k < 2; ++k) dst[n][k] = *(const LAS bf16x8*)(lds + PG8_SB(b, h) + boff + n * 2048 + k * 1024); } while (0)
; #define PG8_MMA(ai, bj, At, Bt) do { __builtin_amdgcn_s_setprio(1); _Pragma("unroll") for (int m = 0; m < 4; ++m) _Pragma("unroll") for (int n = 0; n < 2; ++n) _Pragma("unroll") for (int k = 0; k < 2; ++k) \
;         acc[ai][bj][m][n] = __builtin_amdgcn_mfma_f32_16x16x32_bf16(Bt[n][k], At[m][k], acc[ai][bj][m][n], 0, 0, 0); __builtin_amdgcn_s_setprio(0); } while (0)
; #define PG8_WAIT_V(n) asm volatile("s_waitcnt vmcnt(" #n ")" ::: "memory")
; #define PG8_WAIT_L(n) asm volatile("s_waitcnt lgkmcnt(" #n ")" ::: "memory")
; template <class Epi, class Sched, bool ATILE = false>
; __device__ __forceinline__ void gemm_phase(LAS unsigned char* lds, const Gemm g, const Sched& S, const Epi& E) {
;     ...
;         for (int t = 0; t < nt; t += 2) {
;             const bool last = (t == nt - 2);
;             const char* a1 = cA + (size_t)(t + 1) * kstepA;
;             const char* a2 = last ? nA : cA + (size_t)(t + 2) * kstepA; const char* b2 = last ? nB : cB + (size_t)(t + 2) * kstep;
;             const char* a3 = a2 + kstepA; const char* b3 = b2 + kstep;
;             PG8_LDB(B0, 0, 0); PG8_SCHED; PG8_LDA(At, 0, 0); PG8_STAGE(PG8_SA(1, 1), a1 + hstepA, voffA);
;             PG8_WAIT_L(8); PG8_BAR; PG8_WAIT_L(0); PG8_MMA(0, 0, At, B0); PG8_BAR; PG8_SCHED;
;             PG8_LDB(B1, 0, 1); PG8_STAGE(PG8_SB(0, 0), b2, voffB);
;             PG8_BAR; PG8_WAIT_L(0); PG8_MMA(0, 1, At, B1); PG8_BAR;
;             PG8_LDA(At, 0, 1); PG8_STAGE(PG8_SA(0, 0), a2, voffA);
;             PG8_BAR; PG8_WAIT_L(0); PG8_MMA(1, 0, At, B0); PG8_BAR; PG8_SCHED;
;             PG8_STAGE(PG8_SB(0, 1), b2 + hstepB, voffB);
;             PG8_WAIT_V(6); PG8_BAR; PG8_MMA(1, 1, At, B1); PG8_BAR;
.LBB0_895:
	ds_read_b128 v[32:35], v165
	ds_read_b128 v[36:39], v165 offset:1024
	ds_read_b128 v[178:181], v165 offset:2048
	ds_read_b128 v[182:185], v165 offset:3072
	s_add_i32 m0, s35, 0xc000
	ds_read_b128 v[192:195], v167
	ds_read_b128 v[196:199], v167 offset:1024
	ds_read_b128 v[200:203], v167 offset:2048
	ds_read_b128 v[204:207], v167 offset:3072
	ds_read_b128 v[208:211], v167 offset:4096
	ds_read_b128 v[212:215], v167 offset:5120
	ds_read_b128 v[216:219], v167 offset:6144
	ds_read_b128 v[220:223], v167 offset:7168
	global_load_lds_dwordx4 v170, s[12:13]
	s_add_i32 m0, s35, 0xe000
	s_nop 0
	global_load_lds_dwordx4 v172, s[12:13]
	s_waitcnt lgkmcnt(8)
	s_setprio 1
	s_barrier
	s_waitcnt lgkmcnt(0)
	v_mfma_f32_16x16x32_bf16 v[132:135], v[32:35], v[192:195], v[132:135]
	s_add_i32 s88, s73, 2
	v_mfma_f32_16x16x32_bf16 v[128:131], v[178:181], v[192:195], v[128:131]
	s_add_u32 s84, s12, 0xfff80080
	v_mfma_f32_16x16x32_bf16 v[116:119], v[32:35], v[200:203], v[116:119]
	s_addc_u32 s85, s13, -1
	v_mfma_f32_16x16x32_bf16 v[112:115], v[178:181], v[200:203], v[112:115]
	s_cmp_eq_u32 s53, s73
	v_mfma_f32_16x16x32_bf16 v[100:103], v[32:35], v[208:211], v[100:103]
	s_cselect_b32 s87, s11, s85
	v_mfma_f32_16x16x32_bf16 v[96:99], v[178:181], v[208:211], v[96:99]
	s_cselect_b32 s86, s20, s84
	v_mfma_f32_16x16x32_bf16 v[84:87], v[32:35], v[216:219], v[84:87]
	s_cselect_b32 s85, s41, s63
	v_mfma_f32_16x16x32_bf16 v[80:83], v[178:181], v[216:219], v[80:83]
	s_cselect_b32 s84, s52, s62
	v_mfma_f32_16x16x32_bf16 v[132:135], v[36:39], v[196:199], v[132:135]
	s_add_i32 s73, s43, s31
	v_mfma_f32_16x16x32_bf16 v[128:131], v[182:185], v[196:199], v[128:131]
	s_add_u32 s98, s84, s22
	v_mfma_f32_16x16x32_bf16 v[116:119], v[36:39], v[204:207], v[116:119]
	s_addc_u32 s99, s85, s23
	v_mfma_f32_16x16x32_bf16 v[112:115], v[182:185], v[204:207], v[112:115]
	s_mov_b32 m0, s73
	v_mfma_f32_16x16x32_bf16 v[100:103], v[36:39], v[212:215], v[100:103]
	v_mfma_f32_16x16x32_bf16 v[96:99], v[182:185], v[212:215], v[96:99]
	v_mfma_f32_16x16x32_bf16 v[84:87], v[36:39], v[220:223], v[84:87]
	v_mfma_f32_16x16x32_bf16 v[80:83], v[182:185], v[220:223], v[80:83]
	s_barrier
	s_setprio 0
	ds_read_b128 v[224:227], v186
	ds_read_b128 v[228:231], v186 offset:1024
	ds_read_b128 v[232:235], v186 offset:2048
	ds_read_b128 v[236:239], v186 offset:3072
	global_load_lds_dwordx4 v138, s[84:85]
	s_add_i32 m0, s73, 0x2000
	s_nop 0
	global_load_lds_dwordx4 v142, s[84:85]
	s_setprio 1
	s_barrier
	s_waitcnt lgkmcnt(0)
	v_mfma_f32_16x16x32_bf16 v[124:127], v[224:227], v[192:195], v[124:127]
	v_mfma_f32_16x16x32_bf16 v[120:123], v[232:235], v[192:195], v[120:123]
	v_mfma_f32_16x16x32_bf16 v[108:111], v[224:227], v[200:203], v[108:111]
	v_mfma_f32_16x16x32_bf16 v[104:107], v[232:235], v[200:203], v[104:107]
	v_mfma_f32_16x16x32_bf16 v[92:95], v[224:227], v[208:211], v[92:95]
	v_mfma_f32_16x16x32_bf16 v[88:91], v[232:235], v[208:211], v[88:91]
	v_mfma_f32_16x16x32_bf16 v[76:79], v[224:227], v[216:219], v[76:79]
	v_mfma_f32_16x16x32_bf16 v[72:75], v[232:235], v[216:219], v[72:75]
	s_mov_b32 m0, s35
	v_mfma_f32_16x16x32_bf16 v[124:127], v[228:231], v[196:199], v[124:127]
	s_add_u32 s100, s86, s22
	v_mfma_f32_16x16x32_bf16 v[120:123], v[236:239], v[196:199], v[120:123]
	s_addc_u32 s101, s87, s23
	v_mfma_f32_16x16x32_bf16 v[108:111], v[228:231], v[204:207], v[108:111]
	v_mfma_f32_16x16x32_bf16 v[104:107], v[236:239], v[204:207], v[104:107]
	v_mfma_f32_16x16x32_bf16 v[92:95], v[228:231], v[212:215], v[92:95]
	v_mfma_f32_16x16x32_bf16 v[88:91], v[236:239], v[212:215], v[88:91]
	v_mfma_f32_16x16x32_bf16 v[76:79], v[228:231], v[220:223], v[76:79]
	v_mfma_f32_16x16x32_bf16 v[72:75], v[236:239], v[220:223], v[72:75]
	s_barrier
	s_setprio 0
	ds_read_b128 v[192:195], v167 offset:16384
	ds_read_b128 v[196:199], v167 offset:17408
	ds_read_b128 v[200:203], v167 offset:18432
	ds_read_b128 v[204:207], v167 offset:19456
	ds_read_b128 v[208:211], v167 offset:20480
	ds_read_b128 v[212:215], v167 offset:21504
	ds_read_b128 v[216:219], v167 offset:22528
	ds_read_b128 v[220:223], v167 offset:23552
	global_load_lds_dwordx4 v136, s[86:87]
	s_mov_b32 m0, s37
	s_nop 0
	global_load_lds_dwordx4 v140, s[86:87]
	s_setprio 1
	s_barrier
	s_waitcnt lgkmcnt(0)
	v_mfma_f32_16x16x32_bf16 v[68:71], v[32:35], v[192:195], v[68:71]
	v_mfma_f32_16x16x32_bf16 v[64:67], v[178:181], v[192:195], v[64:67]
	v_mfma_f32_16x16x32_bf16 v[52:55], v[32:35], v[200:203], v[52:55]
	v_mfma_f32_16x16x32_bf16 v[48:51], v[178:181], v[200:203], v[48:51]
	v_mfma_f32_16x16x32_bf16 v[28:31], v[32:35], v[208:211], v[28:31]
	v_mfma_f32_16x16x32_bf16 v[24:27], v[178:181], v[208:211], v[24:27]
	v_mfma_f32_16x16x32_bf16 v[12:15], v[32:35], v[216:219], v[12:15]
	v_mfma_f32_16x16x32_bf16 v[8:11], v[178:181], v[216:219], v[8:11]
	s_add_u32 vcc_lo, s84, 0x80000
	v_mfma_f32_16x16x32_bf16 v[68:71], v[36:39], v[196:199], v[68:71]
	s_addc_u32 vcc_hi, s85, 0
	v_mfma_f32_16x16x32_bf16 v[64:67], v[182:185], v[196:199], v[64:67]
	s_add_i32 s73, s56, s31
	v_mfma_f32_16x16x32_bf16 v[52:55], v[36:39], v[204:207], v[52:55]
	v_mfma_f32_16x16x32_bf16 v[48:51], v[182:185], v[204:207], v[48:51]
	v_mfma_f32_16x16x32_bf16 v[28:31], v[36:39], v[212:215], v[28:31]
	v_mfma_f32_16x16x32_bf16 v[24:27], v[182:185], v[212:215], v[24:27]
	v_mfma_f32_16x16x32_bf16 v[12:15], v[36:39], v[220:223], v[12:15]
	v_mfma_f32_16x16x32_bf16 v[8:11], v[182:185], v[220:223], v[8:11]
	s_barrier
	s_setprio 0
	v_lshl_add_u64 v[32:33], vcc, 0, v[138:139]
	s_mov_b32 m0, s73
	s_nop 0
	global_load_lds_dwordx4 v[32:33], off
	v_lshl_add_u64 v[32:33], vcc, 0, v[142:143]
	s_add_i32 m0, s73, 0x2000
	s_nop 0
	global_load_lds_dwordx4 v[32:33], off
	s_waitcnt vmcnt(6)
	s_setprio 1
	s_barrier
; #define PG8_STAGE(bufoff, gbase, voff) do { _Pragma("unroll") for (int _i = 0; _i < 2; ++_i) \
;         __builtin_amdgcn_global_load_lds((const unsigned*)((const char*)(gbase) + (voff)[_i]), (LAS unsigned*)(lds + (bufoff) + ldsw + _i * 8192), 16, 0, 0); } while (0)
; #define PG8_LDA(dst, b, h) do { _Pragma("unroll") for (int m = 0; m < 4; ++m) _Pragma("unroll") for (int k = 0; k < 2; ++k) dst[m][k] = *(const LAS bf16x8*)(lds + PG8_SA(b, h) + aoff + m * 2048 + k * 1024); } while (0)
; #define PG8_LDB(dst, b, h) do { _Pragma("unroll") for (int n = 0; n < 2; ++n) _Pragma("unroll") for (int k = 0; k < 2; ++k) dst[n][k] = *(const LAS bf16x8*)(lds + PG8_SB(b, h) + boff + n * 2048 + k * 1024); } while (0)
; #define PG8_MMA(ai, bj, At, Bt) do { __builtin_amdgcn_s_setprio(1); _Pragma("unroll") for (int m = 0; m < 4; ++m) _Pragma("unroll") for (int n = 0; n < 2; ++n) _Pragma("unroll") for (int k = 0; k < 2; ++k) \
;         acc[ai][bj][m][n] = __builtin_amdgcn_mfma_f32_16x16x32_bf16(Bt[n][k], At[m][k], acc[ai][bj][m][n], 0, 0, 0); __builtin_amdgcn_s_setprio(0); } while (0)
; #define PG8_WAIT_V(n) asm volatile("s_waitcnt vmcnt(" #n ")" ::: "memory")
; #define PG8_WAIT_L(n) asm volatile("s_waitcnt lgkmcnt(" #n ")" ::: "memory")
; #define PG8_BAR __builtin_amdgcn_s_barrier()
; #define PG8_SCHED __builtin_amdgcn_sched_barrier(0)
; template <class Epi, class Sched, bool ATILE = false>
; __device__ __forceinline__ void gemm_phase(LAS unsigned char* lds, const Gemm g, const Sched& S, const Epi& E) {
;     ...
;             PG8_WAIT_V(6); PG8_BAR; PG8_MMA(1, 1, At, B1); PG8_BAR;
;             PG8_LDB(B0, 1, 0); PG8_SCHED; PG8_LDA(At, 1, 0); PG8_STAGE(PG8_SA(0, 1), a2 + hstepA, voffA);
;             PG8_WAIT_L(8); PG8_BAR; PG8_WAIT_L(0); PG8_MMA(0, 0, At, B0); PG8_BAR; PG8_SCHED;
;             PG8_LDB(B1, 1, 1); PG8_STAGE(PG8_SB(1, 0), b3, voffB);
;             PG8_BAR; PG8_WAIT_L(0); PG8_MMA(0, 1, At, B1); PG8_BAR;
;             PG8_LDA(At, 1, 1); PG8_STAGE(PG8_SA(1, 0), a3, voffA);
;             PG8_BAR; PG8_WAIT_L(0); PG8_MMA(1, 0, At, B0); PG8_BAR; PG8_SCHED;
	v_mfma_f32_16x16x32_bf16 v[44:47], v[224:227], v[200:203], v[44:47]
	v_mfma_f32_16x16x32_bf16 v[40:43], v[232:235], v[200:203], v[40:43]
	v_mfma_f32_16x16x32_bf16 v[20:23], v[224:227], v[208:211], v[20:23]
	v_mfma_f32_16x16x32_bf16 v[16:19], v[232:235], v[208:211], v[16:19]
	v_mfma_f32_16x16x32_bf16 v[4:7], v[224:227], v[216:219], v[4:7]
	v_mfma_f32_16x16x32_bf16 v[0:3], v[232:235], v[216:219], v[0:3]
	v_mfma_f32_16x16x32_bf16 v[32:35], v[224:227], v[192:195], v[60:63]
	v_mfma_f32_16x16x32_bf16 v[36:39], v[232:235], v[192:195], v[56:59]
	s_add_i32 s73, 0, 0x18000
	v_mfma_f32_16x16x32_bf16 v[44:47], v[228:231], v[204:207], v[44:47]
	v_add_u32_e32 v144, s73, v161
	v_mfma_f32_16x16x32_bf16 v[40:43], v[236:239], v[204:207], v[40:43]
	v_mfma_f32_16x16x32_bf16 v[20:23], v[228:231], v[212:215], v[20:23]
	v_mfma_f32_16x16x32_bf16 v[16:19], v[236:239], v[212:215], v[16:19]
	v_mfma_f32_16x16x32_bf16 v[4:7], v[228:231], v[220:223], v[4:7]
	v_mfma_f32_16x16x32_bf16 v[0:3], v[236:239], v[220:223], v[0:3]
	v_mfma_f32_16x16x32_bf16 v[32:35], v[228:231], v[196:199], v[32:35]
	v_mfma_f32_16x16x32_bf16 v[36:39], v[236:239], v[196:199], v[36:39]
	s_barrier
	s_setprio 0
	ds_read_b128 v[56:59], v144
	ds_read_b128 v[60:63], v144 offset:1024
	ds_read_b128 v[178:181], v144 offset:2048
	ds_read_b128 v[182:185], v144 offset:3072
	s_add_u32 s86, s86, 0x80000
	s_addc_u32 s87, s87, 0
	s_mov_b32 m0, s39
	ds_read_b128 v[192:195], v167 offset:32768
	ds_read_b128 v[196:199], v167 offset:33792
	ds_read_b128 v[200:203], v167 offset:34816
	ds_read_b128 v[204:207], v167 offset:35840
	ds_read_b128 v[208:211], v167 offset:36864
	ds_read_b128 v[212:215], v167 offset:37888
	ds_read_b128 v[216:219], v167 offset:38912
	ds_read_b128 v[220:223], v167 offset:39936
	global_load_lds_dwordx4 v136, s[86:87]
	s_mov_b32 m0, s97
	s_nop 0
	global_load_lds_dwordx4 v140, s[86:87]
	s_waitcnt lgkmcnt(8)
	s_setprio 1
	s_barrier
	s_waitcnt lgkmcnt(0)
	v_mfma_f32_16x16x32_bf16 v[132:135], v[56:59], v[192:195], v[132:135]
	v_mfma_f32_16x16x32_bf16 v[128:131], v[178:181], v[192:195], v[128:131]
	v_mfma_f32_16x16x32_bf16 v[116:119], v[56:59], v[200:203], v[116:119]
	v_mfma_f32_16x16x32_bf16 v[112:115], v[178:181], v[200:203], v[112:115]
	v_mfma_f32_16x16x32_bf16 v[100:103], v[56:59], v[208:211], v[100:103]
	v_mfma_f32_16x16x32_bf16 v[96:99], v[178:181], v[208:211], v[96:99]
	v_mfma_f32_16x16x32_bf16 v[84:87], v[56:59], v[216:219], v[84:87]
	v_mfma_f32_16x16x32_bf16 v[80:83], v[178:181], v[216:219], v[80:83]
	s_add_i32 s86, 0, 0x1c000
	v_mfma_f32_16x16x32_bf16 v[132:135], v[60:63], v[196:199], v[132:135]
	s_add_i32 s73, s73, s31
	v_mfma_f32_16x16x32_bf16 v[128:131], v[182:185], v[196:199], v[128:131]
	v_add_u32_e32 v144, s86, v161
	v_mfma_f32_16x16x32_bf16 v[116:119], v[60:63], v[204:207], v[116:119]
	s_mov_b32 m0, s73
	v_mfma_f32_16x16x32_bf16 v[112:115], v[182:185], v[204:207], v[112:115]
	v_mfma_f32_16x16x32_bf16 v[100:103], v[60:63], v[212:215], v[100:103]
	v_mfma_f32_16x16x32_bf16 v[96:99], v[182:185], v[212:215], v[96:99]
	v_mfma_f32_16x16x32_bf16 v[84:87], v[60:63], v[220:223], v[84:87]
	v_mfma_f32_16x16x32_bf16 v[80:83], v[182:185], v[220:223], v[80:83]
	s_barrier
	s_setprio 0
	ds_read_b128 v[224:227], v144
	ds_read_b128 v[228:231], v144 offset:1024
	ds_read_b128 v[232:235], v144 offset:2048
	ds_read_b128 v[236:239], v144 offset:3072
	global_load_lds_dwordx4 v138, s[98:99]
	s_add_i32 m0, s73, 0x2000
	s_nop 0
	global_load_lds_dwordx4 v142, s[98:99]
	s_setprio 1
	s_barrier
; #define PG8_STAGE(bufoff, gbase, voff) do { _Pragma("unroll") for (int _i = 0; _i < 2; ++_i) \
;         __builtin_amdgcn_global_load_lds((const unsigned*)((const char*)(gbase) + (voff)[_i]), (LAS unsigned*)(lds + (bufoff) + ldsw + _i * 8192), 16, 0, 0); } while (0)
; #define PG8_LDA(dst, b, h) do { _Pragma("unroll") for (int m = 0; m < 4; ++m) _Pragma("unroll") for (int k = 0; k < 2; ++k) dst[m][k] = *(const LAS bf16x8*)(lds + PG8_SA(b, h) + aoff + m * 2048 + k * 1024); } while (0)
; #define PG8_MMA(ai, bj, At, Bt) do { __builtin_amdgcn_s_setprio(1); _Pragma("unroll") for (int m = 0; m < 4; ++m) _Pragma("unroll") for (int n = 0; n < 2; ++n) _Pragma("unroll") for (int k = 0; k < 2; ++k) \
;         acc[ai][bj][m][n] = __builtin_amdgcn_mfma_f32_16x16x32_bf16(Bt[n][k], At[m][k], acc[ai][bj][m][n], 0, 0, 0); __builtin_amdgcn_s_setprio(0); } while (0)
; #define PG8_WAIT_V(n) asm volatile("s_waitcnt vmcnt(" #n ")" ::: "memory")
; #define PG8_WAIT_L(n) asm volatile("s_waitcnt lgkmcnt(" #n ")" ::: "memory")
; #define PG8_BAR __builtin_amdgcn_s_barrier()
; #define PG8_SCHED __builtin_amdgcn_sched_barrier(0)
; template <class Epi, class Sched, bool ATILE = false>
; __device__ __forceinline__ void gemm_phase(LAS unsigned char* lds, const Gemm g, const Sched& S, const Epi& E) {
;     ...
;             PG8_BAR; PG8_WAIT_L(0); PG8_MMA(0, 1, At, B1); PG8_BAR;
;             PG8_LDA(At, 1, 1); PG8_STAGE(PG8_SA(1, 0), a3, voffA);
;             PG8_BAR; PG8_WAIT_L(0); PG8_MMA(1, 0, At, B0); PG8_BAR; PG8_SCHED;
;             PG8_STAGE(PG8_SB(1, 1), b3 + hstepB, voffB);
;             PG8_WAIT_V(6); PG8_BAR; PG8_MMA(1, 1, At, B1); PG8_BAR;
	s_waitcnt lgkmcnt(0)
	v_mfma_f32_16x16x32_bf16 v[124:127], v[224:227], v[192:195], v[124:127]
	v_mfma_f32_16x16x32_bf16 v[120:123], v[232:235], v[192:195], v[120:123]
	v_mfma_f32_16x16x32_bf16 v[108:111], v[224:227], v[200:203], v[108:111]
	v_mfma_f32_16x16x32_bf16 v[104:107], v[232:235], v[200:203], v[104:107]
	v_mfma_f32_16x16x32_bf16 v[92:95], v[224:227], v[208:211], v[92:95]
	v_mfma_f32_16x16x32_bf16 v[88:91], v[232:235], v[208:211], v[88:91]
	v_mfma_f32_16x16x32_bf16 v[76:79], v[224:227], v[216:219], v[76:79]
	v_mfma_f32_16x16x32_bf16 v[72:75], v[232:235], v[216:219], v[72:75]
	s_mov_b32 m0, s4
	v_mfma_f32_16x16x32_bf16 v[124:127], v[228:231], v[196:199], v[124:127]
	v_mfma_f32_16x16x32_bf16 v[120:123], v[236:239], v[196:199], v[120:123]
	v_mfma_f32_16x16x32_bf16 v[108:111], v[228:231], v[204:207], v[108:111]
	v_mfma_f32_16x16x32_bf16 v[104:107], v[236:239], v[204:207], v[104:107]
	v_mfma_f32_16x16x32_bf16 v[92:95], v[228:231], v[212:215], v[92:95]
	v_mfma_f32_16x16x32_bf16 v[88:91], v[236:239], v[212:215], v[88:91]
	v_mfma_f32_16x16x32_bf16 v[76:79], v[228:231], v[220:223], v[76:79]
	v_mfma_f32_16x16x32_bf16 v[72:75], v[236:239], v[220:223], v[72:75]
	s_barrier
	s_setprio 0
	ds_read_b128 v[192:195], v167 offset:49152
	ds_read_b128 v[196:199], v167 offset:50176
	ds_read_b128 v[200:203], v167 offset:51200
	ds_read_b128 v[204:207], v167 offset:52224
	ds_read_b128 v[208:211], v167 offset:53248
	ds_read_b128 v[212:215], v167 offset:54272
	ds_read_b128 v[216:219], v167 offset:55296
	ds_read_b128 v[220:223], v167 offset:56320
	global_load_lds_dwordx4 v136, s[100:101]
	s_mov_b32 m0, s5
	s_nop 0
	global_load_lds_dwordx4 v140, s[100:101]
	s_setprio 1
	s_barrier
	s_waitcnt lgkmcnt(0)
	v_mfma_f32_16x16x32_bf16 v[68:71], v[56:59], v[192:195], v[68:71]
	v_mfma_f32_16x16x32_bf16 v[64:67], v[178:181], v[192:195], v[64:67]
	v_mfma_f32_16x16x32_bf16 v[52:55], v[56:59], v[200:203], v[52:55]
	v_mfma_f32_16x16x32_bf16 v[48:51], v[178:181], v[200:203], v[48:51]
	v_mfma_f32_16x16x32_bf16 v[28:31], v[56:59], v[208:211], v[28:31]
	v_mfma_f32_16x16x32_bf16 v[24:27], v[178:181], v[208:211], v[24:27]
	v_mfma_f32_16x16x32_bf16 v[12:15], v[56:59], v[216:219], v[12:15]
	v_mfma_f32_16x16x32_bf16 v[8:11], v[178:181], v[216:219], v[8:11]
	s_add_u32 s84, s84, 0x80080
	v_mfma_f32_16x16x32_bf16 v[68:71], v[60:63], v[196:199], v[68:71]
	s_addc_u32 s85, s85, 0
	v_mfma_f32_16x16x32_bf16 v[64:67], v[182:185], v[196:199], v[64:67]
	s_add_i32 s73, s86, s31
	v_mfma_f32_16x16x32_bf16 v[52:55], v[60:63], v[204:207], v[52:55]
	s_mov_b32 m0, s73
	v_mfma_f32_16x16x32_bf16 v[48:51], v[182:185], v[204:207], v[48:51]
	v_mfma_f32_16x16x32_bf16 v[28:31], v[60:63], v[212:215], v[28:31]
	v_mfma_f32_16x16x32_bf16 v[24:27], v[182:185], v[212:215], v[24:27]
	v_mfma_f32_16x16x32_bf16 v[12:15], v[60:63], v[220:223], v[12:15]
	v_mfma_f32_16x16x32_bf16 v[8:11], v[182:185], v[220:223], v[8:11]
	s_barrier
	s_setprio 0
	s_nop 0
	global_load_lds_dwordx4 v138, s[84:85]
	s_add_i32 m0, s73, 0x2000
	s_nop 0
	global_load_lds_dwordx4 v142, s[84:85]
	s_waitcnt vmcnt(6)
	s_setprio 1
	s_barrier
	v_mfma_f32_16x16x32_bf16 v[32:35], v[224:227], v[192:195], v[32:35]
	v_mfma_f32_16x16x32_bf16 v[60:63], v[228:231], v[196:199], v[32:35]
	v_mfma_f32_16x16x32_bf16 v[32:35], v[232:235], v[192:195], v[36:39]
	v_mfma_f32_16x16x32_bf16 v[56:59], v[236:239], v[196:199], v[32:35]
	v_mfma_f32_16x16x32_bf16 v[32:35], v[224:227], v[200:203], v[44:47]
	v_mfma_f32_16x16x32_bf16 v[44:47], v[228:231], v[204:207], v[32:35]
	v_mfma_f32_16x16x32_bf16 v[32:35], v[232:235], v[200:203], v[40:43]
	s_add_u32 s12, s12, 0x100
	v_mfma_f32_16x16x32_bf16 v[20:23], v[224:227], v[208:211], v[20:23]
	s_addc_u32 s13, s13, 0
	v_mfma_f32_16x16x32_bf16 v[16:19], v[232:235], v[208:211], v[16:19]
	s_add_u32 s62, s62, 0x100
	v_mfma_f32_16x16x32_bf16 v[4:7], v[224:227], v[216:219], v[4:7]
	s_addc_u32 s63, s63, 0
	v_mfma_f32_16x16x32_bf16 v[0:3], v[232:235], v[216:219], v[0:3]
	s_cmp_ge_i32 s88, s1
	v_mfma_f32_16x16x32_bf16 v[40:43], v[236:239], v[204:207], v[32:35]
	s_mov_b32 s73, s88
	v_mfma_f32_16x16x32_bf16 v[20:23], v[228:231], v[212:215], v[20:23]
	v_mfma_f32_16x16x32_bf16 v[16:19], v[236:239], v[212:215], v[16:19]
	v_mfma_f32_16x16x32_bf16 v[4:7], v[228:231], v[220:223], v[4:7]
	v_mfma_f32_16x16x32_bf16 v[0:3], v[236:239], v[220:223], v[0:3]
	s_barrier
	s_setprio 0
	s_cbranch_scc0 .LBB0_895
	s_nop 5
	s_branch .LBB0_897

; #define PG8_STAGE(bufoff, gbase, voff) do { _Pragma("unroll") for (int _i = 0; _i < 2; ++_i) \
;         __builtin_amdgcn_global_load_lds((const unsigned*)((const char*)(gbase) + (voff)[_i]), (LAS unsigned*)(lds + (bufoff) + ldsw + _i * 8192), 16, 0, 0); } while (0)
; #define PG8_LDA(dst, b, h) do { _Pragma("unroll") for (int m = 0; m < 4; ++m) _Pragma("unroll") for (int k = 0; k < 2; ++k) dst[m][k] = *(const LAS bf16x8*)(lds + PG8_SA(b, h) + aoff + m * 2048 + k * 1024); } while (0)
; #define PG8_LDB(dst, b, h) do { _Pragma("unroll") for (int n = 0; n < 2; ++n) _Pragma("unroll") for (int k = 0; k < 2; ++k) dst[n][k] = *(const LAS bf16x8*)(lds + PG8_SB(b, h) + boff + n * 2048 + k * 1024); } while (0)
; #define PG8_MMA(ai, bj, At, Bt) do { __builtin_amdgcn_s_setprio(1); _Pragma("unroll") for (int m = 0; m < 4; ++m) _Pragma("unroll") for (int n = 0; n < 2; ++n) _Pragma("unroll") for (int k = 0; k < 2; ++k) \
;         acc[ai][bj][m][n] = __builtin_amdgcn_mfma_f32_16x16x32_bf16(Bt[n][k], At[m][k], acc[ai][bj][m][n], 0, 0, 0); __builtin_amdgcn_s_setprio(0); } while (0)
; #define PG8_WAIT_V(n) asm volatile("s_waitcnt vmcnt(" #n ")" ::: "memory")
; #define PG8_WAIT_L(n) asm volatile("s_waitcnt lgkmcnt(" #n ")" ::: "memory")
; template <class Epi, class Sched, bool ATILE = false>
; __device__ __forceinline__ void gemm_phase(LAS unsigned char* lds, const Gemm g, const Sched& S, const Epi& E) {
;     ...
;         for (int t = 0; t < nt; t += 2) {
;             const bool last = (t == nt - 2);
;             const char* a1 = cA + (size_t)(t + 1) * kstepA;
;             const char* a2 = last ? nA : cA + (size_t)(t + 2) * kstepA; const char* b2 = last ? nB : cB + (size_t)(t + 2) * kstep;
;             const char* a3 = a2 + kstepA; const char* b3 = b2 + kstep;
;             PG8_LDB(B0, 0, 0); PG8_SCHED; PG8_LDA(At, 0, 0); PG8_STAGE(PG8_SA(1, 1), a1 + hstepA, voffA);
;             PG8_WAIT_L(8); PG8_BAR; PG8_WAIT_L(0); PG8_MMA(0, 0, At, B0); PG8_BAR; PG8_SCHED;
;             PG8_LDB(B1, 0, 1); PG8_STAGE(PG8_SB(0, 0), b2, voffB);
;             PG8_BAR; PG8_WAIT_L(0); PG8_MMA(0, 1, At, B1); PG8_BAR;
;             PG8_LDA(At, 0, 1); PG8_STAGE(PG8_SA(0, 0), a2, voffA);
;             PG8_BAR; PG8_WAIT_L(0); PG8_MMA(1, 0, At, B0); PG8_BAR; PG8_SCHED;
;             PG8_STAGE(PG8_SB(0, 1), b2 + hstepB, voffB);
;             PG8_WAIT_V(6); PG8_BAR; PG8_MMA(1, 1, At, B1); PG8_BAR;
.LBB0_1298:
	ds_read_b128 v[82:85], v79
	ds_read_b128 v[86:89], v79 offset:1024
	ds_read_b128 v[90:93], v79 offset:2048
	ds_read_b128 v[94:97], v79 offset:3072
	s_mov_b32 m0, s38
	v_lshl_add_u64 v[130:131], s[16:17], 0, v[74:75]
	ds_read_b128 v[98:101], v80
	ds_read_b128 v[102:105], v80 offset:1024
	ds_read_b128 v[106:109], v80 offset:2048
	ds_read_b128 v[110:113], v80 offset:3072
	ds_read_b128 v[114:117], v80 offset:4096
	ds_read_b128 v[118:121], v80 offset:5120
	ds_read_b128 v[122:125], v80 offset:6144
	ds_read_b128 v[126:129], v80 offset:7168
	global_load_lds_dwordx4 v[130:131], off
	v_lshl_add_u64 v[130:131], s[16:17], 0, v[76:77]
	s_mov_b32 m0, s39
	s_nop 0
	global_load_lds_dwordx4 v[130:131], off
	s_waitcnt lgkmcnt(8)
	s_setprio 1
	s_barrier
	s_waitcnt lgkmcnt(0)
	v_mfma_f32_16x16x32_bf16 v[60:63], v[82:85], v[98:101], v[60:63]
	s_add_i32 s60, s20, 2
	v_mfma_f32_16x16x32_bf16 v[56:59], v[90:93], v[98:101], v[56:59]
	s_add_u32 s18, s16, 0x100
	v_mfma_f32_16x16x32_bf16 v[52:55], v[82:85], v[106:109], v[52:55]
	s_addc_u32 s19, s17, 0
	v_mfma_f32_16x16x32_bf16 v[48:51], v[90:93], v[106:109], v[48:51]
	s_cmp_eq_u32 s57, s20
	v_mfma_f32_16x16x32_bf16 v[44:47], v[82:85], v[114:117], v[44:47]
	s_cselect_b32 s20, s56, s58
	v_mfma_f32_16x16x32_bf16 v[40:43], v[90:93], v[114:117], v[40:43]
	s_cselect_b32 s23, s9, s19
	v_mfma_f32_16x16x32_bf16 v[36:39], v[82:85], v[122:125], v[36:39]
	s_cselect_b32 s22, s8, s18
	v_mfma_f32_16x16x32_bf16 v[32:35], v[90:93], v[122:125], v[32:35]
	s_cselect_b32 s21, s55, s59
	v_mfma_f32_16x16x32_bf16 v[60:63], v[86:89], v[102:105], v[60:63]
	s_mov_b32 m0, s40
	v_mfma_f32_16x16x32_bf16 v[56:59], v[94:97], v[102:105], v[56:59]
	v_mfma_f32_16x16x32_bf16 v[52:55], v[86:89], v[110:113], v[52:55]
	v_mfma_f32_16x16x32_bf16 v[48:51], v[94:97], v[110:113], v[48:51]
	v_mfma_f32_16x16x32_bf16 v[44:47], v[86:89], v[118:121], v[44:47]
	v_mfma_f32_16x16x32_bf16 v[40:43], v[94:97], v[118:121], v[40:43]
	v_mfma_f32_16x16x32_bf16 v[36:39], v[86:89], v[126:129], v[36:39]
	v_mfma_f32_16x16x32_bf16 v[32:35], v[94:97], v[126:129], v[32:35]
	s_barrier
	s_setprio 0
	v_lshl_add_u64 v[130:131], s[20:21], 0, v[68:69]
	global_load_lds_dwordx4 v[130:131], off
	v_lshl_add_u64 v[132:133], s[20:21], 0, v[64:65]
	s_mov_b32 m0, s41
	s_nop 0
	global_load_lds_dwordx4 v[132:133], off
	s_barrier
	s_waitcnt lgkmcnt(0)
	s_setprio 1
	s_setprio 0
	s_mov_b32 m0, s25
	v_lshl_add_u64 v[134:135], s[22:23], 0, v[70:71]
	s_barrier
	ds_read_b128 v[98:101], v80 offset:16384
	ds_read_b128 v[102:105], v80 offset:17408
	ds_read_b128 v[106:109], v80 offset:18432
	ds_read_b128 v[110:113], v80 offset:19456
	ds_read_b128 v[114:117], v80 offset:20480
	ds_read_b128 v[118:121], v80 offset:21504
	ds_read_b128 v[122:125], v80 offset:22528
	ds_read_b128 v[126:129], v80 offset:23552
	global_load_lds_dwordx4 v[134:135], off
	v_lshl_add_u64 v[136:137], s[22:23], 0, v[66:67]
	s_mov_b32 m0, s26
	s_nop 0
	global_load_lds_dwordx4 v[136:137], off
	s_setprio 1
	s_barrier
	s_waitcnt lgkmcnt(0)
	v_mfma_f32_16x16x32_bf16 v[28:31], v[82:85], v[98:101], v[28:31]
	v_mfma_f32_16x16x32_bf16 v[24:27], v[90:93], v[98:101], v[24:27]
	v_mfma_f32_16x16x32_bf16 v[20:23], v[82:85], v[106:109], v[20:23]
	v_mfma_f32_16x16x32_bf16 v[16:19], v[90:93], v[106:109], v[16:19]
	v_mfma_f32_16x16x32_bf16 v[12:15], v[82:85], v[114:117], v[12:15]
	v_mfma_f32_16x16x32_bf16 v[8:11], v[90:93], v[114:117], v[8:11]
	v_mfma_f32_16x16x32_bf16 v[4:7], v[82:85], v[122:125], v[4:7]
	v_mfma_f32_16x16x32_bf16 v[0:3], v[90:93], v[122:125], v[0:3]
	s_add_u32 s16, s20, 0x10000
	v_mfma_f32_16x16x32_bf16 v[28:31], v[86:89], v[102:105], v[28:31]
	s_addc_u32 s17, s21, 0
	v_mfma_f32_16x16x32_bf16 v[24:27], v[94:97], v[102:105], v[24:27]
	s_mov_b32 m0, s27
	v_mfma_f32_16x16x32_bf16 v[20:23], v[86:89], v[110:113], v[20:23]
	v_mfma_f32_16x16x32_bf16 v[16:19], v[94:97], v[110:113], v[16:19]
	v_mfma_f32_16x16x32_bf16 v[12:15], v[86:89], v[118:121], v[12:15]
	v_mfma_f32_16x16x32_bf16 v[8:11], v[94:97], v[118:121], v[8:11]
	v_mfma_f32_16x16x32_bf16 v[4:7], v[86:89], v[126:129], v[4:7]
	v_mfma_f32_16x16x32_bf16 v[0:3], v[94:97], v[126:129], v[0:3]
	s_barrier
	s_setprio 0
	s_nop 0
	global_load_lds_dwordx4 v68, s[16:17]
	s_mov_b32 m0, s28
	s_nop 0
	global_load_lds_dwordx4 v64, s[16:17]
	s_waitcnt vmcnt(6)
	s_barrier
; #define PG8_STAGE(bufoff, gbase, voff) do { _Pragma("unroll") for (int _i = 0; _i < 2; ++_i) \
;         __builtin_amdgcn_global_load_lds((const unsigned*)((const char*)(gbase) + (voff)[_i]), (LAS unsigned*)(lds + (bufoff) + ldsw + _i * 8192), 16, 0, 0); } while (0)
; #define PG8_LDA(dst, b, h) do { _Pragma("unroll") for (int m = 0; m < 4; ++m) _Pragma("unroll") for (int k = 0; k < 2; ++k) dst[m][k] = *(const LAS bf16x8*)(lds + PG8_SA(b, h) + aoff + m * 2048 + k * 1024); } while (0)
; #define PG8_LDB(dst, b, h) do { _Pragma("unroll") for (int n = 0; n < 2; ++n) _Pragma("unroll") for (int k = 0; k < 2; ++k) dst[n][k] = *(const LAS bf16x8*)(lds + PG8_SB(b, h) + boff + n * 2048 + k * 1024); } while (0)
; #define PG8_MMA(ai, bj, At, Bt) do { __builtin_amdgcn_s_setprio(1); _Pragma("unroll") for (int m = 0; m < 4; ++m) _Pragma("unroll") for (int n = 0; n < 2; ++n) _Pragma("unroll") for (int k = 0; k < 2; ++k) \
;         acc[ai][bj][m][n] = __builtin_amdgcn_mfma_f32_16x16x32_bf16(Bt[n][k], At[m][k], acc[ai][bj][m][n], 0, 0, 0); __builtin_amdgcn_s_setprio(0); } while (0)
; #define PG8_WAIT_V(n) asm volatile("s_waitcnt vmcnt(" #n ")" ::: "memory")
; #define PG8_WAIT_L(n) asm volatile("s_waitcnt lgkmcnt(" #n ")" ::: "memory")
; #define PG8_BAR __builtin_amdgcn_s_barrier()
; #define PG8_SCHED __builtin_amdgcn_sched_barrier(0)
; template <class Epi, class Sched, bool ATILE = false>
; __device__ __forceinline__ void gemm_phase(LAS unsigned char* lds, const Gemm g, const Sched& S, const Epi& E) {
;     ...
;             PG8_LDB(B0, 1, 0); PG8_SCHED; PG8_LDA(At, 1, 0); PG8_STAGE(PG8_SA(0, 1), a2 + hstepA, voffA);
;             PG8_WAIT_L(8); PG8_BAR; PG8_WAIT_L(0); PG8_MMA(0, 0, At, B0); PG8_BAR; PG8_SCHED;
;             PG8_LDB(B1, 1, 1); PG8_STAGE(PG8_SB(1, 0), b3, voffB);
;             PG8_BAR; PG8_WAIT_L(0); PG8_MMA(0, 1, At, B1); PG8_BAR;
;             PG8_LDA(At, 1, 1); PG8_STAGE(PG8_SA(1, 0), a3, voffA);
;             PG8_BAR; PG8_WAIT_L(0); PG8_MMA(1, 0, At, B0); PG8_BAR; PG8_SCHED;
;             PG8_STAGE(PG8_SB(1, 1), b3 + hstepB, voffB);
;             PG8_WAIT_V(6); PG8_BAR; PG8_MMA(1, 1, At, B1); PG8_BAR;
	s_setprio 1
	s_setprio 0
	s_barrier
	ds_read_b128 v[82:85], v81
	ds_read_b128 v[86:89], v81 offset:1024
	ds_read_b128 v[90:93], v81 offset:2048
	ds_read_b128 v[94:97], v81 offset:3072
	s_add_u32 s16, s22, 0x18000
	s_addc_u32 s17, s23, 0
	s_mov_b32 m0, s29
	ds_read_b128 v[98:101], v80 offset:32768
	ds_read_b128 v[102:105], v80 offset:33792
	ds_read_b128 v[106:109], v80 offset:34816
	ds_read_b128 v[110:113], v80 offset:35840
	ds_read_b128 v[114:117], v80 offset:36864
	ds_read_b128 v[118:121], v80 offset:37888
	ds_read_b128 v[122:125], v80 offset:38912
	ds_read_b128 v[126:129], v80 offset:39936
	global_load_lds_dwordx4 v70, s[16:17]
	s_mov_b32 m0, s30
	s_nop 0
	global_load_lds_dwordx4 v66, s[16:17]
	s_waitcnt lgkmcnt(8)
	s_setprio 1
	s_barrier
	s_waitcnt lgkmcnt(0)
	v_mfma_f32_16x16x32_bf16 v[60:63], v[82:85], v[98:101], v[60:63]
	v_mfma_f32_16x16x32_bf16 v[56:59], v[90:93], v[98:101], v[56:59]
	v_mfma_f32_16x16x32_bf16 v[52:55], v[82:85], v[106:109], v[52:55]
	v_mfma_f32_16x16x32_bf16 v[48:51], v[90:93], v[106:109], v[48:51]
	v_mfma_f32_16x16x32_bf16 v[44:47], v[82:85], v[114:117], v[44:47]
	v_mfma_f32_16x16x32_bf16 v[40:43], v[90:93], v[114:117], v[40:43]
	v_mfma_f32_16x16x32_bf16 v[36:39], v[82:85], v[122:125], v[36:39]
	v_mfma_f32_16x16x32_bf16 v[32:35], v[90:93], v[122:125], v[32:35]
	s_mov_b32 m0, s43
	v_mfma_f32_16x16x32_bf16 v[60:63], v[86:89], v[102:105], v[60:63]
	v_mfma_f32_16x16x32_bf16 v[56:59], v[94:97], v[102:105], v[56:59]
	v_mfma_f32_16x16x32_bf16 v[52:55], v[86:89], v[110:113], v[52:55]
	v_mfma_f32_16x16x32_bf16 v[48:51], v[94:97], v[110:113], v[48:51]
	v_mfma_f32_16x16x32_bf16 v[44:47], v[86:89], v[118:121], v[44:47]
	v_mfma_f32_16x16x32_bf16 v[40:43], v[94:97], v[118:121], v[40:43]
	v_mfma_f32_16x16x32_bf16 v[36:39], v[86:89], v[126:129], v[36:39]
	v_mfma_f32_16x16x32_bf16 v[32:35], v[94:97], v[126:129], v[32:35]
	s_barrier
	s_setprio 0
	v_lshl_add_u64 v[98:99], v[130:131], 0, s[6:7]
	global_load_lds_dwordx4 v[98:99], off
	v_lshl_add_u64 v[98:99], v[132:133], 0, s[6:7]
	s_mov_b32 m0, s44
	s_nop 0
	global_load_lds_dwordx4 v[98:99], off
	s_barrier
	s_waitcnt lgkmcnt(0)
	s_setprio 1
	s_setprio 0
	s_mov_b32 m0, s34
	v_lshl_add_u64 v[130:131], v[134:135], 0, s[6:7]
	s_barrier
	ds_read_b128 v[98:101], v80 offset:49152
	ds_read_b128 v[102:105], v80 offset:50176
	ds_read_b128 v[106:109], v80 offset:51200
	ds_read_b128 v[110:113], v80 offset:52224
	ds_read_b128 v[114:117], v80 offset:53248
	ds_read_b128 v[118:121], v80 offset:54272
	ds_read_b128 v[122:125], v80 offset:55296
	ds_read_b128 v[126:129], v80 offset:56320
	global_load_lds_dwordx4 v[130:131], off
	v_lshl_add_u64 v[130:131], v[136:137], 0, s[6:7]
	s_mov_b32 m0, s35
	s_nop 0
	global_load_lds_dwordx4 v[130:131], off
	s_setprio 1
	s_barrier
	s_waitcnt lgkmcnt(0)
	v_mfma_f32_16x16x32_bf16 v[28:31], v[82:85], v[98:101], v[28:31]
	v_mfma_f32_16x16x32_bf16 v[24:27], v[90:93], v[98:101], v[24:27]
	v_mfma_f32_16x16x32_bf16 v[20:23], v[82:85], v[106:109], v[20:23]
	v_mfma_f32_16x16x32_bf16 v[16:19], v[90:93], v[106:109], v[16:19]
	v_mfma_f32_16x16x32_bf16 v[12:15], v[82:85], v[114:117], v[12:15]
	v_mfma_f32_16x16x32_bf16 v[8:11], v[90:93], v[114:117], v[8:11]
	v_mfma_f32_16x16x32_bf16 v[4:7], v[82:85], v[122:125], v[4:7]
	v_mfma_f32_16x16x32_bf16 v[0:3], v[90:93], v[122:125], v[0:3]
	s_add_u32 s16, s20, 0x10080
	v_mfma_f32_16x16x32_bf16 v[28:31], v[86:89], v[102:105], v[28:31]
	s_addc_u32 s17, s21, 0
	v_mfma_f32_16x16x32_bf16 v[24:27], v[94:97], v[102:105], v[24:27]
	s_mov_b32 m0, s36
	v_mfma_f32_16x16x32_bf16 v[20:23], v[86:89], v[110:113], v[20:23]
	v_mfma_f32_16x16x32_bf16 v[16:19], v[94:97], v[110:113], v[16:19]
	v_mfma_f32_16x16x32_bf16 v[12:15], v[86:89], v[118:121], v[12:15]
	v_mfma_f32_16x16x32_bf16 v[8:11], v[94:97], v[118:121], v[8:11]
	v_mfma_f32_16x16x32_bf16 v[4:7], v[86:89], v[126:129], v[4:7]
	v_mfma_f32_16x16x32_bf16 v[0:3], v[94:97], v[126:129], v[0:3]
	s_barrier
	s_setprio 0
	s_nop 0
	global_load_lds_dwordx4 v68, s[16:17]
	s_mov_b32 m0, s37
	s_nop 0
	global_load_lds_dwordx4 v64, s[16:17]
	s_waitcnt vmcnt(6)
	s_barrier
	s_setprio 1
	s_setprio 0
	s_add_u32 s58, s58, 0x100
	s_addc_u32 s59, s59, 0
	s_cmp_ge_i32 s60, s54
	s_mov_b64 s[16:17], s[18:19]
	s_mov_b32 s20, s60
	s_barrier
	s_cbranch_scc0 .LBB0_1298
	s_branch .LBB0_1293

; #define PG8_STAGE(bufoff, gbase, voff) do { _Pragma("unroll") for (int _i = 0; _i < 2; ++_i) \
;         __builtin_amdgcn_global_load_lds((const unsigned*)((const char*)(gbase) + (voff)[_i]), (LAS unsigned*)(lds + (bufoff) + ldsw + _i * 8192), 16, 0, 0); } while (0)
; #define PG8_LDA(dst, b, h) do { _Pragma("unroll") for (int m = 0; m < 4; ++m) _Pragma("unroll") for (int k = 0; k < 2; ++k) dst[m][k] = *(const LAS bf16x8*)(lds + PG8_SA(b, h) + aoff + m * 2048 + k * 1024); } while (0)
; #define PG8_LDB(dst, b, h) do { _Pragma("unroll") for (int n = 0; n < 2; ++n) _Pragma("unroll") for (int k = 0; k < 2; ++k) dst[n][k] = *(const LAS bf16x8*)(lds + PG8_SB(b, h) + boff + n * 2048 + k * 1024); } while (0)
; #define PG8_MMA(ai, bj, At, Bt) do { __builtin_amdgcn_s_setprio(1); _Pragma("unroll") for (int m = 0; m < 4; ++m) _Pragma("unroll") for (int n = 0; n < 2; ++n) _Pragma("unroll") for (int k = 0; k < 2; ++k) \
;         acc[ai][bj][m][n] = __builtin_amdgcn_mfma_f32_16x16x32_bf16(Bt[n][k], At[m][k], acc[ai][bj][m][n], 0, 0, 0); __builtin_amdgcn_s_setprio(0); } while (0)
; #define PG8_WAIT_L(n) asm volatile("s_waitcnt lgkmcnt(" #n ")" ::: "memory")
; #define PG8_BAR __builtin_amdgcn_s_barrier()
; #define PG8_SCHED __builtin_amdgcn_sched_barrier(0)
; template <class Epi, class Sched, bool ATILE = false>
; __device__ __forceinline__ void gemm_phase(LAS unsigned char* lds, const Gemm g, const Sched& S, const Epi& E) {
;     ...
;         for (int t = 0; t < nt; t += 2) {
;             const bool last = (t == nt - 2);
;             const char* a1 = cA + (size_t)(t + 1) * kstepA;
;             const char* a2 = last ? nA : cA + (size_t)(t + 2) * kstepA; const char* b2 = last ? nB : cB + (size_t)(t + 2) * kstep;
;             const char* a3 = a2 + kstepA; const char* b3 = b2 + kstep;
;             PG8_LDB(B0, 0, 0); PG8_SCHED; PG8_LDA(At, 0, 0); PG8_STAGE(PG8_SA(1, 1), a1 + hstepA, voffA);
;             PG8_WAIT_L(8); PG8_BAR; PG8_WAIT_L(0); PG8_MMA(0, 0, At, B0); PG8_BAR; PG8_SCHED;
;             PG8_LDB(B1, 0, 1); PG8_STAGE(PG8_SB(0, 0), b2, voffB);
;             PG8_BAR; PG8_WAIT_L(0); PG8_MMA(0, 1, At, B1); PG8_BAR;
;             PG8_LDA(At, 0, 1); PG8_STAGE(PG8_SA(0, 0), a2, voffA);
;             PG8_BAR; PG8_WAIT_L(0); PG8_MMA(1, 0, At, B0); PG8_BAR; PG8_SCHED;
;             PG8_STAGE(PG8_SB(0, 1), b2 + hstepB, voffB);
.LBB0_1426:
	ds_read_b128 v[162:165], v147
	ds_read_b128 v[166:169], v147 offset:1024
	ds_read_b128 v[170:173], v147 offset:2048
	ds_read_b128 v[174:177], v147 offset:3072
	s_mov_b32 m0, s30
	v_lshl_add_u64 v[144:145], s[12:13], 0, v[140:141]
	ds_read_b128 v[178:181], v148
	ds_read_b128 v[182:185], v148 offset:1024
	ds_read_b128 v[186:189], v148 offset:2048
	ds_read_b128 v[190:193], v148 offset:3072
	ds_read_b128 v[194:197], v148 offset:4096
	ds_read_b128 v[198:201], v148 offset:5120
	ds_read_b128 v[202:205], v148 offset:6144
	ds_read_b128 v[206:209], v148 offset:7168
	global_load_lds_dwordx4 v[144:145], off
	v_lshl_add_u64 v[144:145], s[12:13], 0, v[142:143]
	s_mov_b32 m0, s31
	s_nop 0
	global_load_lds_dwordx4 v[144:145], off
	s_waitcnt lgkmcnt(8)
	s_setprio 1
	s_barrier
	s_waitcnt lgkmcnt(0)
	v_mfma_f32_16x16x32_bf16 v[124:127], v[162:165], v[178:181], v[124:127]
	s_add_i32 s58, s18, 2
	v_mfma_f32_16x16x32_bf16 v[120:123], v[170:173], v[178:181], v[120:123]
	s_add_u32 s16, s12, 0x100
	v_mfma_f32_16x16x32_bf16 v[108:111], v[162:165], v[186:189], v[108:111]
	s_addc_u32 s17, s13, 0
	v_mfma_f32_16x16x32_bf16 v[104:107], v[170:173], v[186:189], v[104:107]
	s_cmp_eq_u32 s55, s18
	v_mfma_f32_16x16x32_bf16 v[92:95], v[162:165], v[194:197], v[92:95]
	s_cselect_b32 s18, s10, s56
	v_mfma_f32_16x16x32_bf16 v[88:91], v[170:173], v[194:197], v[88:91]
	s_cselect_b32 s21, s7, s17
	v_mfma_f32_16x16x32_bf16 v[76:79], v[162:165], v[202:205], v[76:79]
	s_cselect_b32 s20, s6, s16
	v_mfma_f32_16x16x32_bf16 v[72:75], v[170:173], v[202:205], v[72:75]
	s_cselect_b32 s19, s11, s57
	v_mfma_f32_16x16x32_bf16 v[124:127], v[166:169], v[182:185], v[124:127]
	s_mov_b32 m0, s33
	v_mfma_f32_16x16x32_bf16 v[120:123], v[174:177], v[182:185], v[120:123]
	v_mfma_f32_16x16x32_bf16 v[108:111], v[166:169], v[190:193], v[108:111]
	v_mfma_f32_16x16x32_bf16 v[104:107], v[174:177], v[190:193], v[104:107]
	v_mfma_f32_16x16x32_bf16 v[92:95], v[166:169], v[198:201], v[92:95]
	v_mfma_f32_16x16x32_bf16 v[88:91], v[174:177], v[198:201], v[88:91]
	v_mfma_f32_16x16x32_bf16 v[76:79], v[166:169], v[206:209], v[76:79]
	v_mfma_f32_16x16x32_bf16 v[72:75], v[174:177], v[206:209], v[72:75]
	s_barrier
	s_setprio 0
	v_lshl_add_u64 v[144:145], s[18:19], 0, v[132:133]
	ds_read_b128 v[210:213], v149
	ds_read_b128 v[214:217], v149 offset:1024
	ds_read_b128 v[218:221], v149 offset:2048
	ds_read_b128 v[222:225], v149 offset:3072
	global_load_lds_dwordx4 v[144:145], off
	v_lshl_add_u64 v[226:227], s[18:19], 0, v[128:129]
	s_mov_b32 m0, s34
	s_nop 0
	global_load_lds_dwordx4 v[226:227], off
	s_setprio 1
	s_barrier
	s_waitcnt lgkmcnt(0)
	v_mfma_f32_16x16x32_bf16 v[116:119], v[210:213], v[178:181], v[116:119]
	v_mfma_f32_16x16x32_bf16 v[112:115], v[218:221], v[178:181], v[112:115]
	v_mfma_f32_16x16x32_bf16 v[100:103], v[210:213], v[186:189], v[100:103]
	v_mfma_f32_16x16x32_bf16 v[96:99], v[218:221], v[186:189], v[96:99]
	v_mfma_f32_16x16x32_bf16 v[84:87], v[210:213], v[194:197], v[84:87]
	v_mfma_f32_16x16x32_bf16 v[80:83], v[218:221], v[194:197], v[80:83]
	v_mfma_f32_16x16x32_bf16 v[68:71], v[210:213], v[202:205], v[68:71]
	v_mfma_f32_16x16x32_bf16 v[64:67], v[218:221], v[202:205], v[64:67]
	s_mov_b32 m0, s22
	v_mfma_f32_16x16x32_bf16 v[116:119], v[214:217], v[182:185], v[116:119]
	v_mfma_f32_16x16x32_bf16 v[112:115], v[222:225], v[182:185], v[112:115]
	v_mfma_f32_16x16x32_bf16 v[100:103], v[214:217], v[190:193], v[100:103]
	v_mfma_f32_16x16x32_bf16 v[96:99], v[222:225], v[190:193], v[96:99]
	v_mfma_f32_16x16x32_bf16 v[84:87], v[214:217], v[198:201], v[84:87]
	v_mfma_f32_16x16x32_bf16 v[80:83], v[222:225], v[198:201], v[80:83]
	v_mfma_f32_16x16x32_bf16 v[68:71], v[214:217], v[206:209], v[68:71]
	v_mfma_f32_16x16x32_bf16 v[64:67], v[222:225], v[206:209], v[64:67]
	s_barrier
	s_setprio 0
	v_lshl_add_u64 v[228:229], s[20:21], 0, v[134:135]
	ds_read_b128 v[178:181], v148 offset:16384
	ds_read_b128 v[182:185], v148 offset:17408
	ds_read_b128 v[186:189], v148 offset:18432
	ds_read_b128 v[190:193], v148 offset:19456
	ds_read_b128 v[194:197], v148 offset:20480
	ds_read_b128 v[198:201], v148 offset:21504
	ds_read_b128 v[202:205], v148 offset:22528
	ds_read_b128 v[206:209], v148 offset:23552
	global_load_lds_dwordx4 v[228:229], off
	v_lshl_add_u64 v[230:231], s[20:21], 0, v[130:131]
	s_mov_b32 m0, s23
	s_nop 0
	global_load_lds_dwordx4 v[230:231], off
	s_setprio 1
	s_barrier
	s_waitcnt lgkmcnt(0)
	v_mfma_f32_16x16x32_bf16 v[60:63], v[162:165], v[178:181], v[60:63]
	v_mfma_f32_16x16x32_bf16 v[56:59], v[170:173], v[178:181], v[56:59]
	v_mfma_f32_16x16x32_bf16 v[44:47], v[162:165], v[186:189], v[44:47]
	v_mfma_f32_16x16x32_bf16 v[40:43], v[170:173], v[186:189], v[40:43]
	v_mfma_f32_16x16x32_bf16 v[28:31], v[162:165], v[194:197], v[28:31]
	v_mfma_f32_16x16x32_bf16 v[24:27], v[170:173], v[194:197], v[24:27]
	v_mfma_f32_16x16x32_bf16 v[12:15], v[162:165], v[202:205], v[12:15]
	v_mfma_f32_16x16x32_bf16 v[8:11], v[170:173], v[202:205], v[8:11]
	s_add_u32 s12, s18, 0x18000
	v_mfma_f32_16x16x32_bf16 v[60:63], v[166:169], v[182:185], v[60:63]
	s_addc_u32 s13, s19, 0
	v_mfma_f32_16x16x32_bf16 v[56:59], v[174:177], v[182:185], v[56:59]
	s_mov_b32 m0, s35
	v_mfma_f32_16x16x32_bf16 v[44:47], v[166:169], v[190:193], v[44:47]
	v_mfma_f32_16x16x32_bf16 v[40:43], v[174:177], v[190:193], v[40:43]
	v_mfma_f32_16x16x32_bf16 v[28:31], v[166:169], v[198:201], v[28:31]
	v_mfma_f32_16x16x32_bf16 v[24:27], v[174:177], v[198:201], v[24:27]
	v_mfma_f32_16x16x32_bf16 v[12:15], v[166:169], v[206:209], v[12:15]
	v_mfma_f32_16x16x32_bf16 v[8:11], v[174:177], v[206:209], v[8:11]
	s_barrier
; #define PG8_STAGE(bufoff, gbase, voff) do { _Pragma("unroll") for (int _i = 0; _i < 2; ++_i) \
;         __builtin_amdgcn_global_load_lds((const unsigned*)((const char*)(gbase) + (voff)[_i]), (LAS unsigned*)(lds + (bufoff) + ldsw + _i * 8192), 16, 0, 0); } while (0)
; #define PG8_LDA(dst, b, h) do { _Pragma("unroll") for (int m = 0; m < 4; ++m) _Pragma("unroll") for (int k = 0; k < 2; ++k) dst[m][k] = *(const LAS bf16x8*)(lds + PG8_SA(b, h) + aoff + m * 2048 + k * 1024); } while (0)
; #define PG8_LDB(dst, b, h) do { _Pragma("unroll") for (int n = 0; n < 2; ++n) _Pragma("unroll") for (int k = 0; k < 2; ++k) dst[n][k] = *(const LAS bf16x8*)(lds + PG8_SB(b, h) + boff + n * 2048 + k * 1024); } while (0)
; #define PG8_MMA(ai, bj, At, Bt) do { __builtin_amdgcn_s_setprio(1); _Pragma("unroll") for (int m = 0; m < 4; ++m) _Pragma("unroll") for (int n = 0; n < 2; ++n) _Pragma("unroll") for (int k = 0; k < 2; ++k) \
;         acc[ai][bj][m][n] = __builtin_amdgcn_mfma_f32_16x16x32_bf16(Bt[n][k], At[m][k], acc[ai][bj][m][n], 0, 0, 0); __builtin_amdgcn_s_setprio(0); } while (0)
; #define PG8_WAIT_V(n) asm volatile("s_waitcnt vmcnt(" #n ")" ::: "memory")
; #define PG8_WAIT_L(n) asm volatile("s_waitcnt lgkmcnt(" #n ")" ::: "memory")
; #define PG8_BAR __builtin_amdgcn_s_barrier()
; #define PG8_SCHED __builtin_amdgcn_sched_barrier(0)
; template <class Epi, class Sched, bool ATILE = false>
; __device__ __forceinline__ void gemm_phase(LAS unsigned char* lds, const Gemm g, const Sched& S, const Epi& E) {
;     ...
;             PG8_STAGE(PG8_SB(0, 1), b2 + hstepB, voffB);
;             PG8_WAIT_V(6); PG8_BAR; PG8_MMA(1, 1, At, B1); PG8_BAR;
;             PG8_LDB(B0, 1, 0); PG8_SCHED; PG8_LDA(At, 1, 0); PG8_STAGE(PG8_SA(0, 1), a2 + hstepA, voffA);
;             PG8_WAIT_L(8); PG8_BAR; PG8_WAIT_L(0); PG8_MMA(0, 0, At, B0); PG8_BAR; PG8_SCHED;
;             PG8_LDB(B1, 1, 1); PG8_STAGE(PG8_SB(1, 0), b3, voffB);
;             PG8_BAR; PG8_WAIT_L(0); PG8_MMA(0, 1, At, B1); PG8_BAR;
;             PG8_LDA(At, 1, 1); PG8_STAGE(PG8_SA(1, 0), a3, voffA);
	s_setprio 0
	s_nop 0
	global_load_lds_dwordx4 v132, s[12:13]
	s_mov_b32 m0, s36
	s_nop 0
	global_load_lds_dwordx4 v128, s[12:13]
	s_waitcnt vmcnt(6)
	s_setprio 1
	s_barrier
	v_mfma_f32_16x16x32_bf16 v[52:55], v[210:213], v[178:181], v[52:55]
	v_mfma_f32_16x16x32_bf16 v[48:51], v[218:221], v[178:181], v[48:51]
	v_mfma_f32_16x16x32_bf16 v[36:39], v[210:213], v[186:189], v[36:39]
	v_mfma_f32_16x16x32_bf16 v[32:35], v[218:221], v[186:189], v[32:35]
	v_mfma_f32_16x16x32_bf16 v[20:23], v[210:213], v[194:197], v[20:23]
	v_mfma_f32_16x16x32_bf16 v[16:19], v[218:221], v[194:197], v[16:19]
	v_mfma_f32_16x16x32_bf16 v[4:7], v[210:213], v[202:205], v[4:7]
	v_mfma_f32_16x16x32_bf16 v[0:3], v[218:221], v[202:205], v[0:3]
	v_mfma_f32_16x16x32_bf16 v[52:55], v[214:217], v[182:185], v[52:55]
	v_mfma_f32_16x16x32_bf16 v[48:51], v[222:225], v[182:185], v[48:51]
	v_mfma_f32_16x16x32_bf16 v[36:39], v[214:217], v[190:193], v[36:39]
	v_mfma_f32_16x16x32_bf16 v[32:35], v[222:225], v[190:193], v[32:35]
	v_mfma_f32_16x16x32_bf16 v[20:23], v[214:217], v[198:201], v[20:23]
	v_mfma_f32_16x16x32_bf16 v[16:19], v[222:225], v[198:201], v[16:19]
	v_mfma_f32_16x16x32_bf16 v[4:7], v[214:217], v[206:209], v[4:7]
	v_mfma_f32_16x16x32_bf16 v[0:3], v[222:225], v[206:209], v[0:3]
	s_barrier
	s_setprio 0
	ds_read_b128 v[162:165], v150
	ds_read_b128 v[166:169], v150 offset:1024
	ds_read_b128 v[170:173], v150 offset:2048
	ds_read_b128 v[174:177], v150 offset:3072
	s_add_u32 s12, s20, 0x18000
	s_addc_u32 s13, s21, 0
	s_mov_b32 m0, s24
	ds_read_b128 v[178:181], v148 offset:32768
	ds_read_b128 v[182:185], v148 offset:33792
	ds_read_b128 v[186:189], v148 offset:34816
	ds_read_b128 v[190:193], v148 offset:35840
	ds_read_b128 v[194:197], v148 offset:36864
	ds_read_b128 v[198:201], v148 offset:37888
	ds_read_b128 v[202:205], v148 offset:38912
	ds_read_b128 v[206:209], v148 offset:39936
	global_load_lds_dwordx4 v134, s[12:13]
	s_mov_b32 m0, s25
	s_nop 0
	global_load_lds_dwordx4 v130, s[12:13]
	s_waitcnt lgkmcnt(8)
	s_setprio 1
	s_barrier
	s_waitcnt lgkmcnt(0)
	v_mfma_f32_16x16x32_bf16 v[124:127], v[162:165], v[178:181], v[124:127]
	v_mfma_f32_16x16x32_bf16 v[120:123], v[170:173], v[178:181], v[120:123]
	v_mfma_f32_16x16x32_bf16 v[108:111], v[162:165], v[186:189], v[108:111]
	v_mfma_f32_16x16x32_bf16 v[104:107], v[170:173], v[186:189], v[104:107]
	v_mfma_f32_16x16x32_bf16 v[92:95], v[162:165], v[194:197], v[92:95]
	v_mfma_f32_16x16x32_bf16 v[88:91], v[170:173], v[194:197], v[88:91]
	v_mfma_f32_16x16x32_bf16 v[76:79], v[162:165], v[202:205], v[76:79]
	v_mfma_f32_16x16x32_bf16 v[72:75], v[170:173], v[202:205], v[72:75]
	s_mov_b32 m0, s40
	v_mfma_f32_16x16x32_bf16 v[124:127], v[166:169], v[182:185], v[124:127]
	v_mfma_f32_16x16x32_bf16 v[120:123], v[174:177], v[182:185], v[120:123]
	v_mfma_f32_16x16x32_bf16 v[108:111], v[166:169], v[190:193], v[108:111]
	v_mfma_f32_16x16x32_bf16 v[104:107], v[174:177], v[190:193], v[104:107]
	v_mfma_f32_16x16x32_bf16 v[92:95], v[166:169], v[198:201], v[92:95]
	v_mfma_f32_16x16x32_bf16 v[88:91], v[174:177], v[198:201], v[88:91]
	v_mfma_f32_16x16x32_bf16 v[76:79], v[166:169], v[206:209], v[76:79]
	v_mfma_f32_16x16x32_bf16 v[72:75], v[174:177], v[206:209], v[72:75]
	s_barrier
	s_setprio 0
	v_lshl_add_u64 v[144:145], v[144:145], 0, s[0:1]
	ds_read_b128 v[210:213], v157
	ds_read_b128 v[214:217], v157 offset:1024
	ds_read_b128 v[218:221], v157 offset:2048
	ds_read_b128 v[222:225], v157 offset:3072
	global_load_lds_dwordx4 v[144:145], off
	v_lshl_add_u64 v[144:145], v[226:227], 0, s[0:1]
	s_mov_b32 m0, s41
	s_nop 0
	global_load_lds_dwordx4 v[144:145], off
	s_setprio 1
	s_barrier
; #define PG8_STAGE(bufoff, gbase, voff) do { _Pragma("unroll") for (int _i = 0; _i < 2; ++_i) \
;         __builtin_amdgcn_global_load_lds((const unsigned*)((const char*)(gbase) + (voff)[_i]), (LAS unsigned*)(lds + (bufoff) + ldsw + _i * 8192), 16, 0, 0); } while (0)
; #define PG8_LDA(dst, b, h) do { _Pragma("unroll") for (int m = 0; m < 4; ++m) _Pragma("unroll") for (int k = 0; k < 2; ++k) dst[m][k] = *(const LAS bf16x8*)(lds + PG8_SA(b, h) + aoff + m * 2048 + k * 1024); } while (0)
; #define PG8_MMA(ai, bj, At, Bt) do { __builtin_amdgcn_s_setprio(1); _Pragma("unroll") for (int m = 0; m < 4; ++m) _Pragma("unroll") for (int n = 0; n < 2; ++n) _Pragma("unroll") for (int k = 0; k < 2; ++k) \
;         acc[ai][bj][m][n] = __builtin_amdgcn_mfma_f32_16x16x32_bf16(Bt[n][k], At[m][k], acc[ai][bj][m][n], 0, 0, 0); __builtin_amdgcn_s_setprio(0); } while (0)
; #define PG8_WAIT_V(n) asm volatile("s_waitcnt vmcnt(" #n ")" ::: "memory")
; #define PG8_WAIT_L(n) asm volatile("s_waitcnt lgkmcnt(" #n ")" ::: "memory")
; #define PG8_BAR __builtin_amdgcn_s_barrier()
; #define PG8_SCHED __builtin_amdgcn_sched_barrier(0)
; template <class Epi, class Sched, bool ATILE = false>
; __device__ __forceinline__ void gemm_phase(LAS unsigned char* lds, const Gemm g, const Sched& S, const Epi& E) {
;     ...
;             PG8_BAR; PG8_WAIT_L(0); PG8_MMA(0, 1, At, B1); PG8_BAR;
;             PG8_LDA(At, 1, 1); PG8_STAGE(PG8_SA(1, 0), a3, voffA);
;             PG8_BAR; PG8_WAIT_L(0); PG8_MMA(1, 0, At, B0); PG8_BAR; PG8_SCHED;
;             PG8_STAGE(PG8_SB(1, 1), b3 + hstepB, voffB);
;             PG8_WAIT_V(6); PG8_BAR; PG8_MMA(1, 1, At, B1); PG8_BAR;
	s_waitcnt lgkmcnt(0)
	v_mfma_f32_16x16x32_bf16 v[116:119], v[210:213], v[178:181], v[116:119]
	v_mfma_f32_16x16x32_bf16 v[112:115], v[218:221], v[178:181], v[112:115]
	v_mfma_f32_16x16x32_bf16 v[100:103], v[210:213], v[186:189], v[100:103]
	v_mfma_f32_16x16x32_bf16 v[96:99], v[218:221], v[186:189], v[96:99]
	v_mfma_f32_16x16x32_bf16 v[84:87], v[210:213], v[194:197], v[84:87]
	v_mfma_f32_16x16x32_bf16 v[80:83], v[218:221], v[194:197], v[80:83]
	v_mfma_f32_16x16x32_bf16 v[68:71], v[210:213], v[202:205], v[68:71]
	v_mfma_f32_16x16x32_bf16 v[64:67], v[218:221], v[202:205], v[64:67]
	s_mov_b32 m0, s28
	v_mfma_f32_16x16x32_bf16 v[116:119], v[214:217], v[182:185], v[116:119]
	v_mfma_f32_16x16x32_bf16 v[112:115], v[222:225], v[182:185], v[112:115]
	v_mfma_f32_16x16x32_bf16 v[100:103], v[214:217], v[190:193], v[100:103]
	v_mfma_f32_16x16x32_bf16 v[96:99], v[222:225], v[190:193], v[96:99]
	v_mfma_f32_16x16x32_bf16 v[84:87], v[214:217], v[198:201], v[84:87]
	v_mfma_f32_16x16x32_bf16 v[80:83], v[222:225], v[198:201], v[80:83]
	v_mfma_f32_16x16x32_bf16 v[68:71], v[214:217], v[206:209], v[68:71]
	v_mfma_f32_16x16x32_bf16 v[64:67], v[222:225], v[206:209], v[64:67]
	s_barrier
	s_setprio 0
	v_lshl_add_u64 v[144:145], v[228:229], 0, s[0:1]
	ds_read_b128 v[178:181], v148 offset:49152
	ds_read_b128 v[182:185], v148 offset:50176
	ds_read_b128 v[186:189], v148 offset:51200
	ds_read_b128 v[190:193], v148 offset:52224
	ds_read_b128 v[194:197], v148 offset:53248
	ds_read_b128 v[198:201], v148 offset:54272
	ds_read_b128 v[202:205], v148 offset:55296
	ds_read_b128 v[206:209], v148 offset:56320
	global_load_lds_dwordx4 v[144:145], off
	v_lshl_add_u64 v[144:145], v[230:231], 0, s[0:1]
	s_mov_b32 m0, s29
	s_nop 0
	global_load_lds_dwordx4 v[144:145], off
	s_setprio 1
	s_barrier
	s_waitcnt lgkmcnt(0)
	v_mfma_f32_16x16x32_bf16 v[60:63], v[162:165], v[178:181], v[60:63]
	v_mfma_f32_16x16x32_bf16 v[56:59], v[170:173], v[178:181], v[56:59]
	v_mfma_f32_16x16x32_bf16 v[44:47], v[162:165], v[186:189], v[44:47]
	v_mfma_f32_16x16x32_bf16 v[40:43], v[170:173], v[186:189], v[40:43]
	v_mfma_f32_16x16x32_bf16 v[28:31], v[162:165], v[194:197], v[28:31]
	v_mfma_f32_16x16x32_bf16 v[24:27], v[170:173], v[194:197], v[24:27]
	v_mfma_f32_16x16x32_bf16 v[12:15], v[162:165], v[202:205], v[12:15]
	v_mfma_f32_16x16x32_bf16 v[8:11], v[170:173], v[202:205], v[8:11]
	s_add_u32 s12, s18, 0x18080
	v_mfma_f32_16x16x32_bf16 v[60:63], v[166:169], v[182:185], v[60:63]
	s_addc_u32 s13, s19, 0
	v_mfma_f32_16x16x32_bf16 v[56:59], v[174:177], v[182:185], v[56:59]
	s_mov_b32 m0, s42
	v_mfma_f32_16x16x32_bf16 v[44:47], v[166:169], v[190:193], v[44:47]
	v_mfma_f32_16x16x32_bf16 v[40:43], v[174:177], v[190:193], v[40:43]
	v_mfma_f32_16x16x32_bf16 v[28:31], v[166:169], v[198:201], v[28:31]
	v_mfma_f32_16x16x32_bf16 v[24:27], v[174:177], v[198:201], v[24:27]
	v_mfma_f32_16x16x32_bf16 v[12:15], v[166:169], v[206:209], v[12:15]
	v_mfma_f32_16x16x32_bf16 v[8:11], v[174:177], v[206:209], v[8:11]
	s_barrier
	s_setprio 0
	s_nop 0
	global_load_lds_dwordx4 v132, s[12:13]
	s_mov_b32 m0, s43
	s_nop 0
	global_load_lds_dwordx4 v128, s[12:13]
	s_waitcnt vmcnt(6)
	s_setprio 1
	s_barrier
	v_mfma_f32_16x16x32_bf16 v[52:55], v[210:213], v[178:181], v[52:55]
	v_mfma_f32_16x16x32_bf16 v[48:51], v[218:221], v[178:181], v[48:51]
	v_mfma_f32_16x16x32_bf16 v[36:39], v[210:213], v[186:189], v[36:39]
	v_mfma_f32_16x16x32_bf16 v[32:35], v[218:221], v[186:189], v[32:35]
	v_mfma_f32_16x16x32_bf16 v[20:23], v[210:213], v[194:197], v[20:23]
	v_mfma_f32_16x16x32_bf16 v[16:19], v[218:221], v[194:197], v[16:19]
	v_mfma_f32_16x16x32_bf16 v[4:7], v[210:213], v[202:205], v[4:7]
	s_add_u32 s56, s56, 0x100
	v_mfma_f32_16x16x32_bf16 v[0:3], v[218:221], v[202:205], v[0:3]
	s_addc_u32 s57, s57, 0
	v_mfma_f32_16x16x32_bf16 v[52:55], v[214:217], v[182:185], v[52:55]
	s_cmp_ge_i32 s58, s54
	v_mfma_f32_16x16x32_bf16 v[48:51], v[222:225], v[182:185], v[48:51]
	s_mov_b64 s[12:13], s[16:17]
	v_mfma_f32_16x16x32_bf16 v[36:39], v[214:217], v[190:193], v[36:39]
	s_mov_b32 s18, s58
	v_mfma_f32_16x16x32_bf16 v[32:35], v[222:225], v[190:193], v[32:35]
	v_mfma_f32_16x16x32_bf16 v[20:23], v[214:217], v[198:201], v[20:23]
	v_mfma_f32_16x16x32_bf16 v[16:19], v[222:225], v[198:201], v[16:19]
	v_mfma_f32_16x16x32_bf16 v[4:7], v[214:217], v[206:209], v[4:7]
	v_mfma_f32_16x16x32_bf16 v[0:3], v[222:225], v[206:209], v[0:3]
	s_barrier
	s_setprio 0
	s_cbranch_scc0 .LBB0_1426
	s_nop 5
	s_branch .LBB0_1428

; #define PG8_STAGE(bufoff, gbase, voff) do { _Pragma("unroll") for (int _i = 0; _i < 2; ++_i) \
;         __builtin_amdgcn_global_load_lds((const unsigned*)((const char*)(gbase) + (voff)[_i]), (LAS unsigned*)(lds + (bufoff) + ldsw + _i * 8192), 16, 0, 0); } while (0)
; #define PG8_LDA(dst, b, h) do { _Pragma("unroll") for (int m = 0; m < 4; ++m) _Pragma("unroll") for (int k = 0; k < 2; ++k) dst[m][k] = *(const LAS bf16x8*)(lds + PG8_SA(b, h) + aoff + m * 2048 + k * 1024); } while (0)
; #define PG8_LDB(dst, b, h) do { _Pragma("unroll") for (int n = 0; n < 2; ++n) _Pragma("unroll") for (int k = 0; k < 2; ++k) dst[n][k] = *(const LAS bf16x8*)(lds + PG8_SB(b, h) + boff + n * 2048 + k * 1024); } while (0)
; #define PG8_MMA(ai, bj, At, Bt) do { __builtin_amdgcn_s_setprio(1); _Pragma("unroll") for (int m = 0; m < 4; ++m) _Pragma("unroll") for (int n = 0; n < 2; ++n) _Pragma("unroll") for (int k = 0; k < 2; ++k) \
;         acc[ai][bj][m][n] = __builtin_amdgcn_mfma_f32_16x16x32_bf16(Bt[n][k], At[m][k], acc[ai][bj][m][n], 0, 0, 0); __builtin_amdgcn_s_setprio(0); } while (0)
; #define PG8_WAIT_V(n) asm volatile("s_waitcnt vmcnt(" #n ")" ::: "memory")
; #define PG8_WAIT_L(n) asm volatile("s_waitcnt lgkmcnt(" #n ")" ::: "memory")
; template <class Epi, class Sched, bool ATILE = false>
; __device__ __forceinline__ void gemm_phase(LAS unsigned char* lds, const Gemm g, const Sched& S, const Epi& E) {
;     ...
;         for (int t = 0; t < nt; t += 2) {
;             const bool last = (t == nt - 2);
;             const char* a1 = cA + (size_t)(t + 1) * kstepA;
;             const char* a2 = last ? nA : cA + (size_t)(t + 2) * kstepA; const char* b2 = last ? nB : cB + (size_t)(t + 2) * kstep;
;             const char* a3 = a2 + kstepA; const char* b3 = b2 + kstep;
;             PG8_LDB(B0, 0, 0); PG8_SCHED; PG8_LDA(At, 0, 0); PG8_STAGE(PG8_SA(1, 1), a1 + hstepA, voffA);
;             PG8_WAIT_L(8); PG8_BAR; PG8_WAIT_L(0); PG8_MMA(0, 0, At, B0); PG8_BAR; PG8_SCHED;
;             PG8_LDB(B1, 0, 1); PG8_STAGE(PG8_SB(0, 0), b2, voffB);
;             PG8_BAR; PG8_WAIT_L(0); PG8_MMA(0, 1, At, B1); PG8_BAR;
;             PG8_LDA(At, 0, 1); PG8_STAGE(PG8_SA(0, 0), a2, voffA);
;             PG8_BAR; PG8_WAIT_L(0); PG8_MMA(1, 0, At, B0); PG8_BAR; PG8_SCHED;
;             PG8_STAGE(PG8_SB(0, 1), b2 + hstepB, voffB);
;             PG8_WAIT_V(6); PG8_BAR; PG8_MMA(1, 1, At, B1); PG8_BAR;
.LBB0_1517:
	ds_read_b128 v[96:99], v182
	ds_read_b128 v[100:103], v182 offset:1024
	ds_read_b128 v[112:115], v182 offset:2048
	ds_read_b128 v[116:119], v182 offset:3072
	s_add_i32 m0, s23, 0xc000
	ds_read_b128 v[144:147], v183
	ds_read_b128 v[174:177], v183 offset:1024
	ds_read_b128 v[178:181], v183 offset:2048
	ds_read_b128 v[186:189], v183 offset:3072
	ds_read_b128 v[190:193], v183 offset:4096
	ds_read_b128 v[194:197], v183 offset:5120
	ds_read_b128 v[198:201], v183 offset:6144
	ds_read_b128 v[202:205], v183 offset:7168
	global_load_lds_dwordx4 v166, s[24:25]
	s_add_i32 m0, s23, 0xe000
	s_nop 0
	global_load_lds_dwordx4 v168, s[24:25]
	s_waitcnt lgkmcnt(8)
	s_setprio 1
	s_barrier
	s_waitcnt lgkmcnt(0)
	v_mfma_f32_16x16x32_bf16 v[140:143], v[96:99], v[144:147], v[140:143]
	s_add_i32 s54, s26, 2
	v_mfma_f32_16x16x32_bf16 v[136:139], v[112:115], v[144:147], v[136:139]
	s_add_u32 s27, s24, 0xfffc0080
	v_mfma_f32_16x16x32_bf16 v[124:127], v[96:99], v[178:181], v[124:127]
	s_addc_u32 s28, s25, -1
	v_mfma_f32_16x16x32_bf16 v[120:123], v[112:115], v[178:181], v[120:123]
	s_cmp_eq_u32 s45, s26
	v_mfma_f32_16x16x32_bf16 v[92:95], v[96:99], v[190:193], v[92:95]
	s_cselect_b32 s26, s44, s52
	v_mfma_f32_16x16x32_bf16 v[88:91], v[112:115], v[190:193], v[88:91]
	s_cselect_b32 s29, s17, s28
	v_mfma_f32_16x16x32_bf16 v[76:79], v[96:99], v[198:201], v[76:79]
	s_cselect_b32 s28, s42, s27
	v_mfma_f32_16x16x32_bf16 v[72:75], v[112:115], v[198:201], v[72:75]
	s_cselect_b32 s27, s43, s53
	v_mfma_f32_16x16x32_bf16 v[140:143], v[100:103], v[174:177], v[140:143]
	s_add_i32 s55, s39, s5
	v_mfma_f32_16x16x32_bf16 v[136:139], v[116:119], v[174:177], v[136:139]
	s_add_u32 s98, s26, s10
	v_mfma_f32_16x16x32_bf16 v[124:127], v[100:103], v[186:189], v[124:127]
	s_addc_u32 s99, s27, s11
	v_mfma_f32_16x16x32_bf16 v[120:123], v[116:119], v[186:189], v[120:123]
	s_mov_b32 m0, s55
	v_mfma_f32_16x16x32_bf16 v[92:95], v[100:103], v[194:197], v[92:95]
	v_mfma_f32_16x16x32_bf16 v[88:91], v[116:119], v[194:197], v[88:91]
	v_mfma_f32_16x16x32_bf16 v[76:79], v[100:103], v[202:205], v[76:79]
	v_mfma_f32_16x16x32_bf16 v[72:75], v[116:119], v[202:205], v[72:75]
	s_barrier
	s_setprio 0
	ds_read_b128 v[206:209], v184
	ds_read_b128 v[210:213], v184 offset:1024
	ds_read_b128 v[214:217], v184 offset:2048
	ds_read_b128 v[218:221], v184 offset:3072
	global_load_lds_dwordx4 v150, s[26:27]
	s_add_i32 m0, s55, 0x2000
	s_nop 0
	global_load_lds_dwordx4 v164, s[26:27]
	s_setprio 1
	s_barrier
	s_waitcnt lgkmcnt(0)
	v_mfma_f32_16x16x32_bf16 v[132:135], v[206:209], v[144:147], v[132:135]
	v_mfma_f32_16x16x32_bf16 v[128:131], v[214:217], v[144:147], v[128:131]
	v_mfma_f32_16x16x32_bf16 v[108:111], v[206:209], v[178:181], v[108:111]
	v_mfma_f32_16x16x32_bf16 v[104:107], v[214:217], v[178:181], v[104:107]
	v_mfma_f32_16x16x32_bf16 v[84:87], v[206:209], v[190:193], v[84:87]
	v_mfma_f32_16x16x32_bf16 v[80:83], v[214:217], v[190:193], v[80:83]
	v_mfma_f32_16x16x32_bf16 v[68:71], v[206:209], v[198:201], v[68:71]
	v_mfma_f32_16x16x32_bf16 v[64:67], v[214:217], v[198:201], v[64:67]
	s_mov_b32 m0, s23
	v_mfma_f32_16x16x32_bf16 v[132:135], v[210:213], v[174:177], v[132:135]
	s_add_u32 s100, s28, s10
	v_mfma_f32_16x16x32_bf16 v[128:131], v[218:221], v[174:177], v[128:131]
	s_addc_u32 s101, s29, s11
	v_mfma_f32_16x16x32_bf16 v[108:111], v[210:213], v[186:189], v[108:111]
	v_mfma_f32_16x16x32_bf16 v[104:107], v[218:221], v[186:189], v[104:107]
	v_mfma_f32_16x16x32_bf16 v[84:87], v[210:213], v[194:197], v[84:87]
	v_mfma_f32_16x16x32_bf16 v[80:83], v[218:221], v[194:197], v[80:83]
	v_mfma_f32_16x16x32_bf16 v[68:71], v[210:213], v[202:205], v[68:71]
	v_mfma_f32_16x16x32_bf16 v[64:67], v[218:221], v[202:205], v[64:67]
	s_barrier
	s_setprio 0
	ds_read_b128 v[144:147], v183 offset:16384
	ds_read_b128 v[174:177], v183 offset:17408
	ds_read_b128 v[178:181], v183 offset:18432
	ds_read_b128 v[186:189], v183 offset:19456
	ds_read_b128 v[190:193], v183 offset:20480
	ds_read_b128 v[194:197], v183 offset:21504
	ds_read_b128 v[198:201], v183 offset:22528
	ds_read_b128 v[202:205], v183 offset:23552
	global_load_lds_dwordx4 v148, s[28:29]
	s_mov_b32 m0, s30
	s_nop 0
	global_load_lds_dwordx4 v162, s[28:29]
	s_setprio 1
	s_barrier
	s_waitcnt lgkmcnt(0)
	v_mfma_f32_16x16x32_bf16 v[60:63], v[96:99], v[144:147], v[60:63]
	v_mfma_f32_16x16x32_bf16 v[56:59], v[112:115], v[144:147], v[56:59]
	v_mfma_f32_16x16x32_bf16 v[44:47], v[96:99], v[178:181], v[44:47]
	v_mfma_f32_16x16x32_bf16 v[40:43], v[112:115], v[178:181], v[40:43]
	v_mfma_f32_16x16x32_bf16 v[28:31], v[96:99], v[190:193], v[28:31]
	v_mfma_f32_16x16x32_bf16 v[24:27], v[112:115], v[190:193], v[24:27]
	v_mfma_f32_16x16x32_bf16 v[12:15], v[96:99], v[198:201], v[12:15]
	v_mfma_f32_16x16x32_bf16 v[8:11], v[112:115], v[198:201], v[8:11]
	s_add_u32 s56, s26, 0x40000
	v_mfma_f32_16x16x32_bf16 v[60:63], v[100:103], v[174:177], v[60:63]
	s_addc_u32 s57, s27, 0
	v_mfma_f32_16x16x32_bf16 v[56:59], v[116:119], v[174:177], v[56:59]
	s_add_i32 s55, s40, s5
	v_mfma_f32_16x16x32_bf16 v[44:47], v[100:103], v[186:189], v[44:47]
	s_mov_b32 m0, s55
	v_mfma_f32_16x16x32_bf16 v[40:43], v[116:119], v[186:189], v[40:43]
	v_mfma_f32_16x16x32_bf16 v[28:31], v[100:103], v[194:197], v[28:31]
	v_mfma_f32_16x16x32_bf16 v[24:27], v[116:119], v[194:197], v[24:27]
	v_mfma_f32_16x16x32_bf16 v[12:15], v[100:103], v[202:205], v[12:15]
	v_mfma_f32_16x16x32_bf16 v[8:11], v[116:119], v[202:205], v[8:11]
	s_barrier
	s_setprio 0
	s_nop 0
	global_load_lds_dwordx4 v150, s[56:57]
	s_add_i32 m0, s55, 0x2000
	s_nop 0
	global_load_lds_dwordx4 v164, s[56:57]
	s_waitcnt vmcnt(6)
	s_setprio 1
	s_barrier
; #define PG8_STAGE(bufoff, gbase, voff) do { _Pragma("unroll") for (int _i = 0; _i < 2; ++_i) \
;         __builtin_amdgcn_global_load_lds((const unsigned*)((const char*)(gbase) + (voff)[_i]), (LAS unsigned*)(lds + (bufoff) + ldsw + _i * 8192), 16, 0, 0); } while (0)
; #define PG8_LDA(dst, b, h) do { _Pragma("unroll") for (int m = 0; m < 4; ++m) _Pragma("unroll") for (int k = 0; k < 2; ++k) dst[m][k] = *(const LAS bf16x8*)(lds + PG8_SA(b, h) + aoff + m * 2048 + k * 1024); } while (0)
; #define PG8_LDB(dst, b, h) do { _Pragma("unroll") for (int n = 0; n < 2; ++n) _Pragma("unroll") for (int k = 0; k < 2; ++k) dst[n][k] = *(const LAS bf16x8*)(lds + PG8_SB(b, h) + boff + n * 2048 + k * 1024); } while (0)
; #define PG8_MMA(ai, bj, At, Bt) do { __builtin_amdgcn_s_setprio(1); _Pragma("unroll") for (int m = 0; m < 4; ++m) _Pragma("unroll") for (int n = 0; n < 2; ++n) _Pragma("unroll") for (int k = 0; k < 2; ++k) \
;         acc[ai][bj][m][n] = __builtin_amdgcn_mfma_f32_16x16x32_bf16(Bt[n][k], At[m][k], acc[ai][bj][m][n], 0, 0, 0); __builtin_amdgcn_s_setprio(0); } while (0)
; #define PG8_WAIT_V(n) asm volatile("s_waitcnt vmcnt(" #n ")" ::: "memory")
; #define PG8_WAIT_L(n) asm volatile("s_waitcnt lgkmcnt(" #n ")" ::: "memory")
; #define PG8_BAR __builtin_amdgcn_s_barrier()
; #define PG8_SCHED __builtin_amdgcn_sched_barrier(0)
; template <class Epi, class Sched, bool ATILE = false>
; __device__ __forceinline__ void gemm_phase(LAS unsigned char* lds, const Gemm g, const Sched& S, const Epi& E) {
;     ...
;             PG8_WAIT_V(6); PG8_BAR; PG8_MMA(1, 1, At, B1); PG8_BAR;
;             PG8_LDB(B0, 1, 0); PG8_SCHED; PG8_LDA(At, 1, 0); PG8_STAGE(PG8_SA(0, 1), a2 + hstepA, voffA);
;             PG8_WAIT_L(8); PG8_BAR; PG8_WAIT_L(0); PG8_MMA(0, 0, At, B0); PG8_BAR; PG8_SCHED;
;             PG8_LDB(B1, 1, 1); PG8_STAGE(PG8_SB(1, 0), b3, voffB);
;             PG8_BAR; PG8_WAIT_L(0); PG8_MMA(0, 1, At, B1); PG8_BAR;
;             PG8_LDA(At, 1, 1); PG8_STAGE(PG8_SA(1, 0), a3, voffA);
;             PG8_BAR; PG8_WAIT_L(0); PG8_MMA(1, 0, At, B0); PG8_BAR; PG8_SCHED;
	v_mfma_f32_16x16x32_bf16 v[52:55], v[206:209], v[144:147], v[52:55]
	v_mfma_f32_16x16x32_bf16 v[48:51], v[214:217], v[144:147], v[48:51]
	v_mfma_f32_16x16x32_bf16 v[36:39], v[206:209], v[178:181], v[36:39]
	v_mfma_f32_16x16x32_bf16 v[32:35], v[214:217], v[178:181], v[32:35]
	v_mfma_f32_16x16x32_bf16 v[20:23], v[206:209], v[190:193], v[20:23]
	v_mfma_f32_16x16x32_bf16 v[16:19], v[214:217], v[190:193], v[16:19]
	v_mfma_f32_16x16x32_bf16 v[4:7], v[206:209], v[198:201], v[4:7]
	v_mfma_f32_16x16x32_bf16 v[0:3], v[214:217], v[198:201], v[0:3]
	s_add_i32 s55, 0, 0x18000
	v_mfma_f32_16x16x32_bf16 v[52:55], v[210:213], v[174:177], v[52:55]
	v_add_u32_e32 v116, s55, v159
	v_mfma_f32_16x16x32_bf16 v[48:51], v[218:221], v[174:177], v[48:51]
	v_mfma_f32_16x16x32_bf16 v[36:39], v[210:213], v[186:189], v[36:39]
	v_mfma_f32_16x16x32_bf16 v[32:35], v[218:221], v[186:189], v[32:35]
	v_mfma_f32_16x16x32_bf16 v[20:23], v[210:213], v[194:197], v[20:23]
	v_mfma_f32_16x16x32_bf16 v[16:19], v[218:221], v[194:197], v[16:19]
	v_mfma_f32_16x16x32_bf16 v[4:7], v[210:213], v[202:205], v[4:7]
	v_mfma_f32_16x16x32_bf16 v[0:3], v[218:221], v[202:205], v[0:3]
	s_barrier
	s_setprio 0
	ds_read_b128 v[96:99], v116
	ds_read_b128 v[100:103], v116 offset:1024
	ds_read_b128 v[112:115], v116 offset:2048
	ds_read_b128 v[116:119], v116 offset:3072
	s_add_u32 s28, s28, 0x40000
	s_addc_u32 s29, s29, 0
	s_mov_b32 m0, s31
	ds_read_b128 v[144:147], v183 offset:32768
	ds_read_b128 v[174:177], v183 offset:33792
	ds_read_b128 v[178:181], v183 offset:34816
	ds_read_b128 v[186:189], v183 offset:35840
	ds_read_b128 v[190:193], v183 offset:36864
	ds_read_b128 v[194:197], v183 offset:37888
	ds_read_b128 v[198:201], v183 offset:38912
	ds_read_b128 v[202:205], v183 offset:39936
	global_load_lds_dwordx4 v148, s[28:29]
	s_mov_b32 m0, s33
	s_nop 0
	global_load_lds_dwordx4 v162, s[28:29]
	s_waitcnt lgkmcnt(8)
	s_setprio 1
	s_barrier
	s_waitcnt lgkmcnt(0)
	v_mfma_f32_16x16x32_bf16 v[140:143], v[96:99], v[144:147], v[140:143]
	v_mfma_f32_16x16x32_bf16 v[136:139], v[112:115], v[144:147], v[136:139]
	v_mfma_f32_16x16x32_bf16 v[124:127], v[96:99], v[178:181], v[124:127]
	v_mfma_f32_16x16x32_bf16 v[120:123], v[112:115], v[178:181], v[120:123]
	v_mfma_f32_16x16x32_bf16 v[92:95], v[96:99], v[190:193], v[92:95]
	v_mfma_f32_16x16x32_bf16 v[88:91], v[112:115], v[190:193], v[88:91]
	v_mfma_f32_16x16x32_bf16 v[76:79], v[96:99], v[198:201], v[76:79]
	v_mfma_f32_16x16x32_bf16 v[72:75], v[112:115], v[198:201], v[72:75]
	s_add_i32 s28, 0, 0x1c000
	v_mfma_f32_16x16x32_bf16 v[140:143], v[100:103], v[174:177], v[140:143]
	s_add_i32 s29, s55, s5
	v_mfma_f32_16x16x32_bf16 v[136:139], v[116:119], v[174:177], v[136:139]
	v_add_u32_e32 v185, s28, v159
	v_mfma_f32_16x16x32_bf16 v[124:127], v[100:103], v[186:189], v[124:127]
	s_mov_b32 m0, s29
	v_mfma_f32_16x16x32_bf16 v[120:123], v[116:119], v[186:189], v[120:123]
	v_mfma_f32_16x16x32_bf16 v[92:95], v[100:103], v[194:197], v[92:95]
	v_mfma_f32_16x16x32_bf16 v[88:91], v[116:119], v[194:197], v[88:91]
	v_mfma_f32_16x16x32_bf16 v[76:79], v[100:103], v[202:205], v[76:79]
	v_mfma_f32_16x16x32_bf16 v[72:75], v[116:119], v[202:205], v[72:75]
	s_barrier
	s_setprio 0
	ds_read_b128 v[206:209], v185
	ds_read_b128 v[210:213], v185 offset:1024
	ds_read_b128 v[214:217], v185 offset:2048
	ds_read_b128 v[218:221], v185 offset:3072
	global_load_lds_dwordx4 v150, s[98:99]
	s_add_i32 m0, s29, 0x2000
	s_nop 0
	global_load_lds_dwordx4 v164, s[98:99]
	s_setprio 1
	s_barrier
; #define PG8_STAGE(bufoff, gbase, voff) do { _Pragma("unroll") for (int _i = 0; _i < 2; ++_i) \
;         __builtin_amdgcn_global_load_lds((const unsigned*)((const char*)(gbase) + (voff)[_i]), (LAS unsigned*)(lds + (bufoff) + ldsw + _i * 8192), 16, 0, 0); } while (0)
; #define PG8_LDA(dst, b, h) do { _Pragma("unroll") for (int m = 0; m < 4; ++m) _Pragma("unroll") for (int k = 0; k < 2; ++k) dst[m][k] = *(const LAS bf16x8*)(lds + PG8_SA(b, h) + aoff + m * 2048 + k * 1024); } while (0)
; #define PG8_MMA(ai, bj, At, Bt) do { __builtin_amdgcn_s_setprio(1); _Pragma("unroll") for (int m = 0; m < 4; ++m) _Pragma("unroll") for (int n = 0; n < 2; ++n) _Pragma("unroll") for (int k = 0; k < 2; ++k) \
;         acc[ai][bj][m][n] = __builtin_amdgcn_mfma_f32_16x16x32_bf16(Bt[n][k], At[m][k], acc[ai][bj][m][n], 0, 0, 0); __builtin_amdgcn_s_setprio(0); } while (0)
; #define PG8_WAIT_V(n) asm volatile("s_waitcnt vmcnt(" #n ")" ::: "memory")
; #define PG8_WAIT_L(n) asm volatile("s_waitcnt lgkmcnt(" #n ")" ::: "memory")
; #define PG8_BAR __builtin_amdgcn_s_barrier()
; #define PG8_SCHED __builtin_amdgcn_sched_barrier(0)
; template <class Epi, class Sched, bool ATILE = false>
; __device__ __forceinline__ void gemm_phase(LAS unsigned char* lds, const Gemm g, const Sched& S, const Epi& E) {
;     ...
;             PG8_BAR; PG8_WAIT_L(0); PG8_MMA(0, 1, At, B1); PG8_BAR;
;             PG8_LDA(At, 1, 1); PG8_STAGE(PG8_SA(1, 0), a3, voffA);
;             PG8_BAR; PG8_WAIT_L(0); PG8_MMA(1, 0, At, B0); PG8_BAR; PG8_SCHED;
;             PG8_STAGE(PG8_SB(1, 1), b3 + hstepB, voffB);
;             PG8_WAIT_V(6); PG8_BAR; PG8_MMA(1, 1, At, B1); PG8_BAR;
	s_waitcnt lgkmcnt(0)
	v_mfma_f32_16x16x32_bf16 v[132:135], v[206:209], v[144:147], v[132:135]
	v_mfma_f32_16x16x32_bf16 v[128:131], v[214:217], v[144:147], v[128:131]
	v_mfma_f32_16x16x32_bf16 v[108:111], v[206:209], v[178:181], v[108:111]
	v_mfma_f32_16x16x32_bf16 v[104:107], v[214:217], v[178:181], v[104:107]
	v_mfma_f32_16x16x32_bf16 v[84:87], v[206:209], v[190:193], v[84:87]
	v_mfma_f32_16x16x32_bf16 v[80:83], v[214:217], v[190:193], v[80:83]
	v_mfma_f32_16x16x32_bf16 v[68:71], v[206:209], v[198:201], v[68:71]
	v_mfma_f32_16x16x32_bf16 v[64:67], v[214:217], v[198:201], v[64:67]
	s_mov_b32 m0, s35
	v_mfma_f32_16x16x32_bf16 v[132:135], v[210:213], v[174:177], v[132:135]
	v_mfma_f32_16x16x32_bf16 v[128:131], v[218:221], v[174:177], v[128:131]
	v_mfma_f32_16x16x32_bf16 v[108:111], v[210:213], v[186:189], v[108:111]
	v_mfma_f32_16x16x32_bf16 v[104:107], v[218:221], v[186:189], v[104:107]
	v_mfma_f32_16x16x32_bf16 v[84:87], v[210:213], v[194:197], v[84:87]
	v_mfma_f32_16x16x32_bf16 v[80:83], v[218:221], v[194:197], v[80:83]
	v_mfma_f32_16x16x32_bf16 v[68:71], v[210:213], v[202:205], v[68:71]
	v_mfma_f32_16x16x32_bf16 v[64:67], v[218:221], v[202:205], v[64:67]
	s_barrier
	s_setprio 0
	ds_read_b128 v[144:147], v183 offset:49152
	ds_read_b128 v[174:177], v183 offset:50176
	ds_read_b128 v[178:181], v183 offset:51200
	ds_read_b128 v[186:189], v183 offset:52224
	ds_read_b128 v[190:193], v183 offset:53248
	ds_read_b128 v[194:197], v183 offset:54272
	ds_read_b128 v[198:201], v183 offset:55296
	ds_read_b128 v[202:205], v183 offset:56320
	global_load_lds_dwordx4 v148, s[100:101]
	s_mov_b32 m0, s36
	s_nop 0
	global_load_lds_dwordx4 v162, s[100:101]
	s_setprio 1
	s_barrier
	s_waitcnt lgkmcnt(0)
	v_mfma_f32_16x16x32_bf16 v[60:63], v[96:99], v[144:147], v[60:63]
	v_mfma_f32_16x16x32_bf16 v[56:59], v[112:115], v[144:147], v[56:59]
	v_mfma_f32_16x16x32_bf16 v[44:47], v[96:99], v[178:181], v[44:47]
	v_mfma_f32_16x16x32_bf16 v[40:43], v[112:115], v[178:181], v[40:43]
	v_mfma_f32_16x16x32_bf16 v[28:31], v[96:99], v[190:193], v[28:31]
	v_mfma_f32_16x16x32_bf16 v[24:27], v[112:115], v[190:193], v[24:27]
	v_mfma_f32_16x16x32_bf16 v[12:15], v[96:99], v[198:201], v[12:15]
	v_mfma_f32_16x16x32_bf16 v[8:11], v[112:115], v[198:201], v[8:11]
	s_add_u32 s26, s26, 0x40080
	v_mfma_f32_16x16x32_bf16 v[60:63], v[100:103], v[174:177], v[60:63]
	s_addc_u32 s27, s27, 0
	v_mfma_f32_16x16x32_bf16 v[56:59], v[116:119], v[174:177], v[56:59]
	s_add_i32 s28, s28, s5
	v_mfma_f32_16x16x32_bf16 v[44:47], v[100:103], v[186:189], v[44:47]
	s_mov_b32 m0, s28
	v_mfma_f32_16x16x32_bf16 v[40:43], v[116:119], v[186:189], v[40:43]
	v_mfma_f32_16x16x32_bf16 v[28:31], v[100:103], v[194:197], v[28:31]
	v_mfma_f32_16x16x32_bf16 v[24:27], v[116:119], v[194:197], v[24:27]
	v_mfma_f32_16x16x32_bf16 v[12:15], v[100:103], v[202:205], v[12:15]
	v_mfma_f32_16x16x32_bf16 v[8:11], v[116:119], v[202:205], v[8:11]
	s_barrier
	s_setprio 0
	s_nop 0
	global_load_lds_dwordx4 v150, s[26:27]
	s_add_i32 m0, s28, 0x2000
	s_nop 0
	global_load_lds_dwordx4 v164, s[26:27]
	s_waitcnt vmcnt(6)
	s_setprio 1
	s_barrier
	v_mfma_f32_16x16x32_bf16 v[52:55], v[206:209], v[144:147], v[52:55]
	v_mfma_f32_16x16x32_bf16 v[48:51], v[214:217], v[144:147], v[48:51]
	v_mfma_f32_16x16x32_bf16 v[36:39], v[206:209], v[178:181], v[36:39]
	v_mfma_f32_16x16x32_bf16 v[32:35], v[214:217], v[178:181], v[32:35]
	v_mfma_f32_16x16x32_bf16 v[20:23], v[206:209], v[190:193], v[20:23]
	v_mfma_f32_16x16x32_bf16 v[16:19], v[214:217], v[190:193], v[16:19]
	v_mfma_f32_16x16x32_bf16 v[4:7], v[206:209], v[198:201], v[4:7]
	s_add_u32 s24, s24, 0x100
	v_mfma_f32_16x16x32_bf16 v[0:3], v[214:217], v[198:201], v[0:3]
	s_addc_u32 s25, s25, 0
	v_mfma_f32_16x16x32_bf16 v[52:55], v[210:213], v[174:177], v[52:55]
	s_add_u32 s52, s52, 0x100
	v_mfma_f32_16x16x32_bf16 v[48:51], v[218:221], v[174:177], v[48:51]
	s_addc_u32 s53, s53, 0
	v_mfma_f32_16x16x32_bf16 v[36:39], v[210:213], v[186:189], v[36:39]
	s_cmp_ge_i32 s54, s13
	v_mfma_f32_16x16x32_bf16 v[32:35], v[218:221], v[186:189], v[32:35]
	s_mov_b32 s26, s54
	v_mfma_f32_16x16x32_bf16 v[20:23], v[210:213], v[194:197], v[20:23]
	v_mfma_f32_16x16x32_bf16 v[16:19], v[218:221], v[194:197], v[16:19]
	v_mfma_f32_16x16x32_bf16 v[4:7], v[210:213], v[202:205], v[4:7]
	v_mfma_f32_16x16x32_bf16 v[0:3], v[218:221], v[202:205], v[0:3]
	s_barrier
	s_setprio 0
	s_cbranch_scc0 .LBB0_1517
	s_nop 5
	s_branch .LBB0_1508

;     __device__ bool next(int i, Unit& u) const { const int L = i * G + c; if (L >= 64 * 9) return false; u.pm = L; u.pn = L / 9; u.kt0 = 0; u.nt = ntf; u.ks = 0; return true; }
; #define PG8_STAGE(bufoff, gbase, voff) do { _Pragma("unroll") for (int _i = 0; _i < 2; ++_i) \
;         __builtin_amdgcn_global_load_lds((const unsigned*)((const char*)(gbase) + (voff)[_i]), (LAS unsigned*)(lds + (bufoff) + ldsw + _i * 8192), 16, 0, 0); } while (0)
; #define PG8_LDA(dst, b, h) do { _Pragma("unroll") for (int m = 0; m < 4; ++m) _Pragma("unroll") for (int k = 0; k < 2; ++k) dst[m][k] = *(const LAS bf16x8*)(lds + PG8_SA(b, h) + aoff + m * 2048 + k * 1024); } while (0)
; #define PG8_LDB(dst, b, h) do { _Pragma("unroll") for (int n = 0; n < 2; ++n) _Pragma("unroll") for (int k = 0; k < 2; ++k) dst[n][k] = *(const LAS bf16x8*)(lds + PG8_SB(b, h) + boff + n * 2048 + k * 1024); } while (0)
; template <class Epi, class Sched, bool ATILE = false>
; __device__ __forceinline__ void gemm_phase(LAS unsigned char* lds, const Gemm g, const Sched& S, const Epi& E) {
;     ...
;         const bool has_next = S.next(ui + 1, nxt);
;         const char* nA = has_next ? (const char*)g.A + (size_t)nxt.pm * tstepA + (size_t)nxt.kt0 * kstepA : cA; const char* nB = has_next ? (const char*)g.Bt + (size_t)nxt.pn * tstepB + (size_t)nxt.kt0 * kstep : cB;
;         int nt = cur.nt; asm volatile("" : "+s"(nt));
;         for (int t = 0; t < nt; t += 2) {
;             const bool last = (t == nt - 2);
;             const char* a1 = cA + (size_t)(t + 1) * kstepA;
;             const char* a2 = last ? nA : cA + (size_t)(t + 2) * kstepA; const char* b2 = last ? nB : cB + (size_t)(t + 2) * kstep;
;             const char* a3 = a2 + kstepA; const char* b3 = b2 + kstep;
;             PG8_LDB(B0, 0, 0); PG8_SCHED; PG8_LDA(At, 0, 0); PG8_STAGE(PG8_SA(1, 1), a1 + hstepA, voffA);
;             PG8_WAIT_L(8); PG8_BAR; PG8_WAIT_L(0); PG8_MMA(0, 0, At, B0); PG8_BAR; PG8_SCHED;
;             PG8_LDB(B1, 0, 1); PG8_STAGE(PG8_SB(0, 0), b2, voffB);
;             PG8_BAR; PG8_WAIT_L(0); PG8_MMA(0, 1, At, B1); PG8_BAR;
;             PG8_LDA(At, 0, 1); PG8_STAGE(PG8_SA(0, 0), a2, voffA);
;             PG8_BAR; PG8_WAIT_L(0); PG8_MMA(1, 0, At, B0); PG8_BAR; PG8_SCHED;
;             PG8_STAGE(PG8_SB(0, 1), b2 + hstepB, voffB);
;             PG8_WAIT_V(6); PG8_BAR; PG8_MMA(1, 1, At, B1); PG8_BAR;
.LBB0_1658:
	s_waitcnt lgkmcnt(0)
	ds_read_b128 v[128:131], v169
	ds_read_b128 v[132:135], v169 offset:1024
	ds_read_b128 v[136:139], v169 offset:2048
	ds_read_b128 v[140:143], v169 offset:3072
	s_add_i32 m0, s5, 0xc000
	ds_read_b128 v[144:147], v210
	ds_read_b128 v[148:151], v210 offset:1024
	ds_read_b128 v[192:195], v210 offset:2048
	ds_read_b128 v[196:199], v210 offset:3072
	ds_read_b128 v[200:203], v210 offset:4096
	ds_read_b128 v[204:207], v210 offset:5120
	ds_read_b128 v[214:217], v210 offset:6144
	ds_read_b128 v[218:221], v210 offset:7168
	global_load_lds_dwordx4 v186, s[30:31]
	s_add_i32 m0, s5, 0xe000
	s_nop 0
	global_load_lds_dwordx4 v188, s[30:31]
	s_waitcnt lgkmcnt(8)
	s_setprio 1
	s_barrier
	s_waitcnt lgkmcnt(0)
	v_mfma_f32_16x16x32_bf16 v[120:123], v[128:131], v[144:147], v[120:123]
	s_add_i32 s29, s27, 2
	v_mfma_f32_16x16x32_bf16 v[116:119], v[136:139], v[144:147], v[116:119]
	s_add_u32 s34, s30, 0x4000
	v_mfma_f32_16x16x32_bf16 v[108:111], v[128:131], v[192:195], v[108:111]
	s_addc_u32 s35, s31, 0
	v_mfma_f32_16x16x32_bf16 v[100:103], v[136:139], v[192:195], v[100:103]
	s_cmp_eq_u32 s11, s27
	v_mfma_f32_16x16x32_bf16 v[92:95], v[128:131], v[200:203], v[92:95]
	s_cselect_b32 s38, s22, s34
	v_mfma_f32_16x16x32_bf16 v[84:87], v[136:139], v[200:203], v[84:87]
	s_cselect_b32 s39, s23, s35
	v_mfma_f32_16x16x32_bf16 v[76:79], v[128:131], v[214:217], v[76:79]
	s_cselect_b32 s34, s24, s13
	v_mfma_f32_16x16x32_bf16 v[68:71], v[136:139], v[214:217], v[68:71]
	s_cselect_b32 s35, s25, s17
	v_mfma_f32_16x16x32_bf16 v[120:123], v[132:135], v[148:151], v[120:123]
	s_add_u32 s36, s38, 0x8000
	v_mfma_f32_16x16x32_bf16 v[116:119], v[140:143], v[148:151], v[116:119]
	s_addc_u32 s37, s39, 0
	v_mfma_f32_16x16x32_bf16 v[108:111], v[132:135], v[196:199], v[108:111]
	s_add_i32 s27, s52, s4
	v_mfma_f32_16x16x32_bf16 v[100:103], v[140:143], v[196:199], v[100:103]
	s_add_u32 s98, s34, s8
	v_mfma_f32_16x16x32_bf16 v[92:95], v[132:135], v[204:207], v[92:95]
	s_addc_u32 s99, s35, s9
	v_mfma_f32_16x16x32_bf16 v[84:87], v[140:143], v[204:207], v[84:87]
	s_mov_b32 m0, s27
	v_mfma_f32_16x16x32_bf16 v[76:79], v[132:135], v[218:221], v[76:79]
	v_mfma_f32_16x16x32_bf16 v[68:71], v[140:143], v[218:221], v[68:71]
	s_barrier
	s_setprio 0
	ds_read_b128 v[222:225], v211
	ds_read_b128 v[226:229], v211 offset:1024
	ds_read_b128 v[230:233], v211 offset:2048
	ds_read_b128 v[234:237], v211 offset:3072
	global_load_lds_dwordx4 v162, s[34:35]
	s_add_i32 m0, s27, 0x2000
	s_nop 0
	global_load_lds_dwordx4 v166, s[34:35]
	s_setprio 1
	s_barrier
	s_waitcnt lgkmcnt(0)
	v_mfma_f32_16x16x32_bf16 v[124:127], v[222:225], v[144:147], v[124:127]
	v_mfma_f32_16x16x32_bf16 v[112:115], v[230:233], v[144:147], v[112:115]
	v_mfma_f32_16x16x32_bf16 v[104:107], v[222:225], v[192:195], v[104:107]
	v_mfma_f32_16x16x32_bf16 v[96:99], v[230:233], v[192:195], v[96:99]
	v_mfma_f32_16x16x32_bf16 v[88:91], v[222:225], v[200:203], v[88:91]
	v_mfma_f32_16x16x32_bf16 v[80:83], v[230:233], v[200:203], v[80:83]
	v_mfma_f32_16x16x32_bf16 v[72:75], v[222:225], v[214:217], v[72:75]
	v_mfma_f32_16x16x32_bf16 v[64:67], v[230:233], v[214:217], v[64:67]
	s_mov_b32 m0, s5
	v_mfma_f32_16x16x32_bf16 v[124:127], v[226:229], v[148:151], v[124:127]
	v_mfma_f32_16x16x32_bf16 v[112:115], v[234:237], v[148:151], v[112:115]
	v_mfma_f32_16x16x32_bf16 v[104:107], v[226:229], v[196:199], v[104:107]
	v_mfma_f32_16x16x32_bf16 v[96:99], v[234:237], v[196:199], v[96:99]
	v_mfma_f32_16x16x32_bf16 v[88:91], v[226:229], v[204:207], v[88:91]
	v_mfma_f32_16x16x32_bf16 v[80:83], v[234:237], v[204:207], v[80:83]
	v_mfma_f32_16x16x32_bf16 v[72:75], v[226:229], v[218:221], v[72:75]
	v_mfma_f32_16x16x32_bf16 v[64:67], v[234:237], v[218:221], v[64:67]
	s_barrier
	s_setprio 0
	ds_read_b128 v[144:147], v210 offset:16384
	ds_read_b128 v[148:151], v210 offset:17408
	ds_read_b128 v[192:195], v210 offset:18432
	ds_read_b128 v[196:199], v210 offset:19456
	ds_read_b128 v[200:203], v210 offset:20480
	ds_read_b128 v[204:207], v210 offset:21504
	ds_read_b128 v[214:217], v210 offset:22528
	ds_read_b128 v[218:221], v210 offset:23552
	global_load_lds_dwordx4 v160, s[38:39]
	s_mov_b32 m0, s33
	s_nop 0
	global_load_lds_dwordx4 v164, s[38:39]
	s_setprio 1
	s_barrier
	s_waitcnt lgkmcnt(0)
	v_mfma_f32_16x16x32_bf16 v[60:63], v[128:131], v[144:147], v[60:63]
	v_mfma_f32_16x16x32_bf16 v[56:59], v[136:139], v[144:147], v[56:59]
	v_mfma_f32_16x16x32_bf16 v[44:47], v[128:131], v[192:195], v[44:47]
	v_mfma_f32_16x16x32_bf16 v[40:43], v[136:139], v[192:195], v[40:43]
	v_mfma_f32_16x16x32_bf16 v[28:31], v[128:131], v[200:203], v[28:31]
	v_mfma_f32_16x16x32_bf16 v[24:27], v[136:139], v[200:203], v[24:27]
	v_mfma_f32_16x16x32_bf16 v[12:15], v[128:131], v[214:217], v[12:15]
	v_mfma_f32_16x16x32_bf16 v[8:11], v[136:139], v[214:217], v[8:11]
	s_add_u32 s56, s34, 0x80000
	v_mfma_f32_16x16x32_bf16 v[60:63], v[132:135], v[148:151], v[60:63]
	s_addc_u32 s57, s35, 0
	v_mfma_f32_16x16x32_bf16 v[56:59], v[140:143], v[148:151], v[56:59]
	s_add_i32 s27, s53, s4
	v_mfma_f32_16x16x32_bf16 v[44:47], v[132:135], v[196:199], v[44:47]
	s_mov_b32 m0, s27
	v_mfma_f32_16x16x32_bf16 v[40:43], v[140:143], v[196:199], v[40:43]
	v_mfma_f32_16x16x32_bf16 v[28:31], v[132:135], v[204:207], v[28:31]
	v_mfma_f32_16x16x32_bf16 v[24:27], v[140:143], v[204:207], v[24:27]
	v_mfma_f32_16x16x32_bf16 v[12:15], v[132:135], v[218:221], v[12:15]
	v_mfma_f32_16x16x32_bf16 v[8:11], v[140:143], v[218:221], v[8:11]
	s_barrier
	s_setprio 0
	s_nop 0
	global_load_lds_dwordx4 v162, s[56:57]
	s_add_i32 m0, s27, 0x2000
	s_nop 0
	global_load_lds_dwordx4 v166, s[56:57]
	s_waitcnt vmcnt(6)
	s_setprio 1
	s_barrier
; #define PG8_STAGE(bufoff, gbase, voff) do { _Pragma("unroll") for (int _i = 0; _i < 2; ++_i) \
;         __builtin_amdgcn_global_load_lds((const unsigned*)((const char*)(gbase) + (voff)[_i]), (LAS unsigned*)(lds + (bufoff) + ldsw + _i * 8192), 16, 0, 0); } while (0)
; #define PG8_LDA(dst, b, h) do { _Pragma("unroll") for (int m = 0; m < 4; ++m) _Pragma("unroll") for (int k = 0; k < 2; ++k) dst[m][k] = *(const LAS bf16x8*)(lds + PG8_SA(b, h) + aoff + m * 2048 + k * 1024); } while (0)
; #define PG8_LDB(dst, b, h) do { _Pragma("unroll") for (int n = 0; n < 2; ++n) _Pragma("unroll") for (int k = 0; k < 2; ++k) dst[n][k] = *(const LAS bf16x8*)(lds + PG8_SB(b, h) + boff + n * 2048 + k * 1024); } while (0)
; #define PG8_MMA(ai, bj, At, Bt) do { __builtin_amdgcn_s_setprio(1); _Pragma("unroll") for (int m = 0; m < 4; ++m) _Pragma("unroll") for (int n = 0; n < 2; ++n) _Pragma("unroll") for (int k = 0; k < 2; ++k) \
;         acc[ai][bj][m][n] = __builtin_amdgcn_mfma_f32_16x16x32_bf16(Bt[n][k], At[m][k], acc[ai][bj][m][n], 0, 0, 0); __builtin_amdgcn_s_setprio(0); } while (0)
; #define PG8_WAIT_V(n) asm volatile("s_waitcnt vmcnt(" #n ")" ::: "memory")
; #define PG8_WAIT_L(n) asm volatile("s_waitcnt lgkmcnt(" #n ")" ::: "memory")
; #define PG8_BAR __builtin_amdgcn_s_barrier()
; #define PG8_SCHED __builtin_amdgcn_sched_barrier(0)
; template <class Epi, class Sched, bool ATILE = false>
; __device__ __forceinline__ void gemm_phase(LAS unsigned char* lds, const Gemm g, const Sched& S, const Epi& E) {
;     ...
;             PG8_WAIT_V(6); PG8_BAR; PG8_MMA(1, 1, At, B1); PG8_BAR;
;             PG8_LDB(B0, 1, 0); PG8_SCHED; PG8_LDA(At, 1, 0); PG8_STAGE(PG8_SA(0, 1), a2 + hstepA, voffA);
;             PG8_WAIT_L(8); PG8_BAR; PG8_WAIT_L(0); PG8_MMA(0, 0, At, B0); PG8_BAR; PG8_SCHED;
;             PG8_LDB(B1, 1, 1); PG8_STAGE(PG8_SB(1, 0), b3, voffB);
;             PG8_BAR; PG8_WAIT_L(0); PG8_MMA(0, 1, At, B1); PG8_BAR;
;             PG8_LDA(At, 1, 1); PG8_STAGE(PG8_SA(1, 0), a3, voffA);
	v_mfma_f32_16x16x32_bf16 v[52:55], v[222:225], v[144:147], v[52:55]
	v_mfma_f32_16x16x32_bf16 v[48:51], v[230:233], v[144:147], v[48:51]
	v_mfma_f32_16x16x32_bf16 v[36:39], v[222:225], v[192:195], v[36:39]
	v_mfma_f32_16x16x32_bf16 v[32:35], v[230:233], v[192:195], v[32:35]
	v_mfma_f32_16x16x32_bf16 v[20:23], v[222:225], v[200:203], v[20:23]
	v_mfma_f32_16x16x32_bf16 v[16:19], v[230:233], v[200:203], v[16:19]
	v_mfma_f32_16x16x32_bf16 v[4:7], v[222:225], v[214:217], v[4:7]
	v_mfma_f32_16x16x32_bf16 v[0:3], v[230:233], v[214:217], v[0:3]
	s_add_i32 s27, 0, 0x18000
	v_mfma_f32_16x16x32_bf16 v[52:55], v[226:229], v[148:151], v[52:55]
	v_add_u32_e32 v140, s27, v157
	v_mfma_f32_16x16x32_bf16 v[48:51], v[234:237], v[148:151], v[48:51]
	v_mfma_f32_16x16x32_bf16 v[36:39], v[226:229], v[196:199], v[36:39]
	v_mfma_f32_16x16x32_bf16 v[32:35], v[234:237], v[196:199], v[32:35]
	v_mfma_f32_16x16x32_bf16 v[20:23], v[226:229], v[204:207], v[20:23]
	v_mfma_f32_16x16x32_bf16 v[16:19], v[234:237], v[204:207], v[16:19]
	v_mfma_f32_16x16x32_bf16 v[4:7], v[226:229], v[218:221], v[4:7]
	v_mfma_f32_16x16x32_bf16 v[0:3], v[234:237], v[218:221], v[0:3]
	s_barrier
	s_setprio 0
	ds_read_b128 v[128:131], v140
	ds_read_b128 v[132:135], v140 offset:1024
	ds_read_b128 v[136:139], v140 offset:2048
	ds_read_b128 v[140:143], v140 offset:3072
	s_add_u32 s38, s38, 0x4000
	s_addc_u32 s39, s39, 0
	s_mov_b32 m0, s40
	ds_read_b128 v[144:147], v210 offset:32768
	ds_read_b128 v[148:151], v210 offset:33792
	ds_read_b128 v[192:195], v210 offset:34816
	ds_read_b128 v[196:199], v210 offset:35840
	ds_read_b128 v[200:203], v210 offset:36864
	ds_read_b128 v[204:207], v210 offset:37888
	ds_read_b128 v[214:217], v210 offset:38912
	ds_read_b128 v[218:221], v210 offset:39936
	global_load_lds_dwordx4 v160, s[38:39]
	s_mov_b32 m0, s41
	s_nop 0
	global_load_lds_dwordx4 v164, s[38:39]
	s_waitcnt lgkmcnt(8)
	s_setprio 1
	s_barrier
	s_waitcnt lgkmcnt(0)
	v_mfma_f32_16x16x32_bf16 v[120:123], v[128:131], v[144:147], v[120:123]
	v_mfma_f32_16x16x32_bf16 v[116:119], v[136:139], v[144:147], v[116:119]
	v_mfma_f32_16x16x32_bf16 v[108:111], v[128:131], v[192:195], v[108:111]
	v_mfma_f32_16x16x32_bf16 v[100:103], v[136:139], v[192:195], v[100:103]
	v_mfma_f32_16x16x32_bf16 v[92:95], v[128:131], v[200:203], v[92:95]
	v_mfma_f32_16x16x32_bf16 v[84:87], v[136:139], v[200:203], v[84:87]
	v_mfma_f32_16x16x32_bf16 v[76:79], v[128:131], v[214:217], v[76:79]
	v_mfma_f32_16x16x32_bf16 v[68:71], v[136:139], v[214:217], v[68:71]
	s_add_i32 s38, 0, 0x1c000
	v_mfma_f32_16x16x32_bf16 v[120:123], v[132:135], v[148:151], v[120:123]
	s_add_i32 s27, s27, s4
	v_mfma_f32_16x16x32_bf16 v[116:119], v[140:143], v[148:151], v[116:119]
	v_add_u32_e32 v213, s38, v157
	v_mfma_f32_16x16x32_bf16 v[108:111], v[132:135], v[196:199], v[108:111]
	s_mov_b32 m0, s27
	v_mfma_f32_16x16x32_bf16 v[100:103], v[140:143], v[196:199], v[100:103]
	v_mfma_f32_16x16x32_bf16 v[92:95], v[132:135], v[204:207], v[92:95]
	v_mfma_f32_16x16x32_bf16 v[84:87], v[140:143], v[204:207], v[84:87]
	v_mfma_f32_16x16x32_bf16 v[76:79], v[132:135], v[218:221], v[76:79]
	v_mfma_f32_16x16x32_bf16 v[68:71], v[140:143], v[218:221], v[68:71]
	s_barrier
	s_setprio 0
	ds_read_b128 v[222:225], v213
	ds_read_b128 v[226:229], v213 offset:1024
	ds_read_b128 v[230:233], v213 offset:2048
	ds_read_b128 v[234:237], v213 offset:3072
	global_load_lds_dwordx4 v162, s[98:99]
	s_add_i32 m0, s27, 0x2000
	s_nop 0
	global_load_lds_dwordx4 v166, s[98:99]
	s_setprio 1
	s_barrier
; #define PG8_STAGE(bufoff, gbase, voff) do { _Pragma("unroll") for (int _i = 0; _i < 2; ++_i) \
;         __builtin_amdgcn_global_load_lds((const unsigned*)((const char*)(gbase) + (voff)[_i]), (LAS unsigned*)(lds + (bufoff) + ldsw + _i * 8192), 16, 0, 0); } while (0)
; #define PG8_LDA(dst, b, h) do { _Pragma("unroll") for (int m = 0; m < 4; ++m) _Pragma("unroll") for (int k = 0; k < 2; ++k) dst[m][k] = *(const LAS bf16x8*)(lds + PG8_SA(b, h) + aoff + m * 2048 + k * 1024); } while (0)
; #define PG8_MMA(ai, bj, At, Bt) do { __builtin_amdgcn_s_setprio(1); _Pragma("unroll") for (int m = 0; m < 4; ++m) _Pragma("unroll") for (int n = 0; n < 2; ++n) _Pragma("unroll") for (int k = 0; k < 2; ++k) \
;         acc[ai][bj][m][n] = __builtin_amdgcn_mfma_f32_16x16x32_bf16(Bt[n][k], At[m][k], acc[ai][bj][m][n], 0, 0, 0); __builtin_amdgcn_s_setprio(0); } while (0)
; #define PG8_WAIT_V(n) asm volatile("s_waitcnt vmcnt(" #n ")" ::: "memory")
; #define PG8_WAIT_L(n) asm volatile("s_waitcnt lgkmcnt(" #n ")" ::: "memory")
; #define PG8_BAR __builtin_amdgcn_s_barrier()
; #define PG8_SCHED __builtin_amdgcn_sched_barrier(0)
; template <class Epi, class Sched, bool ATILE = false>
; __device__ __forceinline__ void gemm_phase(LAS unsigned char* lds, const Gemm g, const Sched& S, const Epi& E) {
;     ...
;             PG8_BAR; PG8_WAIT_L(0); PG8_MMA(0, 1, At, B1); PG8_BAR;
;             PG8_LDA(At, 1, 1); PG8_STAGE(PG8_SA(1, 0), a3, voffA);
;             PG8_BAR; PG8_WAIT_L(0); PG8_MMA(1, 0, At, B0); PG8_BAR; PG8_SCHED;
;             PG8_STAGE(PG8_SB(1, 1), b3 + hstepB, voffB);
;             PG8_WAIT_V(6); PG8_BAR; PG8_MMA(1, 1, At, B1); PG8_BAR;
;         }
	s_waitcnt lgkmcnt(0)
	v_mfma_f32_16x16x32_bf16 v[124:127], v[222:225], v[144:147], v[124:127]
	v_mfma_f32_16x16x32_bf16 v[112:115], v[230:233], v[144:147], v[112:115]
	v_mfma_f32_16x16x32_bf16 v[104:107], v[222:225], v[192:195], v[104:107]
	v_mfma_f32_16x16x32_bf16 v[96:99], v[230:233], v[192:195], v[96:99]
	v_mfma_f32_16x16x32_bf16 v[88:91], v[222:225], v[200:203], v[88:91]
	v_mfma_f32_16x16x32_bf16 v[80:83], v[230:233], v[200:203], v[80:83]
	v_mfma_f32_16x16x32_bf16 v[72:75], v[222:225], v[214:217], v[72:75]
	v_mfma_f32_16x16x32_bf16 v[64:67], v[230:233], v[214:217], v[64:67]
	s_mov_b32 m0, s43
	v_mfma_f32_16x16x32_bf16 v[124:127], v[226:229], v[148:151], v[124:127]
	v_mfma_f32_16x16x32_bf16 v[112:115], v[234:237], v[148:151], v[112:115]
	v_mfma_f32_16x16x32_bf16 v[104:107], v[226:229], v[196:199], v[104:107]
	v_mfma_f32_16x16x32_bf16 v[96:99], v[234:237], v[196:199], v[96:99]
	v_mfma_f32_16x16x32_bf16 v[88:91], v[226:229], v[204:207], v[88:91]
	v_mfma_f32_16x16x32_bf16 v[80:83], v[234:237], v[204:207], v[80:83]
	v_mfma_f32_16x16x32_bf16 v[72:75], v[226:229], v[218:221], v[72:75]
	v_mfma_f32_16x16x32_bf16 v[64:67], v[234:237], v[218:221], v[64:67]
	s_barrier
	s_setprio 0
	ds_read_b128 v[144:147], v210 offset:49152
	ds_read_b128 v[148:151], v210 offset:50176
	ds_read_b128 v[192:195], v210 offset:51200
	ds_read_b128 v[196:199], v210 offset:52224
	ds_read_b128 v[200:203], v210 offset:53248
	ds_read_b128 v[204:207], v210 offset:54272
	ds_read_b128 v[214:217], v210 offset:55296
	ds_read_b128 v[218:221], v210 offset:56320
	global_load_lds_dwordx4 v160, s[36:37]
	s_mov_b32 m0, s44
	s_nop 0
	global_load_lds_dwordx4 v164, s[36:37]
	s_setprio 1
	s_barrier
	s_waitcnt lgkmcnt(0)
	v_mfma_f32_16x16x32_bf16 v[60:63], v[128:131], v[144:147], v[60:63]
	v_mfma_f32_16x16x32_bf16 v[56:59], v[136:139], v[144:147], v[56:59]
	v_mfma_f32_16x16x32_bf16 v[44:47], v[128:131], v[192:195], v[44:47]
	v_mfma_f32_16x16x32_bf16 v[40:43], v[136:139], v[192:195], v[40:43]
	v_mfma_f32_16x16x32_bf16 v[28:31], v[128:131], v[200:203], v[28:31]
	v_mfma_f32_16x16x32_bf16 v[24:27], v[136:139], v[200:203], v[24:27]
	v_mfma_f32_16x16x32_bf16 v[12:15], v[128:131], v[214:217], v[12:15]
	v_mfma_f32_16x16x32_bf16 v[8:11], v[136:139], v[214:217], v[8:11]
	s_add_u32 s34, s34, 0x80080
	v_mfma_f32_16x16x32_bf16 v[60:63], v[132:135], v[148:151], v[60:63]
	s_addc_u32 s35, s35, 0
	v_mfma_f32_16x16x32_bf16 v[56:59], v[140:143], v[148:151], v[56:59]
	s_add_i32 s27, s38, s4
	v_mfma_f32_16x16x32_bf16 v[44:47], v[132:135], v[196:199], v[44:47]
	s_mov_b32 m0, s27
	v_mfma_f32_16x16x32_bf16 v[40:43], v[140:143], v[196:199], v[40:43]
	v_mfma_f32_16x16x32_bf16 v[28:31], v[132:135], v[204:207], v[28:31]
	v_mfma_f32_16x16x32_bf16 v[24:27], v[140:143], v[204:207], v[24:27]
	v_mfma_f32_16x16x32_bf16 v[12:15], v[132:135], v[218:221], v[12:15]
	v_mfma_f32_16x16x32_bf16 v[8:11], v[140:143], v[218:221], v[8:11]
	s_barrier
	s_setprio 0
	s_nop 0
	global_load_lds_dwordx4 v162, s[34:35]
	s_add_i32 m0, s27, 0x2000
	s_nop 0
	global_load_lds_dwordx4 v166, s[34:35]
	s_waitcnt vmcnt(6)
	s_setprio 1
	s_barrier
	v_mfma_f32_16x16x32_bf16 v[52:55], v[222:225], v[144:147], v[52:55]
	v_mfma_f32_16x16x32_bf16 v[48:51], v[230:233], v[144:147], v[48:51]
	v_mfma_f32_16x16x32_bf16 v[36:39], v[222:225], v[192:195], v[36:39]
	v_mfma_f32_16x16x32_bf16 v[32:35], v[230:233], v[192:195], v[32:35]
	v_mfma_f32_16x16x32_bf16 v[20:23], v[222:225], v[200:203], v[20:23]
	v_mfma_f32_16x16x32_bf16 v[16:19], v[230:233], v[200:203], v[16:19]
	v_mfma_f32_16x16x32_bf16 v[4:7], v[222:225], v[214:217], v[4:7]
	s_add_u32 s13, s13, 0x100
	v_mfma_f32_16x16x32_bf16 v[0:3], v[230:233], v[214:217], v[0:3]
	s_addc_u32 s17, s17, 0
	v_mfma_f32_16x16x32_bf16 v[52:55], v[226:229], v[148:151], v[52:55]
	s_add_u32 s30, s30, 0x10000
	v_mfma_f32_16x16x32_bf16 v[48:51], v[234:237], v[148:151], v[48:51]
	s_addc_u32 s31, s31, 0
	v_mfma_f32_16x16x32_bf16 v[36:39], v[226:229], v[196:199], v[36:39]
	s_cmp_ge_i32 s29, s1
	v_mfma_f32_16x16x32_bf16 v[32:35], v[234:237], v[196:199], v[32:35]
	s_mov_b32 s27, s29
	v_mfma_f32_16x16x32_bf16 v[20:23], v[226:229], v[204:207], v[20:23]
	v_mfma_f32_16x16x32_bf16 v[16:19], v[234:237], v[204:207], v[16:19]
	v_mfma_f32_16x16x32_bf16 v[4:7], v[226:229], v[218:221], v[4:7]
	v_mfma_f32_16x16x32_bf16 v[0:3], v[234:237], v[218:221], v[0:3]
	s_barrier
	s_setprio 0
	s_cbranch_scc0 .LBB0_1658
	s_nop 5
	s_branch .LBB0_1662

;     __device__ bool next(int i, Unit& u) const { const int L = i * G + c; if (L >= 64 * 9) return false; u.pm = L; u.pn = L / 9; u.kt0 = 0; u.nt = ntf; u.ks = 0; return true; }
; #define PG8_STAGE(bufoff, gbase, voff) do { _Pragma("unroll") for (int _i = 0; _i < 2; ++_i) \
;         __builtin_amdgcn_global_load_lds((const unsigned*)((const char*)(gbase) + (voff)[_i]), (LAS unsigned*)(lds + (bufoff) + ldsw + _i * 8192), 16, 0, 0); } while (0)
; #define PG8_LDA(dst, b, h) do { _Pragma("unroll") for (int m = 0; m < 4; ++m) _Pragma("unroll") for (int k = 0; k < 2; ++k) dst[m][k] = *(const LAS bf16x8*)(lds + PG8_SA(b, h) + aoff + m * 2048 + k * 1024); } while (0)
; #define PG8_LDB(dst, b, h) do { _Pragma("unroll") for (int n = 0; n < 2; ++n) _Pragma("unroll") for (int k = 0; k < 2; ++k) dst[n][k] = *(const LAS bf16x8*)(lds + PG8_SB(b, h) + boff + n * 2048 + k * 1024); } while (0)
; template <class Epi, class Sched, bool ATILE = false>
; __device__ __forceinline__ void gemm_phase(LAS unsigned char* lds, const Gemm g, const Sched& S, const Epi& E) {
;     ...
;         const bool has_next = S.next(ui + 1, nxt);
;         const char* nA = has_next ? (const char*)g.A + (size_t)nxt.pm * tstepA + (size_t)nxt.kt0 * kstepA : cA; const char* nB = has_next ? (const char*)g.Bt + (size_t)nxt.pn * tstepB + (size_t)nxt.kt0 * kstep : cB;
;         int nt = cur.nt; asm volatile("" : "+s"(nt));
;         for (int t = 0; t < nt; t += 2) {
;             const bool last = (t == nt - 2);
;             const char* a1 = cA + (size_t)(t + 1) * kstepA;
;             const char* a2 = last ? nA : cA + (size_t)(t + 2) * kstepA; const char* b2 = last ? nB : cB + (size_t)(t + 2) * kstep;
;             const char* a3 = a2 + kstepA; const char* b3 = b2 + kstep;
;             PG8_LDB(B0, 0, 0); PG8_SCHED; PG8_LDA(At, 0, 0); PG8_STAGE(PG8_SA(1, 1), a1 + hstepA, voffA);
;             PG8_WAIT_L(8); PG8_BAR; PG8_WAIT_L(0); PG8_MMA(0, 0, At, B0); PG8_BAR; PG8_SCHED;
;             PG8_LDB(B1, 0, 1); PG8_STAGE(PG8_SB(0, 0), b2, voffB);
;             PG8_BAR; PG8_WAIT_L(0); PG8_MMA(0, 1, At, B1); PG8_BAR;
;             PG8_LDA(At, 0, 1); PG8_STAGE(PG8_SA(0, 0), a2, voffA);
;             PG8_BAR; PG8_WAIT_L(0); PG8_MMA(1, 0, At, B0); PG8_BAR; PG8_SCHED;
;             PG8_STAGE(PG8_SB(0, 1), b2 + hstepB, voffB);
;             PG8_WAIT_V(6); PG8_BAR; PG8_MMA(1, 1, At, B1); PG8_BAR;
.LBB0_1812:
	ds_read_b128 v[176:179], v139
	ds_read_b128 v[180:183], v139 offset:1024
	ds_read_b128 v[184:187], v139 offset:2048
	ds_read_b128 v[188:191], v139 offset:3072
	s_add_i32 m0, s37, 0xc000
	ds_read_b128 v[192:195], v159
	ds_read_b128 v[196:199], v159 offset:1024
	ds_read_b128 v[200:203], v159 offset:2048
	ds_read_b128 v[204:207], v159 offset:3072
	ds_read_b128 v[208:211], v159 offset:4096
	ds_read_b128 v[212:215], v159 offset:5120
	ds_read_b128 v[216:219], v159 offset:6144
	ds_read_b128 v[220:223], v159 offset:7168
	global_load_lds_dwordx4 v164, s[6:7]
	s_add_i32 m0, s37, 0xe000
	s_nop 0
	global_load_lds_dwordx4 v166, s[6:7]
	s_waitcnt lgkmcnt(8)
	s_setprio 1
	s_barrier
	s_waitcnt lgkmcnt(0)
	v_mfma_f32_16x16x32_bf16 v[120:123], v[176:179], v[192:195], v[120:123]
	s_add_i32 s34, s8, 2
	v_mfma_f32_16x16x32_bf16 v[112:115], v[184:187], v[192:195], v[112:115]
	s_add_u32 s9, s6, 0xfff80080
	v_mfma_f32_16x16x32_bf16 v[104:107], v[176:179], v[200:203], v[104:107]
	s_addc_u32 s10, s7, -1
	v_mfma_f32_16x16x32_bf16 v[96:99], v[184:187], v[200:203], v[96:99]
	s_cmp_eq_u32 s19, s8
	v_mfma_f32_16x16x32_bf16 v[88:91], v[176:179], v[208:211], v[88:91]
	s_cselect_b32 s8, s18, s25
	v_mfma_f32_16x16x32_bf16 v[80:83], v[184:187], v[208:211], v[80:83]
	s_cselect_b32 s11, s13, s10
	v_mfma_f32_16x16x32_bf16 v[72:75], v[176:179], v[216:219], v[72:75]
	s_cselect_b32 s10, s16, s9
	v_mfma_f32_16x16x32_bf16 v[64:67], v[184:187], v[216:219], v[64:67]
	s_cselect_b32 s9, s17, s27
	v_mfma_f32_16x16x32_bf16 v[120:123], v[180:183], v[196:199], v[120:123]
	s_add_i32 s35, s51, s36
	v_mfma_f32_16x16x32_bf16 v[112:115], v[188:191], v[196:199], v[112:115]
	s_add_u32 s98, s8, s22
	v_mfma_f32_16x16x32_bf16 v[104:107], v[180:183], v[204:207], v[104:107]
	s_addc_u32 s99, s9, s23
	v_mfma_f32_16x16x32_bf16 v[96:99], v[188:191], v[204:207], v[96:99]
	s_mov_b32 m0, s35
	v_mfma_f32_16x16x32_bf16 v[88:91], v[180:183], v[212:215], v[88:91]
	v_mfma_f32_16x16x32_bf16 v[80:83], v[188:191], v[212:215], v[80:83]
	v_mfma_f32_16x16x32_bf16 v[72:75], v[180:183], v[220:223], v[72:75]
	v_mfma_f32_16x16x32_bf16 v[64:67], v[188:191], v[220:223], v[64:67]
	s_barrier
	s_setprio 0
	ds_read_b128 v[224:227], v173
	ds_read_b128 v[228:231], v173 offset:1024
	ds_read_b128 v[232:235], v173 offset:2048
	ds_read_b128 v[236:239], v173 offset:3072
	global_load_lds_dwordx4 v130, s[8:9]
	s_add_i32 m0, s35, 0x2000
	s_nop 0
	global_load_lds_dwordx4 v134, s[8:9]
	s_setprio 1
	s_barrier
	s_waitcnt lgkmcnt(0)
	v_mfma_f32_16x16x32_bf16 v[124:127], v[224:227], v[192:195], v[124:127]
	v_mfma_f32_16x16x32_bf16 v[116:119], v[232:235], v[192:195], v[116:119]
	v_mfma_f32_16x16x32_bf16 v[108:111], v[224:227], v[200:203], v[108:111]
	v_mfma_f32_16x16x32_bf16 v[100:103], v[232:235], v[200:203], v[100:103]
	v_mfma_f32_16x16x32_bf16 v[92:95], v[224:227], v[208:211], v[92:95]
	v_mfma_f32_16x16x32_bf16 v[84:87], v[232:235], v[208:211], v[84:87]
	v_mfma_f32_16x16x32_bf16 v[76:79], v[224:227], v[216:219], v[76:79]
	v_mfma_f32_16x16x32_bf16 v[68:71], v[232:235], v[216:219], v[68:71]
	s_mov_b32 m0, s37
	v_mfma_f32_16x16x32_bf16 v[124:127], v[228:231], v[196:199], v[124:127]
	s_add_u32 s100, s10, s22
	v_mfma_f32_16x16x32_bf16 v[116:119], v[236:239], v[196:199], v[116:119]
	s_addc_u32 s101, s11, s23
	v_mfma_f32_16x16x32_bf16 v[108:111], v[228:231], v[204:207], v[108:111]
	v_mfma_f32_16x16x32_bf16 v[100:103], v[236:239], v[204:207], v[100:103]
	v_mfma_f32_16x16x32_bf16 v[92:95], v[228:231], v[212:215], v[92:95]
	v_mfma_f32_16x16x32_bf16 v[84:87], v[236:239], v[212:215], v[84:87]
	v_mfma_f32_16x16x32_bf16 v[76:79], v[228:231], v[220:223], v[76:79]
	v_mfma_f32_16x16x32_bf16 v[68:71], v[236:239], v[220:223], v[68:71]
	s_barrier
	s_setprio 0
	ds_read_b128 v[192:195], v159 offset:16384
	ds_read_b128 v[196:199], v159 offset:17408
	ds_read_b128 v[200:203], v159 offset:18432
	ds_read_b128 v[204:207], v159 offset:19456
	ds_read_b128 v[208:211], v159 offset:20480
	ds_read_b128 v[212:215], v159 offset:21504
	ds_read_b128 v[216:219], v159 offset:22528
	ds_read_b128 v[220:223], v159 offset:23552
	global_load_lds_dwordx4 v128, s[10:11]
	s_mov_b32 m0, s38
	s_nop 0
	global_load_lds_dwordx4 v132, s[10:11]
	s_setprio 1
	s_barrier
	s_waitcnt lgkmcnt(0)
	v_mfma_f32_16x16x32_bf16 v[56:59], v[176:179], v[192:195], v[56:59]
	v_mfma_f32_16x16x32_bf16 v[48:51], v[184:187], v[192:195], v[48:51]
	v_mfma_f32_16x16x32_bf16 v[40:43], v[176:179], v[200:203], v[40:43]
	v_mfma_f32_16x16x32_bf16 v[32:35], v[184:187], v[200:203], v[32:35]
	v_mfma_f32_16x16x32_bf16 v[24:27], v[176:179], v[208:211], v[24:27]
	v_mfma_f32_16x16x32_bf16 v[16:19], v[184:187], v[208:211], v[16:19]
	v_mfma_f32_16x16x32_bf16 v[8:11], v[176:179], v[216:219], v[8:11]
	v_mfma_f32_16x16x32_bf16 v[4:7], v[184:187], v[216:219], v[4:7]
	s_add_u32 s54, s8, 0x80000
	v_mfma_f32_16x16x32_bf16 v[56:59], v[180:183], v[196:199], v[56:59]
	s_addc_u32 s55, s9, 0
	v_mfma_f32_16x16x32_bf16 v[48:51], v[188:191], v[196:199], v[48:51]
	s_add_i32 s35, s52, s36
	v_mfma_f32_16x16x32_bf16 v[40:43], v[180:183], v[204:207], v[40:43]
	s_mov_b32 m0, s35
	v_mfma_f32_16x16x32_bf16 v[32:35], v[188:191], v[204:207], v[32:35]
	v_mfma_f32_16x16x32_bf16 v[24:27], v[180:183], v[212:215], v[24:27]
	v_mfma_f32_16x16x32_bf16 v[16:19], v[188:191], v[212:215], v[16:19]
	v_mfma_f32_16x16x32_bf16 v[8:11], v[180:183], v[220:223], v[8:11]
	v_mfma_f32_16x16x32_bf16 v[4:7], v[188:191], v[220:223], v[4:7]
	s_barrier
	s_setprio 0
	s_nop 0
	global_load_lds_dwordx4 v130, s[54:55]
	s_add_i32 m0, s35, 0x2000
	s_nop 0
	global_load_lds_dwordx4 v134, s[54:55]
	s_waitcnt vmcnt(6)
	s_setprio 1
	s_barrier
; #define PG8_STAGE(bufoff, gbase, voff) do { _Pragma("unroll") for (int _i = 0; _i < 2; ++_i) \
;         __builtin_amdgcn_global_load_lds((const unsigned*)((const char*)(gbase) + (voff)[_i]), (LAS unsigned*)(lds + (bufoff) + ldsw + _i * 8192), 16, 0, 0); } while (0)
; #define PG8_LDA(dst, b, h) do { _Pragma("unroll") for (int m = 0; m < 4; ++m) _Pragma("unroll") for (int k = 0; k < 2; ++k) dst[m][k] = *(const LAS bf16x8*)(lds + PG8_SA(b, h) + aoff + m * 2048 + k * 1024); } while (0)
; #define PG8_LDB(dst, b, h) do { _Pragma("unroll") for (int n = 0; n < 2; ++n) _Pragma("unroll") for (int k = 0; k < 2; ++k) dst[n][k] = *(const LAS bf16x8*)(lds + PG8_SB(b, h) + boff + n * 2048 + k * 1024); } while (0)
; #define PG8_MMA(ai, bj, At, Bt) do { __builtin_amdgcn_s_setprio(1); _Pragma("unroll") for (int m = 0; m < 4; ++m) _Pragma("unroll") for (int n = 0; n < 2; ++n) _Pragma("unroll") for (int k = 0; k < 2; ++k) \
;         acc[ai][bj][m][n] = __builtin_amdgcn_mfma_f32_16x16x32_bf16(Bt[n][k], At[m][k], acc[ai][bj][m][n], 0, 0, 0); __builtin_amdgcn_s_setprio(0); } while (0)
; #define PG8_WAIT_V(n) asm volatile("s_waitcnt vmcnt(" #n ")" ::: "memory")
; #define PG8_WAIT_L(n) asm volatile("s_waitcnt lgkmcnt(" #n ")" ::: "memory")
; #define PG8_BAR __builtin_amdgcn_s_barrier()
; #define PG8_SCHED __builtin_amdgcn_sched_barrier(0)
; template <class Epi, class Sched, bool ATILE = false>
; __device__ __forceinline__ void gemm_phase(LAS unsigned char* lds, const Gemm g, const Sched& S, const Epi& E) {
;     ...
;             PG8_WAIT_V(6); PG8_BAR; PG8_MMA(1, 1, At, B1); PG8_BAR;
;             PG8_LDB(B0, 1, 0); PG8_SCHED; PG8_LDA(At, 1, 0); PG8_STAGE(PG8_SA(0, 1), a2 + hstepA, voffA);
;             PG8_WAIT_L(8); PG8_BAR; PG8_WAIT_L(0); PG8_MMA(0, 0, At, B0); PG8_BAR; PG8_SCHED;
;             PG8_LDB(B1, 1, 1); PG8_STAGE(PG8_SB(1, 0), b3, voffB);
;             PG8_BAR; PG8_WAIT_L(0); PG8_MMA(0, 1, At, B1); PG8_BAR;
;             PG8_LDA(At, 1, 1); PG8_STAGE(PG8_SA(1, 0), a3, voffA);
	v_mfma_f32_16x16x32_bf16 v[60:63], v[224:227], v[192:195], v[60:63]
	v_mfma_f32_16x16x32_bf16 v[52:55], v[232:235], v[192:195], v[52:55]
	v_mfma_f32_16x16x32_bf16 v[44:47], v[224:227], v[200:203], v[44:47]
	v_mfma_f32_16x16x32_bf16 v[36:39], v[232:235], v[200:203], v[36:39]
	v_mfma_f32_16x16x32_bf16 v[28:31], v[224:227], v[208:211], v[28:31]
	v_mfma_f32_16x16x32_bf16 v[20:23], v[232:235], v[208:211], v[20:23]
	v_mfma_f32_16x16x32_bf16 v[12:15], v[224:227], v[216:219], v[12:15]
	v_mfma_f32_16x16x32_bf16 v[0:3], v[232:235], v[216:219], v[0:3]
	s_add_i32 s35, 0, 0x18000
	v_mfma_f32_16x16x32_bf16 v[60:63], v[228:231], v[196:199], v[60:63]
	v_add_u32_e32 v172, s35, v157
	v_mfma_f32_16x16x32_bf16 v[52:55], v[236:239], v[196:199], v[52:55]
	v_mfma_f32_16x16x32_bf16 v[44:47], v[228:231], v[204:207], v[44:47]
	v_mfma_f32_16x16x32_bf16 v[36:39], v[236:239], v[204:207], v[36:39]
	v_mfma_f32_16x16x32_bf16 v[28:31], v[228:231], v[212:215], v[28:31]
	v_mfma_f32_16x16x32_bf16 v[20:23], v[236:239], v[212:215], v[20:23]
	v_mfma_f32_16x16x32_bf16 v[12:15], v[228:231], v[220:223], v[12:15]
	v_mfma_f32_16x16x32_bf16 v[0:3], v[236:239], v[220:223], v[0:3]
	s_barrier
	s_setprio 0
	ds_read_b128 v[176:179], v172
	ds_read_b128 v[180:183], v172 offset:1024
	ds_read_b128 v[184:187], v172 offset:2048
	ds_read_b128 v[188:191], v172 offset:3072
	s_add_u32 s10, s10, 0x80000
	s_addc_u32 s11, s11, 0
	s_mov_b32 m0, s39
	ds_read_b128 v[192:195], v159 offset:32768
	ds_read_b128 v[196:199], v159 offset:33792
	ds_read_b128 v[200:203], v159 offset:34816
	ds_read_b128 v[204:207], v159 offset:35840
	ds_read_b128 v[208:211], v159 offset:36864
	ds_read_b128 v[212:215], v159 offset:37888
	ds_read_b128 v[216:219], v159 offset:38912
	ds_read_b128 v[220:223], v159 offset:39936
	global_load_lds_dwordx4 v128, s[10:11]
	s_mov_b32 m0, s40
	s_nop 0
	global_load_lds_dwordx4 v132, s[10:11]
	s_waitcnt lgkmcnt(8)
	s_setprio 1
	s_barrier
	s_waitcnt lgkmcnt(0)
	v_mfma_f32_16x16x32_bf16 v[120:123], v[176:179], v[192:195], v[120:123]
	v_mfma_f32_16x16x32_bf16 v[112:115], v[184:187], v[192:195], v[112:115]
	v_mfma_f32_16x16x32_bf16 v[104:107], v[176:179], v[200:203], v[104:107]
	v_mfma_f32_16x16x32_bf16 v[96:99], v[184:187], v[200:203], v[96:99]
	v_mfma_f32_16x16x32_bf16 v[88:91], v[176:179], v[208:211], v[88:91]
	v_mfma_f32_16x16x32_bf16 v[80:83], v[184:187], v[208:211], v[80:83]
	v_mfma_f32_16x16x32_bf16 v[72:75], v[176:179], v[216:219], v[72:75]
	v_mfma_f32_16x16x32_bf16 v[64:67], v[184:187], v[216:219], v[64:67]
	s_add_i32 s10, 0, 0x1c000
	v_mfma_f32_16x16x32_bf16 v[120:123], v[180:183], v[196:199], v[120:123]
	s_add_i32 s11, s35, s36
	v_mfma_f32_16x16x32_bf16 v[112:115], v[188:191], v[196:199], v[112:115]
	v_add_u32_e32 v172, s10, v157
	v_mfma_f32_16x16x32_bf16 v[104:107], v[180:183], v[204:207], v[104:107]
	s_mov_b32 m0, s11
	v_mfma_f32_16x16x32_bf16 v[96:99], v[188:191], v[204:207], v[96:99]
	v_mfma_f32_16x16x32_bf16 v[88:91], v[180:183], v[212:215], v[88:91]
	v_mfma_f32_16x16x32_bf16 v[80:83], v[188:191], v[212:215], v[80:83]
	v_mfma_f32_16x16x32_bf16 v[72:75], v[180:183], v[220:223], v[72:75]
	v_mfma_f32_16x16x32_bf16 v[64:67], v[188:191], v[220:223], v[64:67]
	s_barrier
	s_setprio 0
	ds_read_b128 v[224:227], v172
	ds_read_b128 v[228:231], v172 offset:1024
	ds_read_b128 v[232:235], v172 offset:2048
	ds_read_b128 v[236:239], v172 offset:3072
	global_load_lds_dwordx4 v130, s[98:99]
	s_add_i32 m0, s11, 0x2000
	s_nop 0
	global_load_lds_dwordx4 v134, s[98:99]
	s_setprio 1
	s_barrier
; #define PG8_STAGE(bufoff, gbase, voff) do { _Pragma("unroll") for (int _i = 0; _i < 2; ++_i) \
;         __builtin_amdgcn_global_load_lds((const unsigned*)((const char*)(gbase) + (voff)[_i]), (LAS unsigned*)(lds + (bufoff) + ldsw + _i * 8192), 16, 0, 0); } while (0)
; #define PG8_LDA(dst, b, h) do { _Pragma("unroll") for (int m = 0; m < 4; ++m) _Pragma("unroll") for (int k = 0; k < 2; ++k) dst[m][k] = *(const LAS bf16x8*)(lds + PG8_SA(b, h) + aoff + m * 2048 + k * 1024); } while (0)
; #define PG8_MMA(ai, bj, At, Bt) do { __builtin_amdgcn_s_setprio(1); _Pragma("unroll") for (int m = 0; m < 4; ++m) _Pragma("unroll") for (int n = 0; n < 2; ++n) _Pragma("unroll") for (int k = 0; k < 2; ++k) \
;         acc[ai][bj][m][n] = __builtin_amdgcn_mfma_f32_16x16x32_bf16(Bt[n][k], At[m][k], acc[ai][bj][m][n], 0, 0, 0); __builtin_amdgcn_s_setprio(0); } while (0)
; #define PG8_WAIT_V(n) asm volatile("s_waitcnt vmcnt(" #n ")" ::: "memory")
; #define PG8_WAIT_L(n) asm volatile("s_waitcnt lgkmcnt(" #n ")" ::: "memory")
; #define PG8_BAR __builtin_amdgcn_s_barrier()
; #define PG8_SCHED __builtin_amdgcn_sched_barrier(0)
; template <class Epi, class Sched, bool ATILE = false>
; __device__ __forceinline__ void gemm_phase(LAS unsigned char* lds, const Gemm g, const Sched& S, const Epi& E) {
;     ...
;             PG8_BAR; PG8_WAIT_L(0); PG8_MMA(0, 1, At, B1); PG8_BAR;
;             PG8_LDA(At, 1, 1); PG8_STAGE(PG8_SA(1, 0), a3, voffA);
;             PG8_BAR; PG8_WAIT_L(0); PG8_MMA(1, 0, At, B0); PG8_BAR; PG8_SCHED;
;             PG8_STAGE(PG8_SB(1, 1), b3 + hstepB, voffB);
;             PG8_WAIT_V(6); PG8_BAR; PG8_MMA(1, 1, At, B1); PG8_BAR;
;         }
	s_waitcnt lgkmcnt(0)
	v_mfma_f32_16x16x32_bf16 v[124:127], v[224:227], v[192:195], v[124:127]
	v_mfma_f32_16x16x32_bf16 v[116:119], v[232:235], v[192:195], v[116:119]
	v_mfma_f32_16x16x32_bf16 v[108:111], v[224:227], v[200:203], v[108:111]
	v_mfma_f32_16x16x32_bf16 v[100:103], v[232:235], v[200:203], v[100:103]
	v_mfma_f32_16x16x32_bf16 v[92:95], v[224:227], v[208:211], v[92:95]
	v_mfma_f32_16x16x32_bf16 v[84:87], v[232:235], v[208:211], v[84:87]
	v_mfma_f32_16x16x32_bf16 v[76:79], v[224:227], v[216:219], v[76:79]
	v_mfma_f32_16x16x32_bf16 v[68:71], v[232:235], v[216:219], v[68:71]
	s_mov_b32 m0, s43
	v_mfma_f32_16x16x32_bf16 v[124:127], v[228:231], v[196:199], v[124:127]
	v_mfma_f32_16x16x32_bf16 v[116:119], v[236:239], v[196:199], v[116:119]
	v_mfma_f32_16x16x32_bf16 v[108:111], v[228:231], v[204:207], v[108:111]
	v_mfma_f32_16x16x32_bf16 v[100:103], v[236:239], v[204:207], v[100:103]
	v_mfma_f32_16x16x32_bf16 v[92:95], v[228:231], v[212:215], v[92:95]
	v_mfma_f32_16x16x32_bf16 v[84:87], v[236:239], v[212:215], v[84:87]
	v_mfma_f32_16x16x32_bf16 v[76:79], v[228:231], v[220:223], v[76:79]
	v_mfma_f32_16x16x32_bf16 v[68:71], v[236:239], v[220:223], v[68:71]
	s_barrier
	s_setprio 0
	ds_read_b128 v[192:195], v159 offset:49152
	ds_read_b128 v[196:199], v159 offset:50176
	ds_read_b128 v[200:203], v159 offset:51200
	ds_read_b128 v[204:207], v159 offset:52224
	ds_read_b128 v[208:211], v159 offset:53248
	ds_read_b128 v[212:215], v159 offset:54272
	ds_read_b128 v[216:219], v159 offset:55296
	ds_read_b128 v[220:223], v159 offset:56320
	global_load_lds_dwordx4 v128, s[100:101]
	s_mov_b32 m0, s44
	s_nop 0
	global_load_lds_dwordx4 v132, s[100:101]
	s_setprio 1
	s_barrier
	s_waitcnt lgkmcnt(0)
	v_mfma_f32_16x16x32_bf16 v[56:59], v[176:179], v[192:195], v[56:59]
	v_mfma_f32_16x16x32_bf16 v[48:51], v[184:187], v[192:195], v[48:51]
	v_mfma_f32_16x16x32_bf16 v[40:43], v[176:179], v[200:203], v[40:43]
	v_mfma_f32_16x16x32_bf16 v[32:35], v[184:187], v[200:203], v[32:35]
	v_mfma_f32_16x16x32_bf16 v[24:27], v[176:179], v[208:211], v[24:27]
	v_mfma_f32_16x16x32_bf16 v[16:19], v[184:187], v[208:211], v[16:19]
	v_mfma_f32_16x16x32_bf16 v[8:11], v[176:179], v[216:219], v[8:11]
	v_mfma_f32_16x16x32_bf16 v[4:7], v[184:187], v[216:219], v[4:7]
	s_add_u32 s8, s8, 0x80080
	v_mfma_f32_16x16x32_bf16 v[56:59], v[180:183], v[196:199], v[56:59]
	s_addc_u32 s9, s9, 0
	v_mfma_f32_16x16x32_bf16 v[48:51], v[188:191], v[196:199], v[48:51]
	s_add_i32 s10, s10, s36
	v_mfma_f32_16x16x32_bf16 v[40:43], v[180:183], v[204:207], v[40:43]
	s_mov_b32 m0, s10
	v_mfma_f32_16x16x32_bf16 v[32:35], v[188:191], v[204:207], v[32:35]
	v_mfma_f32_16x16x32_bf16 v[24:27], v[180:183], v[212:215], v[24:27]
	v_mfma_f32_16x16x32_bf16 v[16:19], v[188:191], v[212:215], v[16:19]
	v_mfma_f32_16x16x32_bf16 v[8:11], v[180:183], v[220:223], v[8:11]
	v_mfma_f32_16x16x32_bf16 v[4:7], v[188:191], v[220:223], v[4:7]
	s_barrier
	s_setprio 0
	s_nop 0
	global_load_lds_dwordx4 v130, s[8:9]
	s_add_i32 m0, s10, 0x2000
	s_nop 0
	global_load_lds_dwordx4 v134, s[8:9]
	s_waitcnt vmcnt(6)
	s_setprio 1
	s_barrier
	v_mfma_f32_16x16x32_bf16 v[60:63], v[224:227], v[192:195], v[60:63]
	v_mfma_f32_16x16x32_bf16 v[52:55], v[232:235], v[192:195], v[52:55]
	v_mfma_f32_16x16x32_bf16 v[44:47], v[224:227], v[200:203], v[44:47]
	v_mfma_f32_16x16x32_bf16 v[36:39], v[232:235], v[200:203], v[36:39]
	v_mfma_f32_16x16x32_bf16 v[28:31], v[224:227], v[208:211], v[28:31]
	v_mfma_f32_16x16x32_bf16 v[20:23], v[232:235], v[208:211], v[20:23]
	v_mfma_f32_16x16x32_bf16 v[12:15], v[224:227], v[216:219], v[12:15]
	s_add_u32 s6, s6, 0x100
	v_mfma_f32_16x16x32_bf16 v[0:3], v[232:235], v[216:219], v[0:3]
	s_addc_u32 s7, s7, 0
	v_mfma_f32_16x16x32_bf16 v[60:63], v[228:231], v[196:199], v[60:63]
	s_add_u32 s25, s25, 0x100
	v_mfma_f32_16x16x32_bf16 v[52:55], v[236:239], v[196:199], v[52:55]
	s_addc_u32 s27, s27, 0
	v_mfma_f32_16x16x32_bf16 v[44:47], v[228:231], v[204:207], v[44:47]
	s_cmp_ge_i32 s34, s12
	v_mfma_f32_16x16x32_bf16 v[36:39], v[236:239], v[204:207], v[36:39]
	s_mov_b32 s8, s34
	v_mfma_f32_16x16x32_bf16 v[28:31], v[228:231], v[212:215], v[28:31]
	v_mfma_f32_16x16x32_bf16 v[20:23], v[236:239], v[212:215], v[20:23]
	v_mfma_f32_16x16x32_bf16 v[12:15], v[228:231], v[220:223], v[12:15]
	v_mfma_f32_16x16x32_bf16 v[0:3], v[236:239], v[220:223], v[0:3]
	s_barrier
	s_setprio 0
	s_cbranch_scc0 .LBB0_1812
	s_nop 5
	s_branch .LBB0_1803

;     __device__ bool next(int i, Unit& u) const { const int L = i * G + c; if (L >= 64 * 9) return false; u.pm = L; u.pn = L / 9; u.kt0 = 0; u.nt = ntf; u.ks = 0; return true; }
; #define PG8_STAGE(bufoff, gbase, voff) do { _Pragma("unroll") for (int _i = 0; _i < 2; ++_i) \
;         __builtin_amdgcn_global_load_lds((const unsigned*)((const char*)(gbase) + (voff)[_i]), (LAS unsigned*)(lds + (bufoff) + ldsw + _i * 8192), 16, 0, 0); } while (0)
; #define PG8_LDA(dst, b, h) do { _Pragma("unroll") for (int m = 0; m < 4; ++m) _Pragma("unroll") for (int k = 0; k < 2; ++k) dst[m][k] = *(const LAS bf16x8*)(lds + PG8_SA(b, h) + aoff + m * 2048 + k * 1024); } while (0)
; #define PG8_LDB(dst, b, h) do { _Pragma("unroll") for (int n = 0; n < 2; ++n) _Pragma("unroll") for (int k = 0; k < 2; ++k) dst[n][k] = *(const LAS bf16x8*)(lds + PG8_SB(b, h) + boff + n * 2048 + k * 1024); } while (0)
; template <class Epi, class Sched, bool ATILE = false>
; __device__ __forceinline__ void gemm_phase(LAS unsigned char* lds, const Gemm g, const Sched& S, const Epi& E) {
;     ...
;         const bool has_next = S.next(ui + 1, nxt);
;         const char* nA = has_next ? (const char*)g.A + (size_t)nxt.pm * tstepA + (size_t)nxt.kt0 * kstepA : cA; const char* nB = has_next ? (const char*)g.Bt + (size_t)nxt.pn * tstepB + (size_t)nxt.kt0 * kstep : cB;
;         int nt = cur.nt; asm volatile("" : "+s"(nt));
;         for (int t = 0; t < nt; t += 2) {
;             const bool last = (t == nt - 2);
;             const char* a1 = cA + (size_t)(t + 1) * kstepA;
;             const char* a2 = last ? nA : cA + (size_t)(t + 2) * kstepA; const char* b2 = last ? nB : cB + (size_t)(t + 2) * kstep;
;             const char* a3 = a2 + kstepA; const char* b3 = b2 + kstep;
;             PG8_LDB(B0, 0, 0); PG8_SCHED; PG8_LDA(At, 0, 0); PG8_STAGE(PG8_SA(1, 1), a1 + hstepA, voffA);
;             PG8_WAIT_L(8); PG8_BAR; PG8_WAIT_L(0); PG8_MMA(0, 0, At, B0); PG8_BAR; PG8_SCHED;
;             PG8_LDB(B1, 0, 1); PG8_STAGE(PG8_SB(0, 0), b2, voffB);
;             PG8_BAR; PG8_WAIT_L(0); PG8_MMA(0, 1, At, B1); PG8_BAR;
;             PG8_LDA(At, 0, 1); PG8_STAGE(PG8_SA(0, 0), a2, voffA);
;             PG8_BAR; PG8_WAIT_L(0); PG8_MMA(1, 0, At, B0); PG8_BAR; PG8_SCHED;
;             PG8_STAGE(PG8_SB(0, 1), b2 + hstepB, voffB);
;             PG8_WAIT_V(6); PG8_BAR; PG8_MMA(1, 1, At, B1); PG8_BAR;
.LBB0_1898:
	ds_read_b128 v[20:23], v180
	ds_read_b128 v[28:31], v180 offset:1024
	ds_read_b128 v[174:177], v180 offset:2048
	ds_read_b128 v[184:187], v180 offset:3072
	s_add_i32 m0, s34, 0xc000
	ds_read_b128 v[188:191], v181
	ds_read_b128 v[192:195], v181 offset:1024
	ds_read_b128 v[196:199], v181 offset:2048
	ds_read_b128 v[200:203], v181 offset:3072
	ds_read_b128 v[204:207], v181 offset:4096
	ds_read_b128 v[208:211], v181 offset:5120
	ds_read_b128 v[212:215], v181 offset:6144
	ds_read_b128 v[216:219], v181 offset:7168
	global_load_lds_dwordx4 v168, s[24:25]
	s_add_i32 m0, s34, 0xe000
	s_nop 0
	global_load_lds_dwordx4 v170, s[24:25]
	s_waitcnt lgkmcnt(8)
	s_setprio 1
	s_barrier
	s_waitcnt lgkmcnt(0)
	v_mfma_f32_16x16x32_bf16 v[0:3], v[20:23], v[188:191], v[0:3]
	s_add_i32 s58, s26, 2
	v_mfma_f32_16x16x32_bf16 v[4:7], v[174:177], v[188:191], v[4:7]
	s_add_u32 s27, s24, 0x4000
	v_mfma_f32_16x16x32_bf16 v[44:47], v[20:23], v[196:199], v[44:47]
	s_addc_u32 s28, s25, 0
	v_mfma_f32_16x16x32_bf16 v[36:39], v[174:177], v[196:199], v[36:39]
	s_cmp_eq_u32 s17, s26
	v_mfma_f32_16x16x32_bf16 v[52:55], v[20:23], v[204:207], v[52:55]
	s_cselect_b32 s30, s20, s27
	v_mfma_f32_16x16x32_bf16 v[48:51], v[174:177], v[204:207], v[48:51]
	s_cselect_b32 s31, s21, s28
	v_mfma_f32_16x16x32_bf16 v[92:95], v[20:23], v[212:215], v[92:95]
	s_cselect_b32 s26, s22, s56
	v_mfma_f32_16x16x32_bf16 v[84:87], v[174:177], v[212:215], v[84:87]
	s_cselect_b32 s27, s23, s57
	v_mfma_f32_16x16x32_bf16 v[0:3], v[28:31], v[192:195], v[0:3]
	s_add_u32 s28, s30, 0x8000
	v_mfma_f32_16x16x32_bf16 v[4:7], v[184:187], v[192:195], v[4:7]
	s_addc_u32 s29, s31, 0
	v_mfma_f32_16x16x32_bf16 v[44:47], v[28:31], v[200:203], v[44:47]
	s_add_i32 s59, s44, s33
	v_mfma_f32_16x16x32_bf16 v[36:39], v[184:187], v[200:203], v[36:39]
	s_add_u32 s98, s26, s4
	v_mfma_f32_16x16x32_bf16 v[52:55], v[28:31], v[208:211], v[52:55]
	s_addc_u32 s99, s27, s5
	v_mfma_f32_16x16x32_bf16 v[48:51], v[184:187], v[208:211], v[48:51]
	s_mov_b32 m0, s59
	v_mfma_f32_16x16x32_bf16 v[92:95], v[28:31], v[216:219], v[92:95]
	v_mfma_f32_16x16x32_bf16 v[84:87], v[184:187], v[216:219], v[84:87]
	s_barrier
	s_setprio 0
	ds_read_b128 v[220:223], v182
	ds_read_b128 v[224:227], v182 offset:1024
	ds_read_b128 v[228:231], v182 offset:2048
	ds_read_b128 v[232:235], v182 offset:3072
	global_load_lds_dwordx4 v138, s[26:27]
	s_add_i32 m0, s59, 0x2000
	s_nop 0
	global_load_lds_dwordx4 v142, s[26:27]
	s_setprio 1
	s_barrier
	s_waitcnt lgkmcnt(0)
	v_mfma_f32_16x16x32_bf16 v[12:15], v[220:223], v[188:191], v[12:15]
	v_mfma_f32_16x16x32_bf16 v[8:11], v[228:231], v[188:191], v[8:11]
	v_mfma_f32_16x16x32_bf16 v[24:27], v[220:223], v[196:199], v[24:27]
	v_mfma_f32_16x16x32_bf16 v[16:19], v[228:231], v[196:199], v[16:19]
	v_mfma_f32_16x16x32_bf16 v[40:43], v[220:223], v[204:207], v[40:43]
	v_mfma_f32_16x16x32_bf16 v[32:35], v[228:231], v[204:207], v[32:35]
	v_mfma_f32_16x16x32_bf16 v[56:59], v[220:223], v[212:215], v[56:59]
	v_mfma_f32_16x16x32_bf16 v[60:63], v[228:231], v[212:215], v[60:63]
	s_mov_b32 m0, s34
	v_mfma_f32_16x16x32_bf16 v[12:15], v[224:227], v[192:195], v[12:15]
	v_mfma_f32_16x16x32_bf16 v[8:11], v[232:235], v[192:195], v[8:11]
	v_mfma_f32_16x16x32_bf16 v[24:27], v[224:227], v[200:203], v[24:27]
	v_mfma_f32_16x16x32_bf16 v[16:19], v[232:235], v[200:203], v[16:19]
	v_mfma_f32_16x16x32_bf16 v[40:43], v[224:227], v[208:211], v[40:43]
	v_mfma_f32_16x16x32_bf16 v[32:35], v[232:235], v[208:211], v[32:35]
	v_mfma_f32_16x16x32_bf16 v[56:59], v[224:227], v[216:219], v[56:59]
	v_mfma_f32_16x16x32_bf16 v[60:63], v[232:235], v[216:219], v[60:63]
	s_barrier
	s_setprio 0
	ds_read_b128 v[188:191], v181 offset:16384
	ds_read_b128 v[192:195], v181 offset:17408
	ds_read_b128 v[196:199], v181 offset:18432
	ds_read_b128 v[200:203], v181 offset:19456
	ds_read_b128 v[204:207], v181 offset:20480
	ds_read_b128 v[208:211], v181 offset:21504
	ds_read_b128 v[212:215], v181 offset:22528
	ds_read_b128 v[216:219], v181 offset:23552
	global_load_lds_dwordx4 v136, s[30:31]
	s_mov_b32 m0, s35
	s_nop 0
	global_load_lds_dwordx4 v140, s[30:31]
	s_setprio 1
	s_barrier
	s_waitcnt lgkmcnt(0)
	v_mfma_f32_16x16x32_bf16 v[64:67], v[20:23], v[188:191], v[64:67]
	v_mfma_f32_16x16x32_bf16 v[68:71], v[174:177], v[188:191], v[68:71]
	v_mfma_f32_16x16x32_bf16 v[108:111], v[20:23], v[196:199], v[108:111]
	v_mfma_f32_16x16x32_bf16 v[100:103], v[174:177], v[196:199], v[100:103]
	v_mfma_f32_16x16x32_bf16 v[116:119], v[20:23], v[204:207], v[116:119]
	v_mfma_f32_16x16x32_bf16 v[112:115], v[174:177], v[204:207], v[112:115]
	v_mfma_f32_16x16x32_bf16 v[20:23], v[20:23], v[212:215], v[132:135]
	v_mfma_f32_16x16x32_bf16 v[64:67], v[28:31], v[192:195], v[64:67]
	s_add_u32 s60, s26, 0x158000
	v_mfma_f32_16x16x32_bf16 v[68:71], v[184:187], v[192:195], v[68:71]
	s_addc_u32 s61, s27, 0
	v_mfma_f32_16x16x32_bf16 v[108:111], v[28:31], v[200:203], v[108:111]
	s_add_i32 s59, s45, s33
	v_mfma_f32_16x16x32_bf16 v[100:103], v[184:187], v[200:203], v[100:103]
	s_mov_b32 m0, s59
	v_mfma_f32_16x16x32_bf16 v[116:119], v[28:31], v[208:211], v[116:119]
	v_mfma_f32_16x16x32_bf16 v[112:115], v[184:187], v[208:211], v[112:115]
	v_mfma_f32_16x16x32_bf16 v[20:23], v[28:31], v[216:219], v[20:23]
	v_mfma_f32_16x16x32_bf16 v[28:31], v[174:177], v[212:215], v[128:131]
	v_mfma_f32_16x16x32_bf16 v[28:31], v[184:187], v[216:219], v[28:31]
	s_barrier
	s_setprio 0
	s_nop 0
	global_load_lds_dwordx4 v138, s[60:61]
	s_add_i32 m0, s59, 0x2000
	s_nop 0
	global_load_lds_dwordx4 v142, s[60:61]
	s_waitcnt vmcnt(6)
	s_setprio 1
	s_barrier
; #define PG8_STAGE(bufoff, gbase, voff) do { _Pragma("unroll") for (int _i = 0; _i < 2; ++_i) \
;         __builtin_amdgcn_global_load_lds((const unsigned*)((const char*)(gbase) + (voff)[_i]), (LAS unsigned*)(lds + (bufoff) + ldsw + _i * 8192), 16, 0, 0); } while (0)
; #define PG8_LDA(dst, b, h) do { _Pragma("unroll") for (int m = 0; m < 4; ++m) _Pragma("unroll") for (int k = 0; k < 2; ++k) dst[m][k] = *(const LAS bf16x8*)(lds + PG8_SA(b, h) + aoff + m * 2048 + k * 1024); } while (0)
; #define PG8_LDB(dst, b, h) do { _Pragma("unroll") for (int n = 0; n < 2; ++n) _Pragma("unroll") for (int k = 0; k < 2; ++k) dst[n][k] = *(const LAS bf16x8*)(lds + PG8_SB(b, h) + boff + n * 2048 + k * 1024); } while (0)
; #define PG8_MMA(ai, bj, At, Bt) do { __builtin_amdgcn_s_setprio(1); _Pragma("unroll") for (int m = 0; m < 4; ++m) _Pragma("unroll") for (int n = 0; n < 2; ++n) _Pragma("unroll") for (int k = 0; k < 2; ++k) \
;         acc[ai][bj][m][n] = __builtin_amdgcn_mfma_f32_16x16x32_bf16(Bt[n][k], At[m][k], acc[ai][bj][m][n], 0, 0, 0); __builtin_amdgcn_s_setprio(0); } while (0)
; #define PG8_WAIT_V(n) asm volatile("s_waitcnt vmcnt(" #n ")" ::: "memory")
; #define PG8_WAIT_L(n) asm volatile("s_waitcnt lgkmcnt(" #n ")" ::: "memory")
; #define PG8_BAR __builtin_amdgcn_s_barrier()
; #define PG8_SCHED __builtin_amdgcn_sched_barrier(0)
; template <class Epi, class Sched, bool ATILE = false>
; __device__ __forceinline__ void gemm_phase(LAS unsigned char* lds, const Gemm g, const Sched& S, const Epi& E) {
;     ...
;             PG8_WAIT_V(6); PG8_BAR; PG8_MMA(1, 1, At, B1); PG8_BAR;
;             PG8_LDB(B0, 1, 0); PG8_SCHED; PG8_LDA(At, 1, 0); PG8_STAGE(PG8_SA(0, 1), a2 + hstepA, voffA);
;             PG8_WAIT_L(8); PG8_BAR; PG8_WAIT_L(0); PG8_MMA(0, 0, At, B0); PG8_BAR; PG8_SCHED;
;             PG8_LDB(B1, 1, 1); PG8_STAGE(PG8_SB(1, 0), b3, voffB);
;             PG8_BAR; PG8_WAIT_L(0); PG8_MMA(0, 1, At, B1); PG8_BAR;
;             PG8_LDA(At, 1, 1); PG8_STAGE(PG8_SA(1, 0), a3, voffA);
;             PG8_BAR; PG8_WAIT_L(0); PG8_MMA(1, 0, At, B0); PG8_BAR; PG8_SCHED;
	v_mfma_f32_16x16x32_bf16 v[76:79], v[220:223], v[188:191], v[76:79]
	v_mfma_f32_16x16x32_bf16 v[72:75], v[228:231], v[188:191], v[72:75]
	v_mfma_f32_16x16x32_bf16 v[88:91], v[220:223], v[196:199], v[88:91]
	v_mfma_f32_16x16x32_bf16 v[80:83], v[228:231], v[196:199], v[80:83]
	v_mfma_f32_16x16x32_bf16 v[104:107], v[220:223], v[204:207], v[104:107]
	v_mfma_f32_16x16x32_bf16 v[96:99], v[228:231], v[204:207], v[96:99]
	v_mfma_f32_16x16x32_bf16 v[120:123], v[220:223], v[212:215], v[120:123]
	v_mfma_f32_16x16x32_bf16 v[124:127], v[228:231], v[212:215], v[124:127]
	s_add_i32 s59, 0, 0x18000
	v_mfma_f32_16x16x32_bf16 v[76:79], v[224:227], v[192:195], v[76:79]
	v_add_u32_e32 v183, s59, v157
	v_mfma_f32_16x16x32_bf16 v[72:75], v[232:235], v[192:195], v[72:75]
	v_mfma_f32_16x16x32_bf16 v[88:91], v[224:227], v[200:203], v[88:91]
	v_mfma_f32_16x16x32_bf16 v[80:83], v[232:235], v[200:203], v[80:83]
	v_mfma_f32_16x16x32_bf16 v[104:107], v[224:227], v[208:211], v[104:107]
	v_mfma_f32_16x16x32_bf16 v[96:99], v[232:235], v[208:211], v[96:99]
	v_mfma_f32_16x16x32_bf16 v[120:123], v[224:227], v[216:219], v[120:123]
	v_mfma_f32_16x16x32_bf16 v[124:127], v[232:235], v[216:219], v[124:127]
	s_barrier
	s_setprio 0
	ds_read_b128 v[128:131], v183
	ds_read_b128 v[132:135], v183 offset:1024
	ds_read_b128 v[174:177], v183 offset:2048
	ds_read_b128 v[184:187], v183 offset:3072
	s_add_u32 s30, s30, 0x4000
	s_addc_u32 s31, s31, 0
	s_mov_b32 m0, s36
	ds_read_b128 v[188:191], v181 offset:32768
	ds_read_b128 v[192:195], v181 offset:33792
	ds_read_b128 v[196:199], v181 offset:34816
	ds_read_b128 v[200:203], v181 offset:35840
	ds_read_b128 v[204:207], v181 offset:36864
	ds_read_b128 v[208:211], v181 offset:37888
	ds_read_b128 v[212:215], v181 offset:38912
	ds_read_b128 v[216:219], v181 offset:39936
	global_load_lds_dwordx4 v136, s[30:31]
	s_mov_b32 m0, s37
	s_nop 0
	global_load_lds_dwordx4 v140, s[30:31]
	s_waitcnt lgkmcnt(8)
	s_setprio 1
	s_barrier
	s_waitcnt lgkmcnt(0)
	v_mfma_f32_16x16x32_bf16 v[0:3], v[128:131], v[188:191], v[0:3]
	v_mfma_f32_16x16x32_bf16 v[4:7], v[174:177], v[188:191], v[4:7]
	v_mfma_f32_16x16x32_bf16 v[44:47], v[128:131], v[196:199], v[44:47]
	v_mfma_f32_16x16x32_bf16 v[36:39], v[174:177], v[196:199], v[36:39]
	v_mfma_f32_16x16x32_bf16 v[52:55], v[128:131], v[204:207], v[52:55]
	v_mfma_f32_16x16x32_bf16 v[48:51], v[174:177], v[204:207], v[48:51]
	v_mfma_f32_16x16x32_bf16 v[92:95], v[128:131], v[212:215], v[92:95]
	v_mfma_f32_16x16x32_bf16 v[84:87], v[174:177], v[212:215], v[84:87]
	s_add_i32 s30, 0, 0x1c000
	v_mfma_f32_16x16x32_bf16 v[0:3], v[132:135], v[192:195], v[0:3]
	s_add_i32 s31, s59, s33
	v_mfma_f32_16x16x32_bf16 v[4:7], v[184:187], v[192:195], v[4:7]
	v_add_u32_e32 v183, s30, v157
	v_mfma_f32_16x16x32_bf16 v[44:47], v[132:135], v[200:203], v[44:47]
	s_mov_b32 m0, s31
	v_mfma_f32_16x16x32_bf16 v[36:39], v[184:187], v[200:203], v[36:39]
	v_mfma_f32_16x16x32_bf16 v[52:55], v[132:135], v[208:211], v[52:55]
	v_mfma_f32_16x16x32_bf16 v[48:51], v[184:187], v[208:211], v[48:51]
	v_mfma_f32_16x16x32_bf16 v[92:95], v[132:135], v[216:219], v[92:95]
	v_mfma_f32_16x16x32_bf16 v[84:87], v[184:187], v[216:219], v[84:87]
	s_barrier
	s_setprio 0
	ds_read_b128 v[220:223], v183
	ds_read_b128 v[224:227], v183 offset:1024
	ds_read_b128 v[228:231], v183 offset:2048
	ds_read_b128 v[232:235], v183 offset:3072
	global_load_lds_dwordx4 v138, s[98:99]
	s_add_i32 m0, s31, 0x2000
	s_nop 0
	global_load_lds_dwordx4 v142, s[98:99]
	s_setprio 1
	s_barrier
	s_waitcnt lgkmcnt(0)
	v_mfma_f32_16x16x32_bf16 v[12:15], v[220:223], v[188:191], v[12:15]
	v_mfma_f32_16x16x32_bf16 v[8:11], v[228:231], v[188:191], v[8:11]
	v_mfma_f32_16x16x32_bf16 v[24:27], v[220:223], v[196:199], v[24:27]
	v_mfma_f32_16x16x32_bf16 v[16:19], v[228:231], v[196:199], v[16:19]
	v_mfma_f32_16x16x32_bf16 v[40:43], v[220:223], v[204:207], v[40:43]
	v_mfma_f32_16x16x32_bf16 v[32:35], v[228:231], v[204:207], v[32:35]
	v_mfma_f32_16x16x32_bf16 v[56:59], v[220:223], v[212:215], v[56:59]
	v_mfma_f32_16x16x32_bf16 v[60:63], v[228:231], v[212:215], v[60:63]
	s_mov_b32 m0, s39
	v_mfma_f32_16x16x32_bf16 v[12:15], v[224:227], v[192:195], v[12:15]
	v_mfma_f32_16x16x32_bf16 v[8:11], v[232:235], v[192:195], v[8:11]
	v_mfma_f32_16x16x32_bf16 v[24:27], v[224:227], v[200:203], v[24:27]
	v_mfma_f32_16x16x32_bf16 v[16:19], v[232:235], v[200:203], v[16:19]
	v_mfma_f32_16x16x32_bf16 v[40:43], v[224:227], v[208:211], v[40:43]
	v_mfma_f32_16x16x32_bf16 v[32:35], v[232:235], v[208:211], v[32:35]
	v_mfma_f32_16x16x32_bf16 v[56:59], v[224:227], v[216:219], v[56:59]
	v_mfma_f32_16x16x32_bf16 v[60:63], v[232:235], v[216:219], v[60:63]
	s_barrier
	s_setprio 0
	ds_read_b128 v[188:191], v181 offset:49152
	ds_read_b128 v[192:195], v181 offset:50176
	ds_read_b128 v[196:199], v181 offset:51200
	ds_read_b128 v[200:203], v181 offset:52224
	ds_read_b128 v[204:207], v181 offset:53248
	ds_read_b128 v[208:211], v181 offset:54272
	ds_read_b128 v[212:215], v181 offset:55296
	ds_read_b128 v[216:219], v181 offset:56320
	global_load_lds_dwordx4 v136, s[28:29]
	s_mov_b32 m0, s40
	s_nop 0
	global_load_lds_dwordx4 v140, s[28:29]
	s_setprio 1
	s_barrier
; __device__ __forceinline__ float bflo(unsigned w) { return __uint_as_float(w << 16); }
; __device__ __forceinline__ float bfhi(unsigned w) { return __uint_as_float(w & 0xffff0000u); }
; #define PG8_STAGE(bufoff, gbase, voff) do { _Pragma("unroll") for (int _i = 0; _i < 2; ++_i) \
;         __builtin_amdgcn_global_load_lds((const unsigned*)((const char*)(gbase) + (voff)[_i]), (LAS unsigned*)(lds + (bufoff) + ldsw + _i * 8192), 16, 0, 0); } while (0)
; #define PG8_MMA(ai, bj, At, Bt) do { __builtin_amdgcn_s_setprio(1); _Pragma("unroll") for (int m = 0; m < 4; ++m) _Pragma("unroll") for (int n = 0; n < 2; ++n) _Pragma("unroll") for (int k = 0; k < 2; ++k) \
;         acc[ai][bj][m][n] = __builtin_amdgcn_mfma_f32_16x16x32_bf16(Bt[n][k], At[m][k], acc[ai][bj][m][n], 0, 0, 0); __builtin_amdgcn_s_setprio(0); } while (0)
; #define PG8_WAIT_V(n) asm volatile("s_waitcnt vmcnt(" #n ")" ::: "memory")
; #define PG8_WAIT_L(n) asm volatile("s_waitcnt lgkmcnt(" #n ")" ::: "memory")
; #define PG8_BAR __builtin_amdgcn_s_barrier()
; #define PG8_SCHED __builtin_amdgcn_sched_barrier(0)
; template <class Epi, class Sched, bool ATILE = false>
; __device__ __forceinline__ void gemm_phase(LAS unsigned char* lds, const Gemm g, const Sched& S, const Epi& E) {
;     ...
;             PG8_BAR; PG8_WAIT_L(0); PG8_MMA(1, 0, At, B0); PG8_BAR; PG8_SCHED;
;             PG8_STAGE(PG8_SB(1, 1), b3 + hstepB, voffB);
;             PG8_WAIT_V(6); PG8_BAR; PG8_MMA(1, 1, At, B1); PG8_BAR;
;         }
;     __device__ __forceinline__ void operator()(const f32x4 (&acc)[2][2][4][2], const Unit& u, int wr, int wc, int fr, int fq) const {
;     ...
;                     const f32x4 v0 = (f32x4){bflo(x.x), bfhi(x.x), bflo(x.y), bfhi(x.y)} + alpha * acc[ai][bj][m][0];
;                     const f32x4 v1 = (f32x4){bflo(x.z), bfhi(x.z), bflo(x.w), bfhi(x.w)} + alpha * acc[ai][bj][m][1];
	s_waitcnt lgkmcnt(0)
	v_mfma_f32_16x16x32_bf16 v[64:67], v[128:131], v[188:191], v[64:67]
	v_mfma_f32_16x16x32_bf16 v[108:111], v[128:131], v[196:199], v[108:111]
	v_mfma_f32_16x16x32_bf16 v[116:119], v[128:131], v[204:207], v[116:119]
	v_mfma_f32_16x16x32_bf16 v[20:23], v[128:131], v[212:215], v[20:23]
	v_mfma_f32_16x16x32_bf16 v[64:67], v[132:135], v[192:195], v[64:67]
	v_mfma_f32_16x16x32_bf16 v[68:71], v[174:177], v[188:191], v[68:71]
	v_mfma_f32_16x16x32_bf16 v[108:111], v[132:135], v[200:203], v[108:111]
	v_mfma_f32_16x16x32_bf16 v[100:103], v[174:177], v[196:199], v[100:103]
	s_add_u32 s26, s26, 0x158080
	v_mfma_f32_16x16x32_bf16 v[116:119], v[132:135], v[208:211], v[116:119]
	s_addc_u32 s27, s27, 0
	v_mfma_f32_16x16x32_bf16 v[112:115], v[174:177], v[204:207], v[112:115]
	s_add_i32 s28, s30, s33
	v_mfma_f32_16x16x32_bf16 v[132:135], v[132:135], v[216:219], v[20:23]
	s_mov_b32 m0, s28
	v_mfma_f32_16x16x32_bf16 v[20:23], v[174:177], v[212:215], v[28:31]
	v_mfma_f32_16x16x32_bf16 v[68:71], v[184:187], v[192:195], v[68:71]
	v_mfma_f32_16x16x32_bf16 v[100:103], v[184:187], v[200:203], v[100:103]
	v_mfma_f32_16x16x32_bf16 v[112:115], v[184:187], v[208:211], v[112:115]
	v_mfma_f32_16x16x32_bf16 v[128:131], v[184:187], v[216:219], v[20:23]
	s_barrier
	s_setprio 0
	s_nop 0
	global_load_lds_dwordx4 v138, s[26:27]
	s_add_i32 m0, s28, 0x2000
	s_nop 0
	global_load_lds_dwordx4 v142, s[26:27]
	s_waitcnt vmcnt(6)
	s_setprio 1
	s_barrier
	v_mfma_f32_16x16x32_bf16 v[20:23], v[220:223], v[188:191], v[76:79]
	v_mfma_f32_16x16x32_bf16 v[76:79], v[224:227], v[192:195], v[20:23]
	v_mfma_f32_16x16x32_bf16 v[20:23], v[228:231], v[188:191], v[72:75]
	v_mfma_f32_16x16x32_bf16 v[72:75], v[232:235], v[192:195], v[20:23]
	v_mfma_f32_16x16x32_bf16 v[20:23], v[220:223], v[196:199], v[88:91]
	v_mfma_f32_16x16x32_bf16 v[88:91], v[224:227], v[200:203], v[20:23]
	v_mfma_f32_16x16x32_bf16 v[20:23], v[228:231], v[196:199], v[80:83]
	s_add_u32 s56, s56, 0x100
	v_mfma_f32_16x16x32_bf16 v[80:83], v[232:235], v[200:203], v[20:23]
	s_addc_u32 s57, s57, 0
	v_mfma_f32_16x16x32_bf16 v[20:23], v[220:223], v[204:207], v[104:107]
	s_add_u32 s24, s24, 0x10000
	v_mfma_f32_16x16x32_bf16 v[104:107], v[224:227], v[208:211], v[20:23]
	s_addc_u32 s25, s25, 0
	v_mfma_f32_16x16x32_bf16 v[20:23], v[228:231], v[204:207], v[96:99]
	s_cmp_ge_i32 s58, s55
	v_mfma_f32_16x16x32_bf16 v[96:99], v[232:235], v[208:211], v[20:23]
	s_mov_b32 s26, s58
	v_mfma_f32_16x16x32_bf16 v[20:23], v[220:223], v[212:215], v[120:123]
	v_mfma_f32_16x16x32_bf16 v[120:123], v[224:227], v[216:219], v[20:23]
	v_mfma_f32_16x16x32_bf16 v[20:23], v[228:231], v[212:215], v[124:127]
	v_mfma_f32_16x16x32_bf16 v[124:127], v[232:235], v[216:219], v[20:23]
	s_barrier
	s_setprio 0
	s_cbranch_scc0 .LBB0_1898
	s_nop 5
	v_pk_mul_f32 v[2:3], v[2:3], 0.5 op_sel_hi:[1,0]
	v_pk_mul_f32 v[0:1], v[0:1], 0.5 op_sel_hi:[1,0]
	v_pk_mul_f32 v[6:7], v[6:7], 0.5 op_sel_hi:[1,0]
	v_pk_mul_f32 v[4:5], v[4:5], 0.5 op_sel_hi:[1,0]
	v_pk_mul_f32 v[22:23], v[14:15], 0.5 op_sel_hi:[1,0]
	v_pk_mul_f32 v[20:21], v[12:13], 0.5 op_sel_hi:[1,0]
	v_pk_mul_f32 v[30:31], v[10:11], 0.5 op_sel_hi:[1,0]
	v_pk_mul_f32 v[28:29], v[8:9], 0.5 op_sel_hi:[1,0]
	v_pk_mul_f32 v[10:11], v[46:47], 0.5 op_sel_hi:[1,0]
	v_pk_mul_f32 v[8:9], v[44:45], 0.5 op_sel_hi:[1,0]
	v_pk_mul_f32 v[14:15], v[38:39], 0.5 op_sel_hi:[1,0]
	v_pk_mul_f32 v[12:13], v[36:37], 0.5 op_sel_hi:[1,0]
	v_pk_mul_f32 v[38:39], v[26:27], 0.5 op_sel_hi:[1,0]
	v_pk_mul_f32 v[36:37], v[24:25], 0.5 op_sel_hi:[1,0]
	v_pk_mul_f32 v[46:47], v[18:19], 0.5 op_sel_hi:[1,0]
	v_pk_mul_f32 v[44:45], v[16:17], 0.5 op_sel_hi:[1,0]
	v_pk_mul_f32 v[18:19], v[54:55], 0.5 op_sel_hi:[1,0]
	v_pk_mul_f32 v[16:17], v[52:53], 0.5 op_sel_hi:[1,0]
	v_pk_mul_f32 v[26:27], v[50:51], 0.5 op_sel_hi:[1,0]
	v_pk_mul_f32 v[24:25], v[48:49], 0.5 op_sel_hi:[1,0]
	v_pk_mul_f32 v[50:51], v[42:43], 0.5 op_sel_hi:[1,0]
	v_pk_mul_f32 v[48:49], v[40:41], 0.5 op_sel_hi:[1,0]
	v_pk_mul_f32 v[54:55], v[34:35], 0.5 op_sel_hi:[1,0]
	v_pk_mul_f32 v[52:53], v[32:33], 0.5 op_sel_hi:[1,0]
	v_pk_mul_f32 v[34:35], v[94:95], 0.5 op_sel_hi:[1,0]
	v_pk_mul_f32 v[32:33], v[92:93], 0.5 op_sel_hi:[1,0]
	v_pk_mul_f32 v[42:43], v[86:87], 0.5 op_sel_hi:[1,0]
	v_pk_mul_f32 v[40:41], v[84:85], 0.5 op_sel_hi:[1,0]
	v_pk_mul_f32 v[58:59], v[58:59], 0.5 op_sel_hi:[1,0]
	v_pk_mul_f32 v[56:57], v[56:57], 0.5 op_sel_hi:[1,0]
	v_pk_mul_f32 v[62:63], v[62:63], 0.5 op_sel_hi:[1,0]
	v_pk_mul_f32 v[60:61], v[60:61], 0.5 op_sel_hi:[1,0]
	v_pk_mul_f32 v[66:67], v[66:67], 0.5 op_sel_hi:[1,0]
	v_pk_mul_f32 v[64:65], v[64:65], 0.5 op_sel_hi:[1,0]
	v_pk_mul_f32 v[70:71], v[70:71], 0.5 op_sel_hi:[1,0]
	v_pk_mul_f32 v[68:69], v[68:69], 0.5 op_sel_hi:[1,0]
	v_pk_mul_f32 v[86:87], v[78:79], 0.5 op_sel_hi:[1,0]
	v_pk_mul_f32 v[84:85], v[76:77], 0.5 op_sel_hi:[1,0]
	v_pk_mul_f32 v[94:95], v[74:75], 0.5 op_sel_hi:[1,0]
	v_pk_mul_f32 v[92:93], v[72:73], 0.5 op_sel_hi:[1,0]
	v_pk_mul_f32 v[74:75], v[110:111], 0.5 op_sel_hi:[1,0]
	v_pk_mul_f32 v[72:73], v[108:109], 0.5 op_sel_hi:[1,0]
	v_pk_mul_f32 v[78:79], v[102:103], 0.5 op_sel_hi:[1,0]
	v_pk_mul_f32 v[76:77], v[100:101], 0.5 op_sel_hi:[1,0]
	v_pk_mul_f32 v[102:103], v[90:91], 0.5 op_sel_hi:[1,0]
	v_pk_mul_f32 v[100:101], v[88:89], 0.5 op_sel_hi:[1,0]
	v_pk_mul_f32 v[110:111], v[82:83], 0.5 op_sel_hi:[1,0]
	v_pk_mul_f32 v[108:109], v[80:81], 0.5 op_sel_hi:[1,0]
	v_pk_mul_f32 v[82:83], v[118:119], 0.5 op_sel_hi:[1,0]
	v_pk_mul_f32 v[80:81], v[116:117], 0.5 op_sel_hi:[1,0]
	v_pk_mul_f32 v[90:91], v[114:115], 0.5 op_sel_hi:[1,0]
	v_pk_mul_f32 v[88:89], v[112:113], 0.5 op_sel_hi:[1,0]
	v_pk_mul_f32 v[114:115], v[106:107], 0.5 op_sel_hi:[1,0]
	v_pk_mul_f32 v[112:113], v[104:105], 0.5 op_sel_hi:[1,0]
	v_pk_mul_f32 v[118:119], v[98:99], 0.5 op_sel_hi:[1,0]
	v_pk_mul_f32 v[116:117], v[96:97], 0.5 op_sel_hi:[1,0]
	v_pk_mul_f32 v[98:99], v[134:135], 0.5 op_sel_hi:[1,0]
	v_pk_mul_f32 v[96:97], v[132:133], 0.5 op_sel_hi:[1,0]
	v_pk_mul_f32 v[106:107], v[130:131], 0.5 op_sel_hi:[1,0]
	v_pk_mul_f32 v[104:105], v[128:129], 0.5 op_sel_hi:[1,0]
	v_pk_mul_f32 v[122:123], v[122:123], 0.5 op_sel_hi:[1,0]
	v_pk_mul_f32 v[120:121], v[120:121], 0.5 op_sel_hi:[1,0]
	v_pk_mul_f32 v[126:127], v[126:127], 0.5 op_sel_hi:[1,0]
	v_pk_mul_f32 v[124:125], v[124:125], 0.5 op_sel_hi:[1,0]
	s_branch .LBB0_1903
